# GEMM K-loops: first iteration peeled with C=0 MFMAs, per-tile accumulator zeroing removed
# baseline (speedup 1.0000x reference)
; #define PG8_STAGE(bufoff, gbase, voff) do { _Pragma("unroll") for (int _i = 0; _i < 2; ++_i) \
;         __builtin_amdgcn_global_load_lds((const unsigned*)((const char*)(gbase) + (voff)[_i]), (PG8_LAS unsigned*)(lds + (bufoff) + ldsw + _i * 8192), 16, 0, 0); } while (0)
; #define PG8_LDA(dst, b, h) do { _Pragma("unroll") for (int m = 0; m < 4; ++m) _Pragma("unroll") for (int k = 0; k < 2; ++k) dst[m][k] = *(const PG8_LAS bf16x8*)(lds + PG8_SA(b, h) + aoff + m * 2048 + k * 1024); } while (0)
; #define PG8_LDB(dst, b, h) do { _Pragma("unroll") for (int n = 0; n < 2; ++n) _Pragma("unroll") for (int k = 0; k < 2; ++k) dst[n][k] = *(const PG8_LAS bf16x8*)(lds + PG8_SB(b, h) + boff + n * 2048 + k * 1024); } while (0)
; template <class Epi, class Sched, bool ALIGN_EPI = false, bool SP2 = false>
; __device__ __forceinline__ void gemm_phase(PG8_LAS unsigned char* lds, const Gemm g, const Sched& S, const Epi& E) {
;     ...
;         for (int t = 0; t < nt; t += 2) {
;             const bool last = (t == nt - 2);
;             const char* a1 = cA + (size_t)(t + 1) * kstep;
;             const char* a2 = last ? nA : cA + (size_t)(t + 2) * kstep; const char* b2 = last ? nB : cB + (size_t)(t + 2) * kstep;
;             const char* a3 = a2 + kstep; const char* b3 = b2 + kstep;
;             if (last && has_next) S.a_ready(nxt);
;             if constexpr (SP2) {
;             PG8_LDB(B0, 0, 0); PG8_LDB(B1, 0, 1); PG8_SCHED; PG8_LDA(At, 0, 0); PG8_STAGE(PG8_SA(1, 1), a1 + hstepA, voffA);
;             PG8_WAIT_V(8); PG8_WAIT_L(0); PG8_BAR; PG8_MMA(0, 0, At, B0); PG8_MMA(0, 1, At, B1); PG8_BAR; PG8_SCHED;
;             PG8_LDA(At, 0, 1); PG8_STAGE(PG8_SB(0, 0), b2, voffB); PG8_STAGE(PG8_SB(0, 1), b2 + hstepB, voffB); PG8_STAGE(PG8_SA(0, 0), a2, voffA);
;             PG8_WAIT_V(8); PG8_WAIT_L(0); PG8_BAR; PG8_MMA(1, 0, At, B0); PG8_MMA(1, 1, At, B1); PG8_BAR; PG8_SCHED;
;             PG8_LDB(B0, 1, 0); PG8_LDB(B1, 1, 1); PG8_SCHED; PG8_LDA(At, 1, 0); PG8_STAGE(PG8_SA(0, 1), a2 + hstepA, voffA);
;             PG8_WAIT_V(8); PG8_WAIT_L(0); PG8_BAR; PG8_MMA(0, 0, At, B0); PG8_MMA(0, 1, At, B1); PG8_BAR; PG8_SCHED;
;             PG8_LDA(At, 1, 1); PG8_STAGE(PG8_SB(1, 0), b3, voffB); PG8_STAGE(PG8_SB(1, 1), b3 + hstepB, voffB); PG8_STAGE(PG8_SA(1, 0), a3, voffA);
;             PG8_WAIT_V(8); PG8_WAIT_L(0); PG8_BAR; PG8_MMA(1, 0, At, B0); PG8_MMA(1, 1, At, B1); PG8_BAR; PG8_SCHED;
.LBB0_134:
	s_ashr_i32 s45, s44, 31
	s_lshl_b64 s[14:15], s[44:45], 19
	v_readlane_b32 s24, v252, 2
	v_readlane_b32 s25, v252, 3
	s_add_u32 s46, s24, s14
	s_addc_u32 s47, s25, s15
	s_and_b64 s[14:15], s[40:41], exec
	s_cselect_b32 s12, s47, s21
	s_cselect_b32 s14, s46, s20
	s_ashr_i32 s43, s42, 31
	s_lshl_b64 s[24:25], s[42:43], 19
	v_readlane_b32 s15, v253, 45
	s_add_u32 s48, s15, s24
	v_readlane_b32 s15, v253, 46
	s_addc_u32 s49, s15, s25
	s_and_b64 s[24:25], s[40:41], exec
	s_cselect_b32 s15, s49, s23
	s_cselect_b32 s38, s48, s22
	s_add_u32 s20, s20, 0x40080
	s_addc_u32 s21, s21, 0
	s_add_u32 s43, s22, 0x100
	s_addc_u32 s45, s23, 0
	s_mov_b32 s53, -2
	s_add_u32 s22, s20, 0xfffc0080
	s_addc_u32 s23, s21, -1
	s_add_i32 s28, 0, 0x10000
	s_cmp_eq_u32 s53, 12
	s_cselect_b32 s25, s12, s23
	s_cselect_b32 s24, s14, s22
	v_add_u32_e32 v138, s28, v141
	s_cselect_b32 s23, s15, s45
	s_cselect_b32 s22, s38, s43
	s_add_i32 s29, 0, 0x14000
	ds_read_b128 v[144:147], v138
	ds_read_b128 v[148:151], v138 offset:1024
	ds_read_b128 v[152:155], v138 offset:2048
	ds_read_b128 v[156:159], v138 offset:3072
	v_add_u32_e32 v138, s29, v141
	ds_read_b128 v[160:163], v138
	ds_read_b128 v[164:167], v138 offset:1024
	ds_read_b128 v[168:171], v138 offset:2048
	ds_read_b128 v[172:175], v138 offset:3072
	v_lshl_add_u64 v[138:139], s[20:21], 0, v[134:135]
	s_add_i32 m0, s26, 0xc000
	ds_read_b128 v[176:179], v143
	ds_read_b128 v[180:183], v143 offset:1024
	ds_read_b128 v[184:187], v143 offset:2048
	ds_read_b128 v[188:191], v143 offset:3072
	ds_read_b128 v[192:195], v143 offset:4096
	ds_read_b128 v[196:199], v143 offset:5120
	ds_read_b128 v[200:203], v143 offset:6144
	ds_read_b128 v[204:207], v143 offset:7168
	global_load_lds_dwordx4 v[138:139], off
	v_lshl_add_u64 v[138:139], s[20:21], 0, v[136:137]
	s_add_i32 m0, s26, 0xe000
	s_nop 0
	global_load_lds_dwordx4 v[138:139], off
	s_waitcnt vmcnt(8)
	s_waitcnt lgkmcnt(0)
	s_barrier
	s_setprio 1
	s_waitcnt lgkmcnt(0)
	v_mfma_f32_16x16x32_bf16 v[124:127], v[144:147], v[176:179], 0
	v_mfma_f32_16x16x32_bf16 v[120:123], v[152:155], v[176:179], 0
	v_mfma_f32_16x16x32_bf16 v[108:111], v[144:147], v[184:187], 0
	v_mfma_f32_16x16x32_bf16 v[104:107], v[152:155], v[184:187], 0
	v_mfma_f32_16x16x32_bf16 v[92:95], v[144:147], v[192:195], 0
	v_mfma_f32_16x16x32_bf16 v[88:91], v[152:155], v[192:195], 0
	v_mfma_f32_16x16x32_bf16 v[76:79], v[144:147], v[200:203], 0
	v_mfma_f32_16x16x32_bf16 v[72:75], v[152:155], v[200:203], 0
	v_mfma_f32_16x16x32_bf16 v[124:127], v[148:151], v[180:183], v[124:127]
	v_mfma_f32_16x16x32_bf16 v[120:123], v[156:159], v[180:183], v[120:123]
	v_mfma_f32_16x16x32_bf16 v[108:111], v[148:151], v[188:191], v[108:111]
	v_mfma_f32_16x16x32_bf16 v[104:107], v[156:159], v[188:191], v[104:107]
	v_mfma_f32_16x16x32_bf16 v[92:95], v[148:151], v[196:199], v[92:95]
	v_mfma_f32_16x16x32_bf16 v[88:91], v[156:159], v[196:199], v[88:91]
	v_mfma_f32_16x16x32_bf16 v[76:79], v[148:151], v[204:207], v[76:79]
	v_mfma_f32_16x16x32_bf16 v[72:75], v[156:159], v[204:207], v[72:75]
	s_setprio 0
	s_setprio 1
	v_mfma_f32_16x16x32_bf16 v[116:119], v[160:163], v[176:179], 0
	v_mfma_f32_16x16x32_bf16 v[112:115], v[168:171], v[176:179], 0
	v_mfma_f32_16x16x32_bf16 v[100:103], v[160:163], v[184:187], 0
	v_mfma_f32_16x16x32_bf16 v[96:99], v[168:171], v[184:187], 0
	v_mfma_f32_16x16x32_bf16 v[84:87], v[160:163], v[192:195], 0
	v_mfma_f32_16x16x32_bf16 v[80:83], v[168:171], v[192:195], 0
	v_mfma_f32_16x16x32_bf16 v[68:71], v[160:163], v[200:203], 0
	v_mfma_f32_16x16x32_bf16 v[64:67], v[168:171], v[200:203], 0
	v_mfma_f32_16x16x32_bf16 v[116:119], v[164:167], v[180:183], v[116:119]
	v_mfma_f32_16x16x32_bf16 v[112:115], v[172:175], v[180:183], v[112:115]
	v_mfma_f32_16x16x32_bf16 v[100:103], v[164:167], v[188:191], v[100:103]
	v_mfma_f32_16x16x32_bf16 v[96:99], v[172:175], v[188:191], v[96:99]
	v_mfma_f32_16x16x32_bf16 v[84:87], v[164:167], v[196:199], v[84:87]
	v_mfma_f32_16x16x32_bf16 v[80:83], v[172:175], v[196:199], v[80:83]
	v_mfma_f32_16x16x32_bf16 v[68:71], v[164:167], v[204:207], v[68:71]
	v_mfma_f32_16x16x32_bf16 v[64:67], v[172:175], v[204:207], v[64:67]
	s_setprio 0
	s_barrier
	s_add_i32 s28, s28, s18
	v_lshl_add_u64 v[138:139], s[22:23], 0, v[208:209]
	s_mov_b32 m0, s28
	ds_read_b128 v[176:179], v143 offset:16384
	ds_read_b128 v[180:183], v143 offset:17408
	ds_read_b128 v[184:187], v143 offset:18432
	ds_read_b128 v[188:191], v143 offset:19456
	ds_read_b128 v[192:195], v143 offset:20480
	ds_read_b128 v[196:199], v143 offset:21504
	ds_read_b128 v[200:203], v143 offset:22528
	ds_read_b128 v[204:207], v143 offset:23552
	global_load_lds_dwordx4 v[138:139], off
	s_add_i32 m0, s28, 0x2000
	s_add_u32 s54, s22, 0x40000
	v_lshl_add_u64 v[210:211], s[22:23], 0, v[128:129]
	s_addc_u32 s55, s23, 0
	s_add_i32 s28, s29, s18
	global_load_lds_dwordx4 v[210:211], off
	v_lshl_add_u64 v[212:213], s[54:55], 0, v[208:209]
	s_mov_b32 m0, s28
	v_lshl_add_u64 v[222:223], s[24:25], 0, v[130:131]
	global_load_lds_dwordx4 v[212:213], off
	v_lshl_add_u64 v[212:213], s[54:55], 0, v[128:129]
	s_add_i32 m0, s28, 0x2000
	s_nop 0
	global_load_lds_dwordx4 v[212:213], off
	v_lshl_add_u64 v[212:213], s[24:25], 0, v[132:133]
	s_mov_b32 m0, s26
	s_nop 0
	global_load_lds_dwordx4 v[212:213], off
	s_mov_b32 m0, s34
	s_nop 0
	global_load_lds_dwordx4 v[222:223], off
	s_waitcnt vmcnt(8)
	s_waitcnt lgkmcnt(0)
	s_barrier
; #define PG8_STAGE(bufoff, gbase, voff) do { _Pragma("unroll") for (int _i = 0; _i < 2; ++_i) \
;         __builtin_amdgcn_global_load_lds((const unsigned*)((const char*)(gbase) + (voff)[_i]), (PG8_LAS unsigned*)(lds + (bufoff) + ldsw + _i * 8192), 16, 0, 0); } while (0)
; #define PG8_LDA(dst, b, h) do { _Pragma("unroll") for (int m = 0; m < 4; ++m) _Pragma("unroll") for (int k = 0; k < 2; ++k) dst[m][k] = *(const PG8_LAS bf16x8*)(lds + PG8_SA(b, h) + aoff + m * 2048 + k * 1024); } while (0)
; #define PG8_LDB(dst, b, h) do { _Pragma("unroll") for (int n = 0; n < 2; ++n) _Pragma("unroll") for (int k = 0; k < 2; ++k) dst[n][k] = *(const PG8_LAS bf16x8*)(lds + PG8_SB(b, h) + boff + n * 2048 + k * 1024); } while (0)
; #define PG8_MMA(ai, bj, At, Bt) do { __builtin_amdgcn_s_setprio(1); _Pragma("unroll") for (int m = 0; m < 4; ++m) _Pragma("unroll") for (int n = 0; n < 2; ++n) _Pragma("unroll") for (int k = 0; k < 2; ++k) \
;         acc[ai][bj][m][n] = __builtin_amdgcn_mfma_f32_16x16x32_bf16(Bt[n][k], At[m][k], acc[ai][bj][m][n], 0, 0, 0); __builtin_amdgcn_s_setprio(0); } while (0)
; #define PG8_WAIT_V(n) asm volatile("s_waitcnt vmcnt(" #n ")" ::: "memory")
; #define PG8_WAIT_L(n) asm volatile("s_waitcnt lgkmcnt(" #n ")" ::: "memory")
; #define PG8_BAR __builtin_amdgcn_s_barrier()
; #define PG8_SCHED __builtin_amdgcn_sched_barrier(0)
; template <class Epi, class Sched, bool ALIGN_EPI = false, bool SP2 = false>
; __device__ __forceinline__ void gemm_phase(PG8_LAS unsigned char* lds, const Gemm g, const Sched& S, const Epi& E) {
;     ...
;             PG8_WAIT_V(8); PG8_WAIT_L(0); PG8_BAR; PG8_MMA(1, 0, At, B0); PG8_MMA(1, 1, At, B1); PG8_BAR; PG8_SCHED;
;             PG8_LDB(B0, 1, 0); PG8_LDB(B1, 1, 1); PG8_SCHED; PG8_LDA(At, 1, 0); PG8_STAGE(PG8_SA(0, 1), a2 + hstepA, voffA);
;             PG8_WAIT_V(8); PG8_WAIT_L(0); PG8_BAR; PG8_MMA(0, 0, At, B0); PG8_MMA(0, 1, At, B1); PG8_BAR; PG8_SCHED;
	s_setprio 1
	s_waitcnt lgkmcnt(0)
	v_mfma_f32_16x16x32_bf16 v[60:63], v[144:147], v[176:179], 0
	v_mfma_f32_16x16x32_bf16 v[56:59], v[152:155], v[176:179], 0
	v_mfma_f32_16x16x32_bf16 v[44:47], v[144:147], v[184:187], 0
	v_mfma_f32_16x16x32_bf16 v[40:43], v[152:155], v[184:187], 0
	v_mfma_f32_16x16x32_bf16 v[28:31], v[144:147], v[192:195], 0
	v_mfma_f32_16x16x32_bf16 v[24:27], v[152:155], v[192:195], 0
	v_mfma_f32_16x16x32_bf16 v[12:15], v[144:147], v[200:203], 0
	v_mfma_f32_16x16x32_bf16 v[8:11], v[152:155], v[200:203], 0
	v_mfma_f32_16x16x32_bf16 v[60:63], v[148:151], v[180:183], v[60:63]
	v_mfma_f32_16x16x32_bf16 v[56:59], v[156:159], v[180:183], v[56:59]
	v_mfma_f32_16x16x32_bf16 v[44:47], v[148:151], v[188:191], v[44:47]
	v_mfma_f32_16x16x32_bf16 v[40:43], v[156:159], v[188:191], v[40:43]
	v_mfma_f32_16x16x32_bf16 v[28:31], v[148:151], v[196:199], v[28:31]
	v_mfma_f32_16x16x32_bf16 v[24:27], v[156:159], v[196:199], v[24:27]
	v_mfma_f32_16x16x32_bf16 v[12:15], v[148:151], v[204:207], v[12:15]
	v_mfma_f32_16x16x32_bf16 v[8:11], v[156:159], v[204:207], v[8:11]
	s_setprio 0
	s_setprio 1
	v_mfma_f32_16x16x32_bf16 v[52:55], v[160:163], v[176:179], 0
	v_mfma_f32_16x16x32_bf16 v[48:51], v[168:171], v[176:179], 0
	v_mfma_f32_16x16x32_bf16 v[36:39], v[160:163], v[184:187], 0
	v_mfma_f32_16x16x32_bf16 v[32:35], v[168:171], v[184:187], 0
	v_mfma_f32_16x16x32_bf16 v[20:23], v[160:163], v[192:195], 0
	v_mfma_f32_16x16x32_bf16 v[16:19], v[168:171], v[192:195], 0
	v_mfma_f32_16x16x32_bf16 v[4:7], v[160:163], v[200:203], 0
	v_mfma_f32_16x16x32_bf16 v[0:3], v[168:171], v[200:203], 0
	v_mfma_f32_16x16x32_bf16 v[52:55], v[164:167], v[180:183], v[52:55]
	v_mfma_f32_16x16x32_bf16 v[48:51], v[172:175], v[180:183], v[48:51]
	v_mfma_f32_16x16x32_bf16 v[36:39], v[164:167], v[188:191], v[36:39]
	v_mfma_f32_16x16x32_bf16 v[32:35], v[172:175], v[188:191], v[32:35]
	v_mfma_f32_16x16x32_bf16 v[20:23], v[164:167], v[196:199], v[20:23]
	v_mfma_f32_16x16x32_bf16 v[16:19], v[172:175], v[196:199], v[16:19]
	v_mfma_f32_16x16x32_bf16 v[4:7], v[164:167], v[204:207], v[4:7]
	v_mfma_f32_16x16x32_bf16 v[0:3], v[172:175], v[204:207], v[0:3]
	s_setprio 0
	s_barrier
	s_add_i32 s28, 0, 0x18000
	s_add_i32 s29, 0, 0x1c000
	v_add_u32_e32 v156, s28, v141
	v_add_u32_e32 v172, s29, v141
	ds_read_b128 v[144:147], v156
	ds_read_b128 v[148:151], v156 offset:1024
	ds_read_b128 v[152:155], v156 offset:2048
	ds_read_b128 v[156:159], v156 offset:3072
	ds_read_b128 v[160:163], v172
	ds_read_b128 v[164:167], v172 offset:1024
	ds_read_b128 v[168:171], v172 offset:2048
	ds_read_b128 v[172:175], v172 offset:3072
	s_add_u32 s24, s24, 0x40000
	s_addc_u32 s25, s25, 0
	s_mov_b32 m0, s35
	v_lshl_add_u64 v[224:225], s[24:25], 0, v[132:133]
	ds_read_b128 v[176:179], v143 offset:32768
	ds_read_b128 v[180:183], v143 offset:33792
	ds_read_b128 v[184:187], v143 offset:34816
	ds_read_b128 v[188:191], v143 offset:35840
	ds_read_b128 v[192:195], v143 offset:36864
	ds_read_b128 v[196:199], v143 offset:37888
	ds_read_b128 v[200:203], v143 offset:38912
	ds_read_b128 v[204:207], v143 offset:39936
	global_load_lds_dwordx4 v[224:225], off
	v_lshl_add_u64 v[224:225], s[24:25], 0, v[130:131]
	s_mov_b32 m0, s39
	s_nop 0
	global_load_lds_dwordx4 v[224:225], off
	s_waitcnt vmcnt(8)
	s_waitcnt lgkmcnt(0)
	s_barrier
	s_setprio 1
	s_waitcnt lgkmcnt(0)
	v_mfma_f32_16x16x32_bf16 v[124:127], v[144:147], v[176:179], v[124:127]
	v_mfma_f32_16x16x32_bf16 v[120:123], v[152:155], v[176:179], v[120:123]
	v_mfma_f32_16x16x32_bf16 v[108:111], v[144:147], v[184:187], v[108:111]
	v_mfma_f32_16x16x32_bf16 v[104:107], v[152:155], v[184:187], v[104:107]
	v_mfma_f32_16x16x32_bf16 v[92:95], v[144:147], v[192:195], v[92:95]
	v_mfma_f32_16x16x32_bf16 v[88:91], v[152:155], v[192:195], v[88:91]
	v_mfma_f32_16x16x32_bf16 v[76:79], v[144:147], v[200:203], v[76:79]
	v_mfma_f32_16x16x32_bf16 v[72:75], v[152:155], v[200:203], v[72:75]
	v_mfma_f32_16x16x32_bf16 v[124:127], v[148:151], v[180:183], v[124:127]
	v_mfma_f32_16x16x32_bf16 v[120:123], v[156:159], v[180:183], v[120:123]
	v_mfma_f32_16x16x32_bf16 v[108:111], v[148:151], v[188:191], v[108:111]
	v_mfma_f32_16x16x32_bf16 v[104:107], v[156:159], v[188:191], v[104:107]
	v_mfma_f32_16x16x32_bf16 v[92:95], v[148:151], v[196:199], v[92:95]
	v_mfma_f32_16x16x32_bf16 v[88:91], v[156:159], v[196:199], v[88:91]
	v_mfma_f32_16x16x32_bf16 v[76:79], v[148:151], v[204:207], v[76:79]
	v_mfma_f32_16x16x32_bf16 v[72:75], v[156:159], v[204:207], v[72:75]
	s_setprio 0
	s_setprio 1
	v_mfma_f32_16x16x32_bf16 v[116:119], v[160:163], v[176:179], v[116:119]
	v_mfma_f32_16x16x32_bf16 v[112:115], v[168:171], v[176:179], v[112:115]
	v_mfma_f32_16x16x32_bf16 v[100:103], v[160:163], v[184:187], v[100:103]
	v_mfma_f32_16x16x32_bf16 v[96:99], v[168:171], v[184:187], v[96:99]
	v_mfma_f32_16x16x32_bf16 v[84:87], v[160:163], v[192:195], v[84:87]
	v_mfma_f32_16x16x32_bf16 v[80:83], v[168:171], v[192:195], v[80:83]
	v_mfma_f32_16x16x32_bf16 v[68:71], v[160:163], v[200:203], v[68:71]
	v_mfma_f32_16x16x32_bf16 v[64:67], v[168:171], v[200:203], v[64:67]
	v_mfma_f32_16x16x32_bf16 v[116:119], v[164:167], v[180:183], v[116:119]
	v_mfma_f32_16x16x32_bf16 v[112:115], v[172:175], v[180:183], v[112:115]
	v_mfma_f32_16x16x32_bf16 v[100:103], v[164:167], v[188:191], v[100:103]
	v_mfma_f32_16x16x32_bf16 v[96:99], v[172:175], v[188:191], v[96:99]
	v_mfma_f32_16x16x32_bf16 v[84:87], v[164:167], v[196:199], v[84:87]
	v_mfma_f32_16x16x32_bf16 v[80:83], v[172:175], v[196:199], v[80:83]
	v_mfma_f32_16x16x32_bf16 v[68:71], v[164:167], v[204:207], v[68:71]
	v_mfma_f32_16x16x32_bf16 v[64:67], v[172:175], v[204:207], v[64:67]
	s_setprio 0
	s_barrier
; #define PG8_STAGE(bufoff, gbase, voff) do { _Pragma("unroll") for (int _i = 0; _i < 2; ++_i) \
;         __builtin_amdgcn_global_load_lds((const unsigned*)((const char*)(gbase) + (voff)[_i]), (PG8_LAS unsigned*)(lds + (bufoff) + ldsw + _i * 8192), 16, 0, 0); } while (0)
; #define PG8_LDA(dst, b, h) do { _Pragma("unroll") for (int m = 0; m < 4; ++m) _Pragma("unroll") for (int k = 0; k < 2; ++k) dst[m][k] = *(const PG8_LAS bf16x8*)(lds + PG8_SA(b, h) + aoff + m * 2048 + k * 1024); } while (0)
; #define PG8_MMA(ai, bj, At, Bt) do { __builtin_amdgcn_s_setprio(1); _Pragma("unroll") for (int m = 0; m < 4; ++m) _Pragma("unroll") for (int n = 0; n < 2; ++n) _Pragma("unroll") for (int k = 0; k < 2; ++k) \
;         acc[ai][bj][m][n] = __builtin_amdgcn_mfma_f32_16x16x32_bf16(Bt[n][k], At[m][k], acc[ai][bj][m][n], 0, 0, 0); __builtin_amdgcn_s_setprio(0); } while (0)
; #define PG8_WAIT_V(n) asm volatile("s_waitcnt vmcnt(" #n ")" ::: "memory")
; #define PG8_WAIT_L(n) asm volatile("s_waitcnt lgkmcnt(" #n ")" ::: "memory")
; #define PG8_BAR __builtin_amdgcn_s_barrier()
; #define PG8_SCHED __builtin_amdgcn_sched_barrier(0)
; template <class Epi, class Sched, bool ALIGN_EPI = false, bool SP2 = false>
; __device__ __forceinline__ void gemm_phase(PG8_LAS unsigned char* lds, const Gemm g, const Sched& S, const Epi& E) {
;     ...
;         for (int t = 0; t < nt; t += 2) {
;             const bool last = (t == nt - 2);
;     ...
;             PG8_LDA(At, 1, 1); PG8_STAGE(PG8_SB(1, 0), b3, voffB); PG8_STAGE(PG8_SB(1, 1), b3 + hstepB, voffB); PG8_STAGE(PG8_SA(1, 0), a3, voffA);
;             PG8_WAIT_V(8); PG8_WAIT_L(0); PG8_BAR; PG8_MMA(1, 0, At, B0); PG8_MMA(1, 1, At, B1); PG8_BAR; PG8_SCHED;
	s_add_i32 s24, s28, s18
	v_lshl_add_u64 v[138:139], v[138:139], 0, s[10:11]
	s_mov_b32 m0, s24
	ds_read_b128 v[176:179], v143 offset:49152
	ds_read_b128 v[180:183], v143 offset:50176
	ds_read_b128 v[184:187], v143 offset:51200
	ds_read_b128 v[188:191], v143 offset:52224
	ds_read_b128 v[192:195], v143 offset:53248
	ds_read_b128 v[196:199], v143 offset:54272
	ds_read_b128 v[200:203], v143 offset:55296
	ds_read_b128 v[204:207], v143 offset:56320
	global_load_lds_dwordx4 v[138:139], off
	s_add_i32 m0, s24, 0x2000
	s_add_u32 s22, s22, 0x40080
	v_lshl_add_u64 v[138:139], v[210:211], 0, s[10:11]
	s_addc_u32 s23, s23, 0
	s_add_i32 s24, s29, s18
	global_load_lds_dwordx4 v[138:139], off
	v_lshl_add_u64 v[138:139], s[22:23], 0, v[208:209]
	s_mov_b32 m0, s24
	s_nop 0
	global_load_lds_dwordx4 v[138:139], off
	v_lshl_add_u64 v[138:139], s[22:23], 0, v[128:129]
	s_add_i32 m0, s24, 0x2000
	s_nop 0
	global_load_lds_dwordx4 v[138:139], off
	v_lshl_add_u64 v[138:139], v[212:213], 0, s[10:11]
	s_mov_b32 m0, s50
	s_nop 0
	global_load_lds_dwordx4 v[138:139], off
	v_lshl_add_u64 v[138:139], v[222:223], 0, s[10:11]
	s_mov_b32 m0, s51
	s_nop 0
	global_load_lds_dwordx4 v[138:139], off
	s_waitcnt vmcnt(8)
	s_waitcnt lgkmcnt(0)
	s_barrier
	s_setprio 1
	s_waitcnt lgkmcnt(0)
	v_mfma_f32_16x16x32_bf16 v[60:63], v[144:147], v[176:179], v[60:63]
	v_mfma_f32_16x16x32_bf16 v[56:59], v[152:155], v[176:179], v[56:59]
	v_mfma_f32_16x16x32_bf16 v[44:47], v[144:147], v[184:187], v[44:47]
	v_mfma_f32_16x16x32_bf16 v[40:43], v[152:155], v[184:187], v[40:43]
	v_mfma_f32_16x16x32_bf16 v[28:31], v[144:147], v[192:195], v[28:31]
	v_mfma_f32_16x16x32_bf16 v[24:27], v[152:155], v[192:195], v[24:27]
	v_mfma_f32_16x16x32_bf16 v[12:15], v[144:147], v[200:203], v[12:15]
	v_mfma_f32_16x16x32_bf16 v[8:11], v[152:155], v[200:203], v[8:11]
	v_mfma_f32_16x16x32_bf16 v[60:63], v[148:151], v[180:183], v[60:63]
	v_mfma_f32_16x16x32_bf16 v[56:59], v[156:159], v[180:183], v[56:59]
	v_mfma_f32_16x16x32_bf16 v[44:47], v[148:151], v[188:191], v[44:47]
	v_mfma_f32_16x16x32_bf16 v[40:43], v[156:159], v[188:191], v[40:43]
	v_mfma_f32_16x16x32_bf16 v[28:31], v[148:151], v[196:199], v[28:31]
	v_mfma_f32_16x16x32_bf16 v[24:27], v[156:159], v[196:199], v[24:27]
	v_mfma_f32_16x16x32_bf16 v[12:15], v[148:151], v[204:207], v[12:15]
	v_mfma_f32_16x16x32_bf16 v[8:11], v[156:159], v[204:207], v[8:11]
	s_setprio 0
	s_setprio 1
	v_mfma_f32_16x16x32_bf16 v[52:55], v[160:163], v[176:179], v[52:55]
	v_mfma_f32_16x16x32_bf16 v[48:51], v[168:171], v[176:179], v[48:51]
	v_mfma_f32_16x16x32_bf16 v[36:39], v[160:163], v[184:187], v[36:39]
	v_mfma_f32_16x16x32_bf16 v[32:35], v[168:171], v[184:187], v[32:35]
	v_mfma_f32_16x16x32_bf16 v[20:23], v[160:163], v[192:195], v[20:23]
	v_mfma_f32_16x16x32_bf16 v[16:19], v[168:171], v[192:195], v[16:19]
	v_mfma_f32_16x16x32_bf16 v[4:7], v[160:163], v[200:203], v[4:7]
	v_mfma_f32_16x16x32_bf16 v[0:3], v[168:171], v[200:203], v[0:3]
	v_mfma_f32_16x16x32_bf16 v[52:55], v[164:167], v[180:183], v[52:55]
	v_mfma_f32_16x16x32_bf16 v[48:51], v[172:175], v[180:183], v[48:51]
	v_mfma_f32_16x16x32_bf16 v[36:39], v[164:167], v[188:191], v[36:39]
	v_mfma_f32_16x16x32_bf16 v[32:35], v[172:175], v[188:191], v[32:35]
	v_mfma_f32_16x16x32_bf16 v[20:23], v[164:167], v[196:199], v[20:23]
	v_mfma_f32_16x16x32_bf16 v[16:19], v[172:175], v[196:199], v[16:19]
	v_mfma_f32_16x16x32_bf16 v[4:7], v[164:167], v[204:207], v[4:7]
	v_mfma_f32_16x16x32_bf16 v[0:3], v[172:175], v[204:207], v[0:3]
	s_setprio 0
	s_barrier
	s_add_i32 s53, s53, 2
	s_add_u32 s20, s20, 0x100
	s_addc_u32 s21, s21, 0
	s_add_u32 s43, s43, 0x100
	s_addc_u32 s45, s45, 0
	s_cmp_gt_u32 s53, 13
	s_cbranch_scc0 .LBB0_135
	s_branch .Lpeel_done_135

; #define PG8_BAR __builtin_amdgcn_s_barrier()
; template <class Epi, class Sched, bool ALIGN_EPI = false, bool SP2 = false>
; __device__ __forceinline__ void gemm_phase(PG8_LAS unsigned char* lds, const Gemm g, const Sched& S, const Epi& E) {
;     ...
;         }
;         if constexpr (ALIGN_EPI) { if (wr == 0) PG8_BAR; }
;         if constexpr (!Epi::AFTER_DRAIN) { E(acc, cur, wr, wc, fr, fq); S.done(cur); }
.Lpeel_done_135:
	s_and_b64 vcc, exec, s[6:7]
	s_cbranch_vccz .LBB0_138
	s_barrier

; #define PG8_STAGE(bufoff, gbase, voff) do { _Pragma("unroll") for (int _i = 0; _i < 2; ++_i) \
;         __builtin_amdgcn_global_load_lds((const unsigned*)((const char*)(gbase) + (voff)[_i]), (PG8_LAS unsigned*)(lds + (bufoff) + ldsw + _i * 8192), 16, 0, 0); } while (0)
; #define PG8_LDA(dst, b, h) do { _Pragma("unroll") for (int m = 0; m < 4; ++m) _Pragma("unroll") for (int k = 0; k < 2; ++k) dst[m][k] = *(const PG8_LAS bf16x8*)(lds + PG8_SA(b, h) + aoff + m * 2048 + k * 1024); } while (0)
; #define PG8_LDB(dst, b, h) do { _Pragma("unroll") for (int n = 0; n < 2; ++n) _Pragma("unroll") for (int k = 0; k < 2; ++k) dst[n][k] = *(const PG8_LAS bf16x8*)(lds + PG8_SB(b, h) + boff + n * 2048 + k * 1024); } while (0)
; #define PG8_MMA(ai, bj, At, Bt) do { __builtin_amdgcn_s_setprio(1); _Pragma("unroll") for (int m = 0; m < 4; ++m) _Pragma("unroll") for (int n = 0; n < 2; ++n) _Pragma("unroll") for (int k = 0; k < 2; ++k) \
;         acc[ai][bj][m][n] = __builtin_amdgcn_mfma_f32_16x16x32_bf16(Bt[n][k], At[m][k], acc[ai][bj][m][n], 0, 0, 0); __builtin_amdgcn_s_setprio(0); } while (0)
; #define PG8_WAIT_V(n) asm volatile("s_waitcnt vmcnt(" #n ")" ::: "memory")
; #define PG8_BAR __builtin_amdgcn_s_barrier()
; template <class Epi, class Sched, bool ALIGN_EPI = false, bool SP2 = false>
; __device__ __forceinline__ void gemm_phase(PG8_LAS unsigned char* lds, const Gemm g, const Sched& S, const Epi& E) {
;     ...
;         for (int t = 0; t < nt; t += 2) {
;             const bool last = (t == nt - 2);
;             const char* a1 = cA + (size_t)(t + 1) * kstep;
;             const char* a2 = last ? nA : cA + (size_t)(t + 2) * kstep; const char* b2 = last ? nB : cB + (size_t)(t + 2) * kstep;
;             const char* a3 = a2 + kstep; const char* b3 = b2 + kstep;
;             if (last && has_next) S.a_ready(nxt);
;             if constexpr (SP2) {
;             PG8_LDB(B0, 0, 0); PG8_LDB(B1, 0, 1); PG8_SCHED; PG8_LDA(At, 0, 0); PG8_STAGE(PG8_SA(1, 1), a1 + hstepA, voffA);
;             PG8_WAIT_V(8); PG8_WAIT_L(0); PG8_BAR; PG8_MMA(0, 0, At, B0); PG8_MMA(0, 1, At, B1); PG8_BAR; PG8_SCHED;
;             PG8_LDA(At, 0, 1); PG8_STAGE(PG8_SB(0, 0), b2, voffB); PG8_STAGE(PG8_SB(0, 1), b2 + hstepB, voffB); PG8_STAGE(PG8_SA(0, 0), a2, voffA);
;             PG8_WAIT_V(8); PG8_WAIT_L(0); PG8_BAR; PG8_MMA(1, 0, At, B0); PG8_MMA(1, 1, At, B1); PG8_BAR; PG8_SCHED;
.LBB0_214:
	s_add_u32 s14, s20, 0x100
	s_addc_u32 s15, s21, 0
	s_mov_b32 s51, -2
	s_add_u32 s20, s0, 0x100
	s_addc_u32 s21, s1, 0
	s_add_i32 s28, 0, 0x10000
	s_cmp_eq_u32 s51, 40
	s_cselect_b32 s25, s5, s21
	s_cselect_b32 s24, s4, s20
	v_add_u32_e32 v138, s28, v141
	s_cselect_b32 s23, s45, s15
	s_cselect_b32 s22, s44, s14
	s_add_i32 s29, 0, 0x14000
	ds_read_b128 v[134:137], v138
	ds_read_b128 v[144:147], v138 offset:1024
	ds_read_b128 v[148:151], v138 offset:2048
	ds_read_b128 v[152:155], v138 offset:3072
	v_add_u32_e32 v138, s29, v141
	ds_read_b128 v[156:159], v138
	ds_read_b128 v[160:163], v138 offset:1024
	ds_read_b128 v[164:167], v138 offset:2048
	ds_read_b128 v[168:171], v138 offset:3072
	v_lshl_add_u64 v[138:139], s[0:1], 0, v[130:131]
	s_add_i32 m0, s26, 0xc000
	ds_read_b128 v[172:175], v143
	ds_read_b128 v[176:179], v143 offset:1024
	ds_read_b128 v[180:183], v143 offset:2048
	ds_read_b128 v[184:187], v143 offset:3072
	ds_read_b128 v[188:191], v143 offset:4096
	ds_read_b128 v[192:195], v143 offset:5120
	ds_read_b128 v[196:199], v143 offset:6144
	ds_read_b128 v[200:203], v143 offset:7168
	global_load_lds_dwordx4 v[138:139], off
	v_lshl_add_u64 v[138:139], s[0:1], 0, v[132:133]
	s_add_i32 m0, s26, 0xe000
	s_nop 0
	global_load_lds_dwordx4 v[138:139], off
	s_waitcnt vmcnt(8)
	s_waitcnt lgkmcnt(0)
	s_barrier
	s_setprio 1
	s_waitcnt lgkmcnt(0)
	v_mfma_f32_16x16x32_bf16 v[124:127], v[134:137], v[172:175], 0
	v_mfma_f32_16x16x32_bf16 v[120:123], v[148:151], v[172:175], 0
	v_mfma_f32_16x16x32_bf16 v[116:119], v[134:137], v[180:183], 0
	v_mfma_f32_16x16x32_bf16 v[112:115], v[148:151], v[180:183], 0
	v_mfma_f32_16x16x32_bf16 v[108:111], v[134:137], v[188:191], 0
	v_mfma_f32_16x16x32_bf16 v[100:103], v[148:151], v[188:191], 0
	v_mfma_f32_16x16x32_bf16 v[92:95], v[134:137], v[196:199], 0
	v_mfma_f32_16x16x32_bf16 v[80:83], v[148:151], v[196:199], 0
	v_mfma_f32_16x16x32_bf16 v[124:127], v[144:147], v[176:179], v[124:127]
	v_mfma_f32_16x16x32_bf16 v[120:123], v[152:155], v[176:179], v[120:123]
	v_mfma_f32_16x16x32_bf16 v[116:119], v[144:147], v[184:187], v[116:119]
	v_mfma_f32_16x16x32_bf16 v[112:115], v[152:155], v[184:187], v[112:115]
	v_mfma_f32_16x16x32_bf16 v[108:111], v[144:147], v[192:195], v[108:111]
	v_mfma_f32_16x16x32_bf16 v[100:103], v[152:155], v[192:195], v[100:103]
	v_mfma_f32_16x16x32_bf16 v[92:95], v[144:147], v[200:203], v[92:95]
	v_mfma_f32_16x16x32_bf16 v[80:83], v[152:155], v[200:203], v[80:83]
	s_setprio 0
	s_setprio 1
	v_mfma_f32_16x16x32_bf16 v[104:107], v[156:159], v[172:175], 0
	v_mfma_f32_16x16x32_bf16 v[96:99], v[164:167], v[172:175], 0
	v_mfma_f32_16x16x32_bf16 v[88:91], v[156:159], v[180:183], 0
	v_mfma_f32_16x16x32_bf16 v[84:87], v[164:167], v[180:183], 0
	v_mfma_f32_16x16x32_bf16 v[76:79], v[156:159], v[188:191], 0
	v_mfma_f32_16x16x32_bf16 v[72:75], v[164:167], v[188:191], 0
	v_mfma_f32_16x16x32_bf16 v[68:71], v[156:159], v[196:199], 0
	v_mfma_f32_16x16x32_bf16 v[64:67], v[164:167], v[196:199], 0
	v_mfma_f32_16x16x32_bf16 v[104:107], v[160:163], v[176:179], v[104:107]
	v_mfma_f32_16x16x32_bf16 v[96:99], v[168:171], v[176:179], v[96:99]
	v_mfma_f32_16x16x32_bf16 v[88:91], v[160:163], v[184:187], v[88:91]
	v_mfma_f32_16x16x32_bf16 v[84:87], v[168:171], v[184:187], v[84:87]
	v_mfma_f32_16x16x32_bf16 v[76:79], v[160:163], v[192:195], v[76:79]
	v_mfma_f32_16x16x32_bf16 v[72:75], v[168:171], v[192:195], v[72:75]
	v_mfma_f32_16x16x32_bf16 v[68:71], v[160:163], v[200:203], v[68:71]
	v_mfma_f32_16x16x32_bf16 v[64:67], v[168:171], v[200:203], v[64:67]
	s_setprio 0
	s_barrier
	s_add_i32 s0, s28, s19
	v_lshl_add_u64 v[138:139], s[22:23], 0, v[208:209]
	s_mov_b32 m0, s0
	ds_read_b128 v[172:175], v143 offset:16384
	ds_read_b128 v[176:179], v143 offset:17408
	ds_read_b128 v[180:183], v143 offset:18432
	ds_read_b128 v[184:187], v143 offset:19456
	ds_read_b128 v[188:191], v143 offset:20480
	ds_read_b128 v[192:195], v143 offset:21504
	ds_read_b128 v[196:199], v143 offset:22528
	ds_read_b128 v[200:203], v143 offset:23552
	global_load_lds_dwordx4 v[138:139], off
	s_add_i32 m0, s0, 0x2000
	s_add_u32 s0, s22, 0xb0000
	v_lshl_add_u64 v[204:205], s[22:23], 0, v[128:129]
	s_addc_u32 s1, s23, 0
	s_add_i32 s28, s29, s19
	global_load_lds_dwordx4 v[204:205], off
	v_lshl_add_u64 v[206:207], s[0:1], 0, v[208:209]
	s_mov_b32 m0, s28
	v_lshl_add_u64 v[210:211], s[24:25], 0, v[128:129]
	global_load_lds_dwordx4 v[206:207], off
	v_lshl_add_u64 v[206:207], s[0:1], 0, v[128:129]
	s_add_i32 m0, s28, 0x2000
	s_nop 0
	global_load_lds_dwordx4 v[206:207], off
	v_lshl_add_u64 v[206:207], s[24:25], 0, v[208:209]
	s_mov_b32 m0, s26
	s_nop 0
	global_load_lds_dwordx4 v[206:207], off
	s_mov_b32 m0, s34
	s_nop 0
	global_load_lds_dwordx4 v[210:211], off
	s_waitcnt vmcnt(8)
	s_waitcnt lgkmcnt(0)
	s_barrier
; #define PG8_STAGE(bufoff, gbase, voff) do { _Pragma("unroll") for (int _i = 0; _i < 2; ++_i) \
;         __builtin_amdgcn_global_load_lds((const unsigned*)((const char*)(gbase) + (voff)[_i]), (PG8_LAS unsigned*)(lds + (bufoff) + ldsw + _i * 8192), 16, 0, 0); } while (0)
; #define PG8_LDA(dst, b, h) do { _Pragma("unroll") for (int m = 0; m < 4; ++m) _Pragma("unroll") for (int k = 0; k < 2; ++k) dst[m][k] = *(const PG8_LAS bf16x8*)(lds + PG8_SA(b, h) + aoff + m * 2048 + k * 1024); } while (0)
; #define PG8_LDB(dst, b, h) do { _Pragma("unroll") for (int n = 0; n < 2; ++n) _Pragma("unroll") for (int k = 0; k < 2; ++k) dst[n][k] = *(const PG8_LAS bf16x8*)(lds + PG8_SB(b, h) + boff + n * 2048 + k * 1024); } while (0)
; #define PG8_MMA(ai, bj, At, Bt) do { __builtin_amdgcn_s_setprio(1); _Pragma("unroll") for (int m = 0; m < 4; ++m) _Pragma("unroll") for (int n = 0; n < 2; ++n) _Pragma("unroll") for (int k = 0; k < 2; ++k) \
;         acc[ai][bj][m][n] = __builtin_amdgcn_mfma_f32_16x16x32_bf16(Bt[n][k], At[m][k], acc[ai][bj][m][n], 0, 0, 0); __builtin_amdgcn_s_setprio(0); } while (0)
; #define PG8_WAIT_V(n) asm volatile("s_waitcnt vmcnt(" #n ")" ::: "memory")
; #define PG8_WAIT_L(n) asm volatile("s_waitcnt lgkmcnt(" #n ")" ::: "memory")
; #define PG8_BAR __builtin_amdgcn_s_barrier()
; #define PG8_SCHED __builtin_amdgcn_sched_barrier(0)
; template <class Epi, class Sched, bool ALIGN_EPI = false, bool SP2 = false>
; __device__ __forceinline__ void gemm_phase(PG8_LAS unsigned char* lds, const Gemm g, const Sched& S, const Epi& E) {
;     ...
;             PG8_WAIT_V(8); PG8_WAIT_L(0); PG8_BAR; PG8_MMA(1, 0, At, B0); PG8_MMA(1, 1, At, B1); PG8_BAR; PG8_SCHED;
;             PG8_LDB(B0, 1, 0); PG8_LDB(B1, 1, 1); PG8_SCHED; PG8_LDA(At, 1, 0); PG8_STAGE(PG8_SA(0, 1), a2 + hstepA, voffA);
;             PG8_WAIT_V(8); PG8_WAIT_L(0); PG8_BAR; PG8_MMA(0, 0, At, B0); PG8_MMA(0, 1, At, B1); PG8_BAR; PG8_SCHED;
	s_setprio 1
	s_waitcnt lgkmcnt(0)
	v_mfma_f32_16x16x32_bf16 v[60:63], v[134:137], v[172:175], 0
	v_mfma_f32_16x16x32_bf16 v[56:59], v[148:151], v[172:175], 0
	v_mfma_f32_16x16x32_bf16 v[52:55], v[134:137], v[180:183], 0
	v_mfma_f32_16x16x32_bf16 v[48:51], v[148:151], v[180:183], 0
	v_mfma_f32_16x16x32_bf16 v[44:47], v[134:137], v[188:191], 0
	v_mfma_f32_16x16x32_bf16 v[32:35], v[148:151], v[188:191], 0
	v_mfma_f32_16x16x32_bf16 v[16:19], v[134:137], v[196:199], 0
	v_mfma_f32_16x16x32_bf16 v[8:11], v[148:151], v[196:199], 0
	v_mfma_f32_16x16x32_bf16 v[60:63], v[144:147], v[176:179], v[60:63]
	v_mfma_f32_16x16x32_bf16 v[56:59], v[152:155], v[176:179], v[56:59]
	v_mfma_f32_16x16x32_bf16 v[52:55], v[144:147], v[184:187], v[52:55]
	v_mfma_f32_16x16x32_bf16 v[48:51], v[152:155], v[184:187], v[48:51]
	v_mfma_f32_16x16x32_bf16 v[44:47], v[144:147], v[192:195], v[44:47]
	v_mfma_f32_16x16x32_bf16 v[32:35], v[152:155], v[192:195], v[32:35]
	v_mfma_f32_16x16x32_bf16 v[16:19], v[144:147], v[200:203], v[16:19]
	v_mfma_f32_16x16x32_bf16 v[8:11], v[152:155], v[200:203], v[8:11]
	s_setprio 0
	s_setprio 1
	v_mfma_f32_16x16x32_bf16 v[40:43], v[156:159], v[172:175], 0
	v_mfma_f32_16x16x32_bf16 v[36:39], v[164:167], v[172:175], 0
	v_mfma_f32_16x16x32_bf16 v[28:31], v[156:159], v[180:183], 0
	v_mfma_f32_16x16x32_bf16 v[24:27], v[164:167], v[180:183], 0
	v_mfma_f32_16x16x32_bf16 v[20:23], v[156:159], v[188:191], 0
	v_mfma_f32_16x16x32_bf16 v[12:15], v[164:167], v[188:191], 0
	v_mfma_f32_16x16x32_bf16 v[4:7], v[156:159], v[196:199], 0
	v_mfma_f32_16x16x32_bf16 v[0:3], v[164:167], v[196:199], 0
	v_mfma_f32_16x16x32_bf16 v[40:43], v[160:163], v[176:179], v[40:43]
	v_mfma_f32_16x16x32_bf16 v[36:39], v[168:171], v[176:179], v[36:39]
	v_mfma_f32_16x16x32_bf16 v[28:31], v[160:163], v[184:187], v[28:31]
	v_mfma_f32_16x16x32_bf16 v[24:27], v[168:171], v[184:187], v[24:27]
	v_mfma_f32_16x16x32_bf16 v[20:23], v[160:163], v[192:195], v[20:23]
	v_mfma_f32_16x16x32_bf16 v[12:15], v[168:171], v[192:195], v[12:15]
	v_mfma_f32_16x16x32_bf16 v[4:7], v[160:163], v[200:203], v[4:7]
	v_mfma_f32_16x16x32_bf16 v[0:3], v[168:171], v[200:203], v[0:3]
	s_setprio 0
	s_barrier
	s_add_i32 s28, 0, 0x18000
	s_add_i32 s29, 0, 0x1c000
	v_add_u32_e32 v152, s28, v141
	v_add_u32_e32 v168, s29, v141
	ds_read_b128 v[134:137], v152
	ds_read_b128 v[144:147], v152 offset:1024
	ds_read_b128 v[148:151], v152 offset:2048
	ds_read_b128 v[152:155], v152 offset:3072
	ds_read_b128 v[156:159], v168
	ds_read_b128 v[160:163], v168 offset:1024
	ds_read_b128 v[164:167], v168 offset:2048
	ds_read_b128 v[168:171], v168 offset:3072
	s_add_u32 s0, s24, 0xb0000
	s_addc_u32 s1, s25, 0
	s_mov_b32 m0, s35
	v_lshl_add_u64 v[212:213], s[0:1], 0, v[208:209]
	ds_read_b128 v[172:175], v143 offset:32768
	ds_read_b128 v[176:179], v143 offset:33792
	ds_read_b128 v[180:183], v143 offset:34816
	ds_read_b128 v[184:187], v143 offset:35840
	ds_read_b128 v[188:191], v143 offset:36864
	ds_read_b128 v[192:195], v143 offset:37888
	ds_read_b128 v[196:199], v143 offset:38912
	ds_read_b128 v[200:203], v143 offset:39936
	global_load_lds_dwordx4 v[212:213], off
	v_lshl_add_u64 v[212:213], s[0:1], 0, v[128:129]
	s_mov_b32 m0, s39
	s_nop 0
	global_load_lds_dwordx4 v[212:213], off
	s_waitcnt vmcnt(8)
	s_waitcnt lgkmcnt(0)
	s_barrier
	s_setprio 1
	s_waitcnt lgkmcnt(0)
	v_mfma_f32_16x16x32_bf16 v[124:127], v[134:137], v[172:175], v[124:127]
	v_mfma_f32_16x16x32_bf16 v[120:123], v[148:151], v[172:175], v[120:123]
	v_mfma_f32_16x16x32_bf16 v[116:119], v[134:137], v[180:183], v[116:119]
	v_mfma_f32_16x16x32_bf16 v[112:115], v[148:151], v[180:183], v[112:115]
	v_mfma_f32_16x16x32_bf16 v[108:111], v[134:137], v[188:191], v[108:111]
	v_mfma_f32_16x16x32_bf16 v[100:103], v[148:151], v[188:191], v[100:103]
	v_mfma_f32_16x16x32_bf16 v[92:95], v[134:137], v[196:199], v[92:95]
	v_mfma_f32_16x16x32_bf16 v[80:83], v[148:151], v[196:199], v[80:83]
	v_mfma_f32_16x16x32_bf16 v[124:127], v[144:147], v[176:179], v[124:127]
	v_mfma_f32_16x16x32_bf16 v[120:123], v[152:155], v[176:179], v[120:123]
	v_mfma_f32_16x16x32_bf16 v[116:119], v[144:147], v[184:187], v[116:119]
	v_mfma_f32_16x16x32_bf16 v[112:115], v[152:155], v[184:187], v[112:115]
	v_mfma_f32_16x16x32_bf16 v[108:111], v[144:147], v[192:195], v[108:111]
	v_mfma_f32_16x16x32_bf16 v[100:103], v[152:155], v[192:195], v[100:103]
	v_mfma_f32_16x16x32_bf16 v[92:95], v[144:147], v[200:203], v[92:95]
	v_mfma_f32_16x16x32_bf16 v[80:83], v[152:155], v[200:203], v[80:83]
	s_setprio 0
	s_setprio 1
	v_mfma_f32_16x16x32_bf16 v[104:107], v[156:159], v[172:175], v[104:107]
	v_mfma_f32_16x16x32_bf16 v[96:99], v[164:167], v[172:175], v[96:99]
	v_mfma_f32_16x16x32_bf16 v[88:91], v[156:159], v[180:183], v[88:91]
	v_mfma_f32_16x16x32_bf16 v[84:87], v[164:167], v[180:183], v[84:87]
	v_mfma_f32_16x16x32_bf16 v[76:79], v[156:159], v[188:191], v[76:79]
	v_mfma_f32_16x16x32_bf16 v[72:75], v[164:167], v[188:191], v[72:75]
	v_mfma_f32_16x16x32_bf16 v[68:71], v[156:159], v[196:199], v[68:71]
	v_mfma_f32_16x16x32_bf16 v[64:67], v[164:167], v[196:199], v[64:67]
	v_mfma_f32_16x16x32_bf16 v[104:107], v[160:163], v[176:179], v[104:107]
	v_mfma_f32_16x16x32_bf16 v[96:99], v[168:171], v[176:179], v[96:99]
	v_mfma_f32_16x16x32_bf16 v[88:91], v[160:163], v[184:187], v[88:91]
	v_mfma_f32_16x16x32_bf16 v[84:87], v[168:171], v[184:187], v[84:87]
	v_mfma_f32_16x16x32_bf16 v[76:79], v[160:163], v[192:195], v[76:79]
	v_mfma_f32_16x16x32_bf16 v[72:75], v[168:171], v[192:195], v[72:75]
	v_mfma_f32_16x16x32_bf16 v[68:71], v[160:163], v[200:203], v[68:71]
	v_mfma_f32_16x16x32_bf16 v[64:67], v[168:171], v[200:203], v[64:67]
	s_setprio 0
	s_barrier
; #define PG8_STAGE(bufoff, gbase, voff) do { _Pragma("unroll") for (int _i = 0; _i < 2; ++_i) \
;         __builtin_amdgcn_global_load_lds((const unsigned*)((const char*)(gbase) + (voff)[_i]), (PG8_LAS unsigned*)(lds + (bufoff) + ldsw + _i * 8192), 16, 0, 0); } while (0)
; #define PG8_LDA(dst, b, h) do { _Pragma("unroll") for (int m = 0; m < 4; ++m) _Pragma("unroll") for (int k = 0; k < 2; ++k) dst[m][k] = *(const PG8_LAS bf16x8*)(lds + PG8_SA(b, h) + aoff + m * 2048 + k * 1024); } while (0)
; #define PG8_MMA(ai, bj, At, Bt) do { __builtin_amdgcn_s_setprio(1); _Pragma("unroll") for (int m = 0; m < 4; ++m) _Pragma("unroll") for (int n = 0; n < 2; ++n) _Pragma("unroll") for (int k = 0; k < 2; ++k) \
;         acc[ai][bj][m][n] = __builtin_amdgcn_mfma_f32_16x16x32_bf16(Bt[n][k], At[m][k], acc[ai][bj][m][n], 0, 0, 0); __builtin_amdgcn_s_setprio(0); } while (0)
; #define PG8_WAIT_V(n) asm volatile("s_waitcnt vmcnt(" #n ")" ::: "memory")
; #define PG8_WAIT_L(n) asm volatile("s_waitcnt lgkmcnt(" #n ")" ::: "memory")
; #define PG8_BAR __builtin_amdgcn_s_barrier()
; #define PG8_SCHED __builtin_amdgcn_sched_barrier(0)
; template <class Epi, class Sched, bool ALIGN_EPI = false, bool SP2 = false>
; __device__ __forceinline__ void gemm_phase(PG8_LAS unsigned char* lds, const Gemm g, const Sched& S, const Epi& E) {
;     ...
;             PG8_LDA(At, 1, 1); PG8_STAGE(PG8_SB(1, 0), b3, voffB); PG8_STAGE(PG8_SB(1, 1), b3 + hstepB, voffB); PG8_STAGE(PG8_SA(1, 0), a3, voffA);
;             PG8_WAIT_V(8); PG8_WAIT_L(0); PG8_BAR; PG8_MMA(1, 0, At, B0); PG8_MMA(1, 1, At, B1); PG8_BAR; PG8_SCHED;
	s_add_i32 s0, s28, s19
	v_lshl_add_u64 v[138:139], v[138:139], 0, s[10:11]
	s_mov_b32 m0, s0
	ds_read_b128 v[172:175], v143 offset:49152
	ds_read_b128 v[176:179], v143 offset:50176
	ds_read_b128 v[180:183], v143 offset:51200
	ds_read_b128 v[184:187], v143 offset:52224
	ds_read_b128 v[188:191], v143 offset:53248
	ds_read_b128 v[192:195], v143 offset:54272
	ds_read_b128 v[196:199], v143 offset:55296
	ds_read_b128 v[200:203], v143 offset:56320
	global_load_lds_dwordx4 v[138:139], off
	s_add_i32 m0, s0, 0x2000
	s_add_u32 s0, s22, 0xb0080
	v_lshl_add_u64 v[138:139], v[204:205], 0, s[10:11]
	s_addc_u32 s1, s23, 0
	s_add_i32 s22, s29, s19
	global_load_lds_dwordx4 v[138:139], off
	v_lshl_add_u64 v[138:139], s[0:1], 0, v[208:209]
	s_mov_b32 m0, s22
	s_nop 0
	global_load_lds_dwordx4 v[138:139], off
	v_lshl_add_u64 v[138:139], s[0:1], 0, v[128:129]
	s_add_i32 m0, s22, 0x2000
	s_nop 0
	global_load_lds_dwordx4 v[138:139], off
	v_lshl_add_u64 v[138:139], v[206:207], 0, s[10:11]
	s_mov_b32 m0, s46
	s_nop 0
	global_load_lds_dwordx4 v[138:139], off
	v_lshl_add_u64 v[138:139], v[210:211], 0, s[10:11]
	s_mov_b32 m0, s47
	s_nop 0
	global_load_lds_dwordx4 v[138:139], off
	s_waitcnt vmcnt(8)
	s_waitcnt lgkmcnt(0)
	s_barrier
	s_setprio 1
	s_waitcnt lgkmcnt(0)
	v_mfma_f32_16x16x32_bf16 v[60:63], v[134:137], v[172:175], v[60:63]
	v_mfma_f32_16x16x32_bf16 v[56:59], v[148:151], v[172:175], v[56:59]
	v_mfma_f32_16x16x32_bf16 v[52:55], v[134:137], v[180:183], v[52:55]
	v_mfma_f32_16x16x32_bf16 v[48:51], v[148:151], v[180:183], v[48:51]
	v_mfma_f32_16x16x32_bf16 v[44:47], v[134:137], v[188:191], v[44:47]
	v_mfma_f32_16x16x32_bf16 v[32:35], v[148:151], v[188:191], v[32:35]
	v_mfma_f32_16x16x32_bf16 v[16:19], v[134:137], v[196:199], v[16:19]
	v_mfma_f32_16x16x32_bf16 v[8:11], v[148:151], v[196:199], v[8:11]
	v_mfma_f32_16x16x32_bf16 v[60:63], v[144:147], v[176:179], v[60:63]
	v_mfma_f32_16x16x32_bf16 v[56:59], v[152:155], v[176:179], v[56:59]
	v_mfma_f32_16x16x32_bf16 v[52:55], v[144:147], v[184:187], v[52:55]
	v_mfma_f32_16x16x32_bf16 v[48:51], v[152:155], v[184:187], v[48:51]
	v_mfma_f32_16x16x32_bf16 v[44:47], v[144:147], v[192:195], v[44:47]
	v_mfma_f32_16x16x32_bf16 v[32:35], v[152:155], v[192:195], v[32:35]
	v_mfma_f32_16x16x32_bf16 v[16:19], v[144:147], v[200:203], v[16:19]
	v_mfma_f32_16x16x32_bf16 v[8:11], v[152:155], v[200:203], v[8:11]
	s_setprio 0
	s_setprio 1
	v_mfma_f32_16x16x32_bf16 v[40:43], v[156:159], v[172:175], v[40:43]
	v_mfma_f32_16x16x32_bf16 v[36:39], v[164:167], v[172:175], v[36:39]
	v_mfma_f32_16x16x32_bf16 v[28:31], v[156:159], v[180:183], v[28:31]
	v_mfma_f32_16x16x32_bf16 v[24:27], v[164:167], v[180:183], v[24:27]
	v_mfma_f32_16x16x32_bf16 v[20:23], v[156:159], v[188:191], v[20:23]
	v_mfma_f32_16x16x32_bf16 v[12:15], v[164:167], v[188:191], v[12:15]
	v_mfma_f32_16x16x32_bf16 v[4:7], v[156:159], v[196:199], v[4:7]
	v_mfma_f32_16x16x32_bf16 v[0:3], v[164:167], v[196:199], v[0:3]
	v_mfma_f32_16x16x32_bf16 v[40:43], v[160:163], v[176:179], v[40:43]
	v_mfma_f32_16x16x32_bf16 v[36:39], v[168:171], v[176:179], v[36:39]
	v_mfma_f32_16x16x32_bf16 v[28:31], v[160:163], v[184:187], v[28:31]
	v_mfma_f32_16x16x32_bf16 v[24:27], v[168:171], v[184:187], v[24:27]
	v_mfma_f32_16x16x32_bf16 v[20:23], v[160:163], v[192:195], v[20:23]
	v_mfma_f32_16x16x32_bf16 v[12:15], v[168:171], v[192:195], v[12:15]
	v_mfma_f32_16x16x32_bf16 v[4:7], v[160:163], v[200:203], v[4:7]
	v_mfma_f32_16x16x32_bf16 v[0:3], v[168:171], v[200:203], v[0:3]
	s_setprio 0
	s_barrier
	s_add_i32 s51, s51, 2
	s_add_u32 s14, s14, 0x100
	s_addc_u32 s15, s15, 0
	s_cmp_gt_u32 s51, 41
	s_mov_b64 s[0:1], s[20:21]
	s_cbranch_scc0 .LBB0_215
	s_branch .Lpeel_done_215

; #define PG8_BAR __builtin_amdgcn_s_barrier()
; template <class Epi, class Sched, bool ALIGN_EPI = false, bool SP2 = false>
; __device__ __forceinline__ void gemm_phase(PG8_LAS unsigned char* lds, const Gemm g, const Sched& S, const Epi& E) {
;     ...
;         }
;         if constexpr (ALIGN_EPI) { if (wr == 0) PG8_BAR; }
;         if constexpr (!Epi::AFTER_DRAIN) { E(acc, cur, wr, wc, fr, fq); S.done(cur); }
.Lpeel_done_215:
	s_and_b64 vcc, exec, s[42:43]
	s_cbranch_vccz .LBB0_218
	s_barrier

; #define PG8_STAGE(bufoff, gbase, voff) do { _Pragma("unroll") for (int _i = 0; _i < 2; ++_i) \
;         __builtin_amdgcn_global_load_lds((const unsigned*)((const char*)(gbase) + (voff)[_i]), (PG8_LAS unsigned*)(lds + (bufoff) + ldsw + _i * 8192), 16, 0, 0); } while (0)
; #define PG8_LDA(dst, b, h) do { _Pragma("unroll") for (int m = 0; m < 4; ++m) _Pragma("unroll") for (int k = 0; k < 2; ++k) dst[m][k] = *(const PG8_LAS bf16x8*)(lds + PG8_SA(b, h) + aoff + m * 2048 + k * 1024); } while (0)
; #define PG8_LDB(dst, b, h) do { _Pragma("unroll") for (int n = 0; n < 2; ++n) _Pragma("unroll") for (int k = 0; k < 2; ++k) dst[n][k] = *(const PG8_LAS bf16x8*)(lds + PG8_SB(b, h) + boff + n * 2048 + k * 1024); } while (0)
; #define PG8_MMA(ai, bj, At, Bt) do { __builtin_amdgcn_s_setprio(1); _Pragma("unroll") for (int m = 0; m < 4; ++m) _Pragma("unroll") for (int n = 0; n < 2; ++n) _Pragma("unroll") for (int k = 0; k < 2; ++k) \
;         acc[ai][bj][m][n] = __builtin_amdgcn_mfma_f32_16x16x32_bf16(Bt[n][k], At[m][k], acc[ai][bj][m][n], 0, 0, 0); __builtin_amdgcn_s_setprio(0); } while (0)
; #define PG8_WAIT_V(n) asm volatile("s_waitcnt vmcnt(" #n ")" ::: "memory")
; #define PG8_BAR __builtin_amdgcn_s_barrier()
; template <class Epi, class Sched, bool ALIGN_EPI = false, bool SP2 = false>
; __device__ __forceinline__ void gemm_phase(PG8_LAS unsigned char* lds, const Gemm g, const Sched& S, const Epi& E) {
;     ...
;         for (int t = 0; t < nt; t += 2) {
;             const bool last = (t == nt - 2);
;             const char* a1 = cA + (size_t)(t + 1) * kstep;
;             const char* a2 = last ? nA : cA + (size_t)(t + 2) * kstep; const char* b2 = last ? nB : cB + (size_t)(t + 2) * kstep;
;             const char* a3 = a2 + kstep; const char* b3 = b2 + kstep;
;             if (last && has_next) S.a_ready(nxt);
;             if constexpr (SP2) {
;             PG8_LDB(B0, 0, 0); PG8_LDB(B1, 0, 1); PG8_SCHED; PG8_LDA(At, 0, 0); PG8_STAGE(PG8_SA(1, 1), a1 + hstepA, voffA);
;             PG8_WAIT_V(8); PG8_WAIT_L(0); PG8_BAR; PG8_MMA(0, 0, At, B0); PG8_MMA(0, 1, At, B1); PG8_BAR; PG8_SCHED;
;             PG8_LDA(At, 0, 1); PG8_STAGE(PG8_SB(0, 0), b2, voffB); PG8_STAGE(PG8_SB(0, 1), b2 + hstepB, voffB); PG8_STAGE(PG8_SA(0, 0), a2, voffA);
;             PG8_WAIT_V(8); PG8_WAIT_L(0); PG8_BAR; PG8_MMA(1, 0, At, B0); PG8_MMA(1, 1, At, B1); PG8_BAR; PG8_SCHED;
.LBB0_337:
	s_ashr_i32 s41, s40, 31
	s_lshl_b64 s[14:15], s[40:41], 19
	v_readlane_b32 s22, v252, 2
	v_readlane_b32 s23, v252, 3
	s_add_u32 s44, s22, s14
	s_addc_u32 s45, s23, s15
	s_and_b64 s[14:15], s[4:5], exec
	s_cselect_b32 s14, s45, s1
	s_cselect_b32 s15, s44, s0
	s_ashr_i32 s21, s20, 31
	s_lshl_b64 s[22:23], s[20:21], 19
	s_add_u32 s46, s31, s22
	v_readlane_b32 s21, v253, 50
	s_addc_u32 s47, s21, s23
	s_and_b64 s[22:23], s[4:5], exec
	s_cselect_b32 s21, s47, s25
	s_cselect_b32 s41, s46, s24
	s_add_u32 s0, s0, 0x40080
	s_addc_u32 s1, s1, 0
	s_add_u32 s49, s24, 0x100
	s_addc_u32 s50, s25, 0
	s_mov_b32 s51, -2
	s_add_u32 s22, s0, 0xfffc0080
	s_addc_u32 s23, s1, -1
	s_add_i32 s28, 0, 0x10000
	s_cmp_eq_u32 s51, 12
	s_cselect_b32 s25, s14, s23
	s_cselect_b32 s24, s15, s22
	v_add_u32_e32 v138, s28, v142
	s_cselect_b32 s23, s21, s50
	s_cselect_b32 s22, s41, s49
	s_add_i32 s29, 0, 0x14000
	ds_read_b128 v[146:149], v138
	ds_read_b128 v[150:153], v138 offset:1024
	ds_read_b128 v[154:157], v138 offset:2048
	ds_read_b128 v[158:161], v138 offset:3072
	v_add_u32_e32 v138, s29, v142
	ds_read_b128 v[162:165], v138
	ds_read_b128 v[166:169], v138 offset:1024
	ds_read_b128 v[170:173], v138 offset:2048
	ds_read_b128 v[174:177], v138 offset:3072
	v_lshl_add_u64 v[140:141], s[0:1], 0, v[134:135]
	s_add_i32 m0, s26, 0xc000
	ds_read_b128 v[178:181], v144
	ds_read_b128 v[182:185], v144 offset:1024
	ds_read_b128 v[186:189], v144 offset:2048
	ds_read_b128 v[190:193], v144 offset:3072
	ds_read_b128 v[194:197], v144 offset:4096
	ds_read_b128 v[198:201], v144 offset:5120
	ds_read_b128 v[202:205], v144 offset:6144
	ds_read_b128 v[210:213], v144 offset:7168
	global_load_lds_dwordx4 v[140:141], off
	v_lshl_add_u64 v[140:141], s[0:1], 0, v[136:137]
	s_add_i32 m0, s26, 0xe000
	s_nop 0
	global_load_lds_dwordx4 v[140:141], off
	s_waitcnt vmcnt(8)
	s_waitcnt lgkmcnt(0)
	s_barrier
	s_setprio 1
	s_waitcnt lgkmcnt(0)
	v_mfma_f32_16x16x32_bf16 v[124:127], v[146:149], v[178:181], 0
	v_mfma_f32_16x16x32_bf16 v[120:123], v[154:157], v[178:181], 0
	v_mfma_f32_16x16x32_bf16 v[116:119], v[146:149], v[186:189], 0
	v_mfma_f32_16x16x32_bf16 v[108:111], v[154:157], v[186:189], 0
	v_mfma_f32_16x16x32_bf16 v[100:103], v[146:149], v[194:197], 0
	v_mfma_f32_16x16x32_bf16 v[92:95], v[154:157], v[194:197], 0
	v_mfma_f32_16x16x32_bf16 v[84:87], v[146:149], v[202:205], 0
	v_mfma_f32_16x16x32_bf16 v[76:79], v[154:157], v[202:205], 0
	v_mfma_f32_16x16x32_bf16 v[124:127], v[150:153], v[182:185], v[124:127]
	v_mfma_f32_16x16x32_bf16 v[120:123], v[158:161], v[182:185], v[120:123]
	v_mfma_f32_16x16x32_bf16 v[116:119], v[150:153], v[190:193], v[116:119]
	v_mfma_f32_16x16x32_bf16 v[108:111], v[158:161], v[190:193], v[108:111]
	v_mfma_f32_16x16x32_bf16 v[100:103], v[150:153], v[198:201], v[100:103]
	v_mfma_f32_16x16x32_bf16 v[92:95], v[158:161], v[198:201], v[92:95]
	v_mfma_f32_16x16x32_bf16 v[84:87], v[150:153], v[210:213], v[84:87]
	v_mfma_f32_16x16x32_bf16 v[76:79], v[158:161], v[210:213], v[76:79]
	s_setprio 0
	s_setprio 1
	v_mfma_f32_16x16x32_bf16 v[112:115], v[162:165], v[178:181], 0
	v_mfma_f32_16x16x32_bf16 v[104:107], v[170:173], v[178:181], 0
	v_mfma_f32_16x16x32_bf16 v[96:99], v[162:165], v[186:189], 0
	v_mfma_f32_16x16x32_bf16 v[88:91], v[170:173], v[186:189], 0
	v_mfma_f32_16x16x32_bf16 v[80:83], v[162:165], v[194:197], 0
	v_mfma_f32_16x16x32_bf16 v[72:75], v[170:173], v[194:197], 0
	v_mfma_f32_16x16x32_bf16 v[68:71], v[162:165], v[202:205], 0
	v_mfma_f32_16x16x32_bf16 v[64:67], v[170:173], v[202:205], 0
	v_mfma_f32_16x16x32_bf16 v[112:115], v[166:169], v[182:185], v[112:115]
	v_mfma_f32_16x16x32_bf16 v[104:107], v[174:177], v[182:185], v[104:107]
	v_mfma_f32_16x16x32_bf16 v[96:99], v[166:169], v[190:193], v[96:99]
	v_mfma_f32_16x16x32_bf16 v[88:91], v[174:177], v[190:193], v[88:91]
	v_mfma_f32_16x16x32_bf16 v[80:83], v[166:169], v[198:201], v[80:83]
	v_mfma_f32_16x16x32_bf16 v[72:75], v[174:177], v[198:201], v[72:75]
	v_mfma_f32_16x16x32_bf16 v[68:71], v[166:169], v[210:213], v[68:71]
	v_mfma_f32_16x16x32_bf16 v[64:67], v[174:177], v[210:213], v[64:67]
	s_setprio 0
	s_barrier
	s_add_i32 s28, s28, s18
	v_lshl_add_u64 v[140:141], s[22:23], 0, v[208:209]
	s_mov_b32 m0, s28
	ds_read_b128 v[178:181], v144 offset:16384
	ds_read_b128 v[182:185], v144 offset:17408
	ds_read_b128 v[186:189], v144 offset:18432
	ds_read_b128 v[190:193], v144 offset:19456
	ds_read_b128 v[194:197], v144 offset:20480
	ds_read_b128 v[198:201], v144 offset:21504
	ds_read_b128 v[202:205], v144 offset:22528
	ds_read_b128 v[210:213], v144 offset:23552
	global_load_lds_dwordx4 v[140:141], off
	s_add_i32 m0, s28, 0x2000
	s_add_u32 s52, s22, 0x40000
	v_lshl_add_u64 v[206:207], s[22:23], 0, v[128:129]
	s_addc_u32 s53, s23, 0
	s_add_i32 s28, s29, s18
	global_load_lds_dwordx4 v[206:207], off
	v_lshl_add_u64 v[222:223], s[52:53], 0, v[208:209]
	s_mov_b32 m0, s28
	v_lshl_add_u64 v[224:225], s[24:25], 0, v[130:131]
	global_load_lds_dwordx4 v[222:223], off
	v_lshl_add_u64 v[222:223], s[52:53], 0, v[128:129]
	s_add_i32 m0, s28, 0x2000
	s_nop 0
	global_load_lds_dwordx4 v[222:223], off
	v_lshl_add_u64 v[222:223], s[24:25], 0, v[132:133]
	s_mov_b32 m0, s26
	s_nop 0
	global_load_lds_dwordx4 v[222:223], off
	s_mov_b32 m0, s34
	s_nop 0
	global_load_lds_dwordx4 v[224:225], off
	s_waitcnt vmcnt(8)
	s_waitcnt lgkmcnt(0)
	s_barrier
; #define PG8_STAGE(bufoff, gbase, voff) do { _Pragma("unroll") for (int _i = 0; _i < 2; ++_i) \
;         __builtin_amdgcn_global_load_lds((const unsigned*)((const char*)(gbase) + (voff)[_i]), (PG8_LAS unsigned*)(lds + (bufoff) + ldsw + _i * 8192), 16, 0, 0); } while (0)
; #define PG8_LDA(dst, b, h) do { _Pragma("unroll") for (int m = 0; m < 4; ++m) _Pragma("unroll") for (int k = 0; k < 2; ++k) dst[m][k] = *(const PG8_LAS bf16x8*)(lds + PG8_SA(b, h) + aoff + m * 2048 + k * 1024); } while (0)
; #define PG8_LDB(dst, b, h) do { _Pragma("unroll") for (int n = 0; n < 2; ++n) _Pragma("unroll") for (int k = 0; k < 2; ++k) dst[n][k] = *(const PG8_LAS bf16x8*)(lds + PG8_SB(b, h) + boff + n * 2048 + k * 1024); } while (0)
; #define PG8_MMA(ai, bj, At, Bt) do { __builtin_amdgcn_s_setprio(1); _Pragma("unroll") for (int m = 0; m < 4; ++m) _Pragma("unroll") for (int n = 0; n < 2; ++n) _Pragma("unroll") for (int k = 0; k < 2; ++k) \
;         acc[ai][bj][m][n] = __builtin_amdgcn_mfma_f32_16x16x32_bf16(Bt[n][k], At[m][k], acc[ai][bj][m][n], 0, 0, 0); __builtin_amdgcn_s_setprio(0); } while (0)
; #define PG8_WAIT_V(n) asm volatile("s_waitcnt vmcnt(" #n ")" ::: "memory")
; #define PG8_WAIT_L(n) asm volatile("s_waitcnt lgkmcnt(" #n ")" ::: "memory")
; #define PG8_BAR __builtin_amdgcn_s_barrier()
; #define PG8_SCHED __builtin_amdgcn_sched_barrier(0)
; template <class Epi, class Sched, bool ALIGN_EPI = false, bool SP2 = false>
; __device__ __forceinline__ void gemm_phase(PG8_LAS unsigned char* lds, const Gemm g, const Sched& S, const Epi& E) {
;     ...
;             PG8_WAIT_V(8); PG8_WAIT_L(0); PG8_BAR; PG8_MMA(1, 0, At, B0); PG8_MMA(1, 1, At, B1); PG8_BAR; PG8_SCHED;
;             PG8_LDB(B0, 1, 0); PG8_LDB(B1, 1, 1); PG8_SCHED; PG8_LDA(At, 1, 0); PG8_STAGE(PG8_SA(0, 1), a2 + hstepA, voffA);
;             PG8_WAIT_V(8); PG8_WAIT_L(0); PG8_BAR; PG8_MMA(0, 0, At, B0); PG8_MMA(0, 1, At, B1); PG8_BAR; PG8_SCHED;
	s_setprio 1
	s_waitcnt lgkmcnt(0)
	v_mfma_f32_16x16x32_bf16 v[60:63], v[146:149], v[178:181], 0
	v_mfma_f32_16x16x32_bf16 v[56:59], v[154:157], v[178:181], 0
	v_mfma_f32_16x16x32_bf16 v[52:55], v[146:149], v[186:189], 0
	v_mfma_f32_16x16x32_bf16 v[44:47], v[154:157], v[186:189], 0
	v_mfma_f32_16x16x32_bf16 v[36:39], v[146:149], v[194:197], 0
	v_mfma_f32_16x16x32_bf16 v[28:31], v[154:157], v[194:197], 0
	v_mfma_f32_16x16x32_bf16 v[20:23], v[146:149], v[202:205], 0
	v_mfma_f32_16x16x32_bf16 v[12:15], v[154:157], v[202:205], 0
	v_mfma_f32_16x16x32_bf16 v[60:63], v[150:153], v[182:185], v[60:63]
	v_mfma_f32_16x16x32_bf16 v[56:59], v[158:161], v[182:185], v[56:59]
	v_mfma_f32_16x16x32_bf16 v[52:55], v[150:153], v[190:193], v[52:55]
	v_mfma_f32_16x16x32_bf16 v[44:47], v[158:161], v[190:193], v[44:47]
	v_mfma_f32_16x16x32_bf16 v[36:39], v[150:153], v[198:201], v[36:39]
	v_mfma_f32_16x16x32_bf16 v[28:31], v[158:161], v[198:201], v[28:31]
	v_mfma_f32_16x16x32_bf16 v[20:23], v[150:153], v[210:213], v[20:23]
	v_mfma_f32_16x16x32_bf16 v[12:15], v[158:161], v[210:213], v[12:15]
	s_setprio 0
	s_setprio 1
	v_mfma_f32_16x16x32_bf16 v[48:51], v[162:165], v[178:181], 0
	v_mfma_f32_16x16x32_bf16 v[40:43], v[170:173], v[178:181], 0
	v_mfma_f32_16x16x32_bf16 v[32:35], v[162:165], v[186:189], 0
	v_mfma_f32_16x16x32_bf16 v[24:27], v[170:173], v[186:189], 0
	v_mfma_f32_16x16x32_bf16 v[16:19], v[162:165], v[194:197], 0
	v_mfma_f32_16x16x32_bf16 v[8:11], v[170:173], v[194:197], 0
	v_mfma_f32_16x16x32_bf16 v[4:7], v[162:165], v[202:205], 0
	v_mfma_f32_16x16x32_bf16 v[0:3], v[170:173], v[202:205], 0
	v_mfma_f32_16x16x32_bf16 v[48:51], v[166:169], v[182:185], v[48:51]
	v_mfma_f32_16x16x32_bf16 v[40:43], v[174:177], v[182:185], v[40:43]
	v_mfma_f32_16x16x32_bf16 v[32:35], v[166:169], v[190:193], v[32:35]
	v_mfma_f32_16x16x32_bf16 v[24:27], v[174:177], v[190:193], v[24:27]
	v_mfma_f32_16x16x32_bf16 v[16:19], v[166:169], v[198:201], v[16:19]
	v_mfma_f32_16x16x32_bf16 v[8:11], v[174:177], v[198:201], v[8:11]
	v_mfma_f32_16x16x32_bf16 v[4:7], v[166:169], v[210:213], v[4:7]
	v_mfma_f32_16x16x32_bf16 v[0:3], v[174:177], v[210:213], v[0:3]
	s_setprio 0
	s_barrier
	s_add_i32 s28, 0, 0x18000
	v_add_u32_e32 v138, s28, v142
	s_add_i32 s29, 0, 0x1c000
	ds_read_b128 v[146:149], v138
	ds_read_b128 v[150:153], v138 offset:1024
	ds_read_b128 v[154:157], v138 offset:2048
	ds_read_b128 v[158:161], v138 offset:3072
	v_add_u32_e32 v138, s29, v142
	ds_read_b128 v[162:165], v138
	ds_read_b128 v[166:169], v138 offset:1024
	ds_read_b128 v[170:173], v138 offset:2048
	ds_read_b128 v[174:177], v138 offset:3072
	s_add_u32 s24, s24, 0x40000
	s_addc_u32 s25, s25, 0
	s_mov_b32 m0, s35
	v_lshl_add_u64 v[226:227], s[24:25], 0, v[132:133]
	ds_read_b128 v[178:181], v144 offset:32768
	ds_read_b128 v[182:185], v144 offset:33792
	ds_read_b128 v[186:189], v144 offset:34816
	ds_read_b128 v[190:193], v144 offset:35840
	ds_read_b128 v[194:197], v144 offset:36864
	ds_read_b128 v[198:201], v144 offset:37888
	ds_read_b128 v[202:205], v144 offset:38912
	ds_read_b128 v[210:213], v144 offset:39936
	global_load_lds_dwordx4 v[226:227], off
	v_lshl_add_u64 v[226:227], s[24:25], 0, v[130:131]
	s_mov_b32 m0, s39
	s_nop 0
	global_load_lds_dwordx4 v[226:227], off
	s_waitcnt vmcnt(8)
	s_waitcnt lgkmcnt(0)
	s_barrier
	s_setprio 1
	s_waitcnt lgkmcnt(0)
	v_mfma_f32_16x16x32_bf16 v[124:127], v[146:149], v[178:181], v[124:127]
	v_mfma_f32_16x16x32_bf16 v[120:123], v[154:157], v[178:181], v[120:123]
	v_mfma_f32_16x16x32_bf16 v[116:119], v[146:149], v[186:189], v[116:119]
	v_mfma_f32_16x16x32_bf16 v[108:111], v[154:157], v[186:189], v[108:111]
	v_mfma_f32_16x16x32_bf16 v[100:103], v[146:149], v[194:197], v[100:103]
	v_mfma_f32_16x16x32_bf16 v[92:95], v[154:157], v[194:197], v[92:95]
	v_mfma_f32_16x16x32_bf16 v[84:87], v[146:149], v[202:205], v[84:87]
	v_mfma_f32_16x16x32_bf16 v[76:79], v[154:157], v[202:205], v[76:79]
	v_mfma_f32_16x16x32_bf16 v[124:127], v[150:153], v[182:185], v[124:127]
	v_mfma_f32_16x16x32_bf16 v[120:123], v[158:161], v[182:185], v[120:123]
	v_mfma_f32_16x16x32_bf16 v[116:119], v[150:153], v[190:193], v[116:119]
	v_mfma_f32_16x16x32_bf16 v[108:111], v[158:161], v[190:193], v[108:111]
	v_mfma_f32_16x16x32_bf16 v[100:103], v[150:153], v[198:201], v[100:103]
	v_mfma_f32_16x16x32_bf16 v[92:95], v[158:161], v[198:201], v[92:95]
	v_mfma_f32_16x16x32_bf16 v[84:87], v[150:153], v[210:213], v[84:87]
	v_mfma_f32_16x16x32_bf16 v[76:79], v[158:161], v[210:213], v[76:79]
	s_setprio 0
	s_setprio 1
	v_mfma_f32_16x16x32_bf16 v[112:115], v[162:165], v[178:181], v[112:115]
	v_mfma_f32_16x16x32_bf16 v[104:107], v[170:173], v[178:181], v[104:107]
	v_mfma_f32_16x16x32_bf16 v[96:99], v[162:165], v[186:189], v[96:99]
	v_mfma_f32_16x16x32_bf16 v[88:91], v[170:173], v[186:189], v[88:91]
	v_mfma_f32_16x16x32_bf16 v[80:83], v[162:165], v[194:197], v[80:83]
	v_mfma_f32_16x16x32_bf16 v[72:75], v[170:173], v[194:197], v[72:75]
	v_mfma_f32_16x16x32_bf16 v[68:71], v[162:165], v[202:205], v[68:71]
	v_mfma_f32_16x16x32_bf16 v[64:67], v[170:173], v[202:205], v[64:67]
	v_mfma_f32_16x16x32_bf16 v[112:115], v[166:169], v[182:185], v[112:115]
	v_mfma_f32_16x16x32_bf16 v[104:107], v[174:177], v[182:185], v[104:107]
	v_mfma_f32_16x16x32_bf16 v[96:99], v[166:169], v[190:193], v[96:99]
	v_mfma_f32_16x16x32_bf16 v[88:91], v[174:177], v[190:193], v[88:91]
	v_mfma_f32_16x16x32_bf16 v[80:83], v[166:169], v[198:201], v[80:83]
	v_mfma_f32_16x16x32_bf16 v[72:75], v[174:177], v[198:201], v[72:75]
	v_mfma_f32_16x16x32_bf16 v[68:71], v[166:169], v[210:213], v[68:71]
	v_mfma_f32_16x16x32_bf16 v[64:67], v[174:177], v[210:213], v[64:67]
	s_setprio 0
	s_barrier
; #define PG8_STAGE(bufoff, gbase, voff) do { _Pragma("unroll") for (int _i = 0; _i < 2; ++_i) \
;         __builtin_amdgcn_global_load_lds((const unsigned*)((const char*)(gbase) + (voff)[_i]), (PG8_LAS unsigned*)(lds + (bufoff) + ldsw + _i * 8192), 16, 0, 0); } while (0)
; #define PG8_LDA(dst, b, h) do { _Pragma("unroll") for (int m = 0; m < 4; ++m) _Pragma("unroll") for (int k = 0; k < 2; ++k) dst[m][k] = *(const PG8_LAS bf16x8*)(lds + PG8_SA(b, h) + aoff + m * 2048 + k * 1024); } while (0)
; #define PG8_MMA(ai, bj, At, Bt) do { __builtin_amdgcn_s_setprio(1); _Pragma("unroll") for (int m = 0; m < 4; ++m) _Pragma("unroll") for (int n = 0; n < 2; ++n) _Pragma("unroll") for (int k = 0; k < 2; ++k) \
;         acc[ai][bj][m][n] = __builtin_amdgcn_mfma_f32_16x16x32_bf16(Bt[n][k], At[m][k], acc[ai][bj][m][n], 0, 0, 0); __builtin_amdgcn_s_setprio(0); } while (0)
; #define PG8_WAIT_V(n) asm volatile("s_waitcnt vmcnt(" #n ")" ::: "memory")
; #define PG8_WAIT_L(n) asm volatile("s_waitcnt lgkmcnt(" #n ")" ::: "memory")
; #define PG8_BAR __builtin_amdgcn_s_barrier()
; #define PG8_SCHED __builtin_amdgcn_sched_barrier(0)
; template <class Epi, class Sched, bool ALIGN_EPI = false, bool SP2 = false>
; __device__ __forceinline__ void gemm_phase(PG8_LAS unsigned char* lds, const Gemm g, const Sched& S, const Epi& E) {
;     ...
;             PG8_LDA(At, 1, 1); PG8_STAGE(PG8_SB(1, 0), b3, voffB); PG8_STAGE(PG8_SB(1, 1), b3 + hstepB, voffB); PG8_STAGE(PG8_SA(1, 0), a3, voffA);
;             PG8_WAIT_V(8); PG8_WAIT_L(0); PG8_BAR; PG8_MMA(1, 0, At, B0); PG8_MMA(1, 1, At, B1); PG8_BAR; PG8_SCHED;
	s_add_i32 s24, s28, s18
	v_lshl_add_u64 v[140:141], v[140:141], 0, s[10:11]
	s_mov_b32 m0, s24
	ds_read_b128 v[178:181], v144 offset:49152
	ds_read_b128 v[182:185], v144 offset:50176
	ds_read_b128 v[186:189], v144 offset:51200
	ds_read_b128 v[190:193], v144 offset:52224
	ds_read_b128 v[194:197], v144 offset:53248
	ds_read_b128 v[198:201], v144 offset:54272
	ds_read_b128 v[202:205], v144 offset:55296
	ds_read_b128 v[210:213], v144 offset:56320
	global_load_lds_dwordx4 v[140:141], off
	s_add_i32 m0, s24, 0x2000
	s_add_u32 s22, s22, 0x40080
	v_lshl_add_u64 v[140:141], v[206:207], 0, s[10:11]
	s_addc_u32 s23, s23, 0
	s_add_i32 s24, s29, s18
	global_load_lds_dwordx4 v[140:141], off
	v_lshl_add_u64 v[140:141], s[22:23], 0, v[208:209]
	s_mov_b32 m0, s24
	s_nop 0
	global_load_lds_dwordx4 v[140:141], off
	v_lshl_add_u64 v[140:141], s[22:23], 0, v[128:129]
	s_add_i32 m0, s24, 0x2000
	s_nop 0
	global_load_lds_dwordx4 v[140:141], off
	v_lshl_add_u64 v[140:141], v[222:223], 0, s[10:11]
	s_mov_b32 m0, s12
	s_nop 0
	global_load_lds_dwordx4 v[140:141], off
	v_lshl_add_u64 v[140:141], v[224:225], 0, s[10:11]
	s_mov_b32 m0, s43
	s_nop 0
	global_load_lds_dwordx4 v[140:141], off
	s_waitcnt vmcnt(8)
	s_waitcnt lgkmcnt(0)
	s_barrier
	s_setprio 1
	s_waitcnt lgkmcnt(0)
	v_mfma_f32_16x16x32_bf16 v[60:63], v[146:149], v[178:181], v[60:63]
	v_mfma_f32_16x16x32_bf16 v[56:59], v[154:157], v[178:181], v[56:59]
	v_mfma_f32_16x16x32_bf16 v[52:55], v[146:149], v[186:189], v[52:55]
	v_mfma_f32_16x16x32_bf16 v[44:47], v[154:157], v[186:189], v[44:47]
	v_mfma_f32_16x16x32_bf16 v[36:39], v[146:149], v[194:197], v[36:39]
	v_mfma_f32_16x16x32_bf16 v[28:31], v[154:157], v[194:197], v[28:31]
	v_mfma_f32_16x16x32_bf16 v[20:23], v[146:149], v[202:205], v[20:23]
	v_mfma_f32_16x16x32_bf16 v[12:15], v[154:157], v[202:205], v[12:15]
	v_mfma_f32_16x16x32_bf16 v[60:63], v[150:153], v[182:185], v[60:63]
	v_mfma_f32_16x16x32_bf16 v[56:59], v[158:161], v[182:185], v[56:59]
	v_mfma_f32_16x16x32_bf16 v[52:55], v[150:153], v[190:193], v[52:55]
	v_mfma_f32_16x16x32_bf16 v[44:47], v[158:161], v[190:193], v[44:47]
	v_mfma_f32_16x16x32_bf16 v[36:39], v[150:153], v[198:201], v[36:39]
	v_mfma_f32_16x16x32_bf16 v[28:31], v[158:161], v[198:201], v[28:31]
	v_mfma_f32_16x16x32_bf16 v[20:23], v[150:153], v[210:213], v[20:23]
	v_mfma_f32_16x16x32_bf16 v[12:15], v[158:161], v[210:213], v[12:15]
	s_setprio 0
	s_setprio 1
	v_mfma_f32_16x16x32_bf16 v[48:51], v[162:165], v[178:181], v[48:51]
	v_mfma_f32_16x16x32_bf16 v[40:43], v[170:173], v[178:181], v[40:43]
	v_mfma_f32_16x16x32_bf16 v[32:35], v[162:165], v[186:189], v[32:35]
	v_mfma_f32_16x16x32_bf16 v[24:27], v[170:173], v[186:189], v[24:27]
	v_mfma_f32_16x16x32_bf16 v[16:19], v[162:165], v[194:197], v[16:19]
	v_mfma_f32_16x16x32_bf16 v[8:11], v[170:173], v[194:197], v[8:11]
	v_mfma_f32_16x16x32_bf16 v[4:7], v[162:165], v[202:205], v[4:7]
	v_mfma_f32_16x16x32_bf16 v[0:3], v[170:173], v[202:205], v[0:3]
	v_mfma_f32_16x16x32_bf16 v[48:51], v[166:169], v[182:185], v[48:51]
	v_mfma_f32_16x16x32_bf16 v[40:43], v[174:177], v[182:185], v[40:43]
	v_mfma_f32_16x16x32_bf16 v[32:35], v[166:169], v[190:193], v[32:35]
	v_mfma_f32_16x16x32_bf16 v[24:27], v[174:177], v[190:193], v[24:27]
	v_mfma_f32_16x16x32_bf16 v[16:19], v[166:169], v[198:201], v[16:19]
	v_mfma_f32_16x16x32_bf16 v[8:11], v[174:177], v[198:201], v[8:11]
	v_mfma_f32_16x16x32_bf16 v[4:7], v[166:169], v[210:213], v[4:7]
	v_mfma_f32_16x16x32_bf16 v[0:3], v[174:177], v[210:213], v[0:3]
	s_setprio 0
	s_barrier
	s_add_i32 s51, s51, 2
	s_add_u32 s0, s0, 0x100
	s_addc_u32 s1, s1, 0
	s_add_u32 s49, s49, 0x100
	s_addc_u32 s50, s50, 0
	s_cmp_gt_u32 s51, 13
	s_cbranch_scc0 .LBB0_338
	s_branch .Lpeel_done_338

; #define PG8_BAR __builtin_amdgcn_s_barrier()
; template <class Epi, class Sched, bool ALIGN_EPI = false, bool SP2 = false>
; __device__ __forceinline__ void gemm_phase(PG8_LAS unsigned char* lds, const Gemm g, const Sched& S, const Epi& E) {
;     ...
;         }
;         if constexpr (ALIGN_EPI) { if (wr == 0) PG8_BAR; }
;         if constexpr (!Epi::AFTER_DRAIN) { E(acc, cur, wr, wc, fr, fq); S.done(cur); }
.Lpeel_done_338:
	s_and_b64 vcc, exec, s[8:9]
	s_cbranch_vccz .LBB0_341
	s_barrier

; #define PG8_STAGE(bufoff, gbase, voff) do { _Pragma("unroll") for (int _i = 0; _i < 2; ++_i) \
;         __builtin_amdgcn_global_load_lds((const unsigned*)((const char*)(gbase) + (voff)[_i]), (PG8_LAS unsigned*)(lds + (bufoff) + ldsw + _i * 8192), 16, 0, 0); } while (0)
; #define PG8_LDA(dst, b, h) do { _Pragma("unroll") for (int m = 0; m < 4; ++m) _Pragma("unroll") for (int k = 0; k < 2; ++k) dst[m][k] = *(const PG8_LAS bf16x8*)(lds + PG8_SA(b, h) + aoff + m * 2048 + k * 1024); } while (0)
; #define PG8_LDB(dst, b, h) do { _Pragma("unroll") for (int n = 0; n < 2; ++n) _Pragma("unroll") for (int k = 0; k < 2; ++k) dst[n][k] = *(const PG8_LAS bf16x8*)(lds + PG8_SB(b, h) + boff + n * 2048 + k * 1024); } while (0)
; #define PG8_MMA(ai, bj, At, Bt) do { __builtin_amdgcn_s_setprio(1); _Pragma("unroll") for (int m = 0; m < 4; ++m) _Pragma("unroll") for (int n = 0; n < 2; ++n) _Pragma("unroll") for (int k = 0; k < 2; ++k) \
;         acc[ai][bj][m][n] = __builtin_amdgcn_mfma_f32_16x16x32_bf16(Bt[n][k], At[m][k], acc[ai][bj][m][n], 0, 0, 0); __builtin_amdgcn_s_setprio(0); } while (0)
; #define PG8_WAIT_V(n) asm volatile("s_waitcnt vmcnt(" #n ")" ::: "memory")
; #define PG8_BAR __builtin_amdgcn_s_barrier()
; template <class Epi, class Sched, bool ALIGN_EPI = false, bool SP2 = false>
; __device__ __forceinline__ void gemm_phase(PG8_LAS unsigned char* lds, const Gemm g, const Sched& S, const Epi& E) {
;     ...
;         for (int t = 0; t < nt; t += 2) {
;             const bool last = (t == nt - 2);
;             const char* a1 = cA + (size_t)(t + 1) * kstep;
;             const char* a2 = last ? nA : cA + (size_t)(t + 2) * kstep; const char* b2 = last ? nB : cB + (size_t)(t + 2) * kstep;
;             const char* a3 = a2 + kstep; const char* b3 = b2 + kstep;
;             if (last && has_next) S.a_ready(nxt);
;             if constexpr (SP2) {
;             PG8_LDB(B0, 0, 0); PG8_LDB(B1, 0, 1); PG8_SCHED; PG8_LDA(At, 0, 0); PG8_STAGE(PG8_SA(1, 1), a1 + hstepA, voffA);
;             PG8_WAIT_V(8); PG8_WAIT_L(0); PG8_BAR; PG8_MMA(0, 0, At, B0); PG8_MMA(0, 1, At, B1); PG8_BAR; PG8_SCHED;
;             PG8_LDA(At, 0, 1); PG8_STAGE(PG8_SB(0, 0), b2, voffB); PG8_STAGE(PG8_SB(0, 1), b2 + hstepB, voffB); PG8_STAGE(PG8_SA(0, 0), a2, voffA);
;             PG8_WAIT_V(8); PG8_WAIT_L(0); PG8_BAR; PG8_MMA(1, 0, At, B0); PG8_MMA(1, 1, At, B1); PG8_BAR; PG8_SCHED;
.LBB0_353:
	s_ashr_i32 s41, s40, 31
	s_lshl_b64 s[14:15], s[40:41], 19
	v_readlane_b32 s1, v253, 51
	s_add_u32 s24, s1, s14
	v_readlane_b32 s1, v253, 52
	s_addc_u32 s25, s1, s15
	s_and_b64 s[14:15], s[4:5], exec
	s_cselect_b32 s14, s25, s45
	s_cselect_b32 s15, s24, s44
	s_ashr_i32 s1, s0, 31
	s_lshl_b64 s[22:23], s[0:1], 19
	v_readlane_b32 s28, v252, 2
	v_readlane_b32 s29, v252, 3
	s_add_u32 s42, s28, s22
	s_addc_u32 s43, s29, s23
	s_and_b64 s[22:23], s[4:5], exec
	s_cselect_b32 s1, s43, s47
	s_cselect_b32 s41, s42, s46
	s_add_u32 s44, s44, 0x40080
	s_addc_u32 s45, s45, 0
	s_add_u32 s49, s46, 0x100
	s_addc_u32 s50, s47, 0
	s_mov_b32 s51, -2
	s_add_u32 s22, s44, 0xfffc0080
	s_addc_u32 s23, s45, -1
	s_add_i32 s28, 0, 0x10000
	s_cmp_eq_u32 s51, 12
	s_cselect_b32 s47, s14, s23
	s_cselect_b32 s46, s15, s22
	s_cselect_b32 s23, s1, s50
	s_cselect_b32 s22, s41, s49
	s_add_i32 s29, 0, 0x14000
	v_add_u32_e32 v154, s28, v139
	v_add_u32_e32 v170, s29, v139
	ds_read_b128 v[142:145], v154
	ds_read_b128 v[146:149], v154 offset:1024
	ds_read_b128 v[150:153], v154 offset:2048
	ds_read_b128 v[154:157], v154 offset:3072
	ds_read_b128 v[158:161], v170
	ds_read_b128 v[162:165], v170 offset:1024
	ds_read_b128 v[166:169], v170 offset:2048
	ds_read_b128 v[170:173], v170 offset:3072
	v_lshl_add_u64 v[206:207], s[44:45], 0, v[134:135]
	s_add_i32 m0, s21, 0xc000
	ds_read_b128 v[174:177], v141
	ds_read_b128 v[178:181], v141 offset:1024
	ds_read_b128 v[182:185], v141 offset:2048
	ds_read_b128 v[186:189], v141 offset:3072
	ds_read_b128 v[190:193], v141 offset:4096
	ds_read_b128 v[194:197], v141 offset:5120
	ds_read_b128 v[198:201], v141 offset:6144
	ds_read_b128 v[202:205], v141 offset:7168
	global_load_lds_dwordx4 v[206:207], off
	v_lshl_add_u64 v[206:207], s[44:45], 0, v[136:137]
	s_add_i32 m0, s21, 0xe000
	s_nop 0
	global_load_lds_dwordx4 v[206:207], off
	s_waitcnt vmcnt(8)
	s_waitcnt lgkmcnt(0)
	s_barrier
	s_setprio 1
	s_waitcnt lgkmcnt(0)
	v_mfma_f32_16x16x32_bf16 v[124:127], v[142:145], v[174:177], 0
	v_mfma_f32_16x16x32_bf16 v[120:123], v[150:153], v[174:177], 0
	v_mfma_f32_16x16x32_bf16 v[116:119], v[142:145], v[182:185], 0
	v_mfma_f32_16x16x32_bf16 v[112:115], v[150:153], v[182:185], 0
	v_mfma_f32_16x16x32_bf16 v[100:103], v[142:145], v[190:193], 0
	v_mfma_f32_16x16x32_bf16 v[96:99], v[150:153], v[190:193], 0
	v_mfma_f32_16x16x32_bf16 v[84:87], v[142:145], v[198:201], 0
	v_mfma_f32_16x16x32_bf16 v[80:83], v[150:153], v[198:201], 0
	v_mfma_f32_16x16x32_bf16 v[124:127], v[146:149], v[178:181], v[124:127]
	v_mfma_f32_16x16x32_bf16 v[120:123], v[154:157], v[178:181], v[120:123]
	v_mfma_f32_16x16x32_bf16 v[116:119], v[146:149], v[186:189], v[116:119]
	v_mfma_f32_16x16x32_bf16 v[112:115], v[154:157], v[186:189], v[112:115]
	v_mfma_f32_16x16x32_bf16 v[100:103], v[146:149], v[194:197], v[100:103]
	v_mfma_f32_16x16x32_bf16 v[96:99], v[154:157], v[194:197], v[96:99]
	v_mfma_f32_16x16x32_bf16 v[84:87], v[146:149], v[202:205], v[84:87]
	v_mfma_f32_16x16x32_bf16 v[80:83], v[154:157], v[202:205], v[80:83]
	s_setprio 0
	s_setprio 1
	v_mfma_f32_16x16x32_bf16 v[108:111], v[158:161], v[174:177], 0
	v_mfma_f32_16x16x32_bf16 v[104:107], v[166:169], v[174:177], 0
	v_mfma_f32_16x16x32_bf16 v[92:95], v[158:161], v[182:185], 0
	v_mfma_f32_16x16x32_bf16 v[88:91], v[166:169], v[182:185], 0
	v_mfma_f32_16x16x32_bf16 v[76:79], v[158:161], v[190:193], 0
	v_mfma_f32_16x16x32_bf16 v[72:75], v[166:169], v[190:193], 0
	v_mfma_f32_16x16x32_bf16 v[68:71], v[158:161], v[198:201], 0
	v_mfma_f32_16x16x32_bf16 v[64:67], v[166:169], v[198:201], 0
	v_mfma_f32_16x16x32_bf16 v[108:111], v[162:165], v[178:181], v[108:111]
	v_mfma_f32_16x16x32_bf16 v[104:107], v[170:173], v[178:181], v[104:107]
	v_mfma_f32_16x16x32_bf16 v[92:95], v[162:165], v[186:189], v[92:95]
	v_mfma_f32_16x16x32_bf16 v[88:91], v[170:173], v[186:189], v[88:91]
	v_mfma_f32_16x16x32_bf16 v[76:79], v[162:165], v[194:197], v[76:79]
	v_mfma_f32_16x16x32_bf16 v[72:75], v[170:173], v[194:197], v[72:75]
	v_mfma_f32_16x16x32_bf16 v[68:71], v[162:165], v[202:205], v[68:71]
	v_mfma_f32_16x16x32_bf16 v[64:67], v[170:173], v[202:205], v[64:67]
	s_setprio 0
	s_barrier
	s_add_i32 s28, s28, s18
	v_lshl_add_u64 v[206:207], s[22:23], 0, v[208:209]
	s_mov_b32 m0, s28
	ds_read_b128 v[174:177], v141 offset:16384
	ds_read_b128 v[178:181], v141 offset:17408
	ds_read_b128 v[182:185], v141 offset:18432
	ds_read_b128 v[186:189], v141 offset:19456
	ds_read_b128 v[190:193], v141 offset:20480
	ds_read_b128 v[194:197], v141 offset:21504
	ds_read_b128 v[198:201], v141 offset:22528
	ds_read_b128 v[202:205], v141 offset:23552
	global_load_lds_dwordx4 v[206:207], off
	s_add_i32 m0, s28, 0x2000
	s_add_u32 s52, s22, 0x40000
	v_lshl_add_u64 v[210:211], s[22:23], 0, v[128:129]
	s_addc_u32 s53, s23, 0
	s_add_i32 s28, s29, s18
	global_load_lds_dwordx4 v[210:211], off
	v_lshl_add_u64 v[212:213], s[52:53], 0, v[208:209]
	s_mov_b32 m0, s28
	v_lshl_add_u64 v[222:223], s[46:47], 0, v[130:131]
	global_load_lds_dwordx4 v[212:213], off
	v_lshl_add_u64 v[212:213], s[52:53], 0, v[128:129]
	s_add_i32 m0, s28, 0x2000
	s_nop 0
	global_load_lds_dwordx4 v[212:213], off
	v_lshl_add_u64 v[212:213], s[46:47], 0, v[132:133]
	s_mov_b32 m0, s21
	s_nop 0
	global_load_lds_dwordx4 v[212:213], off
	s_mov_b32 m0, s12
	s_nop 0
	global_load_lds_dwordx4 v[222:223], off
	s_waitcnt vmcnt(8)
	s_waitcnt lgkmcnt(0)
	s_barrier
; #define PG8_STAGE(bufoff, gbase, voff) do { _Pragma("unroll") for (int _i = 0; _i < 2; ++_i) \
;         __builtin_amdgcn_global_load_lds((const unsigned*)((const char*)(gbase) + (voff)[_i]), (PG8_LAS unsigned*)(lds + (bufoff) + ldsw + _i * 8192), 16, 0, 0); } while (0)
; #define PG8_LDA(dst, b, h) do { _Pragma("unroll") for (int m = 0; m < 4; ++m) _Pragma("unroll") for (int k = 0; k < 2; ++k) dst[m][k] = *(const PG8_LAS bf16x8*)(lds + PG8_SA(b, h) + aoff + m * 2048 + k * 1024); } while (0)
; #define PG8_LDB(dst, b, h) do { _Pragma("unroll") for (int n = 0; n < 2; ++n) _Pragma("unroll") for (int k = 0; k < 2; ++k) dst[n][k] = *(const PG8_LAS bf16x8*)(lds + PG8_SB(b, h) + boff + n * 2048 + k * 1024); } while (0)
; #define PG8_MMA(ai, bj, At, Bt) do { __builtin_amdgcn_s_setprio(1); _Pragma("unroll") for (int m = 0; m < 4; ++m) _Pragma("unroll") for (int n = 0; n < 2; ++n) _Pragma("unroll") for (int k = 0; k < 2; ++k) \
;         acc[ai][bj][m][n] = __builtin_amdgcn_mfma_f32_16x16x32_bf16(Bt[n][k], At[m][k], acc[ai][bj][m][n], 0, 0, 0); __builtin_amdgcn_s_setprio(0); } while (0)
; #define PG8_WAIT_V(n) asm volatile("s_waitcnt vmcnt(" #n ")" ::: "memory")
; #define PG8_WAIT_L(n) asm volatile("s_waitcnt lgkmcnt(" #n ")" ::: "memory")
; #define PG8_BAR __builtin_amdgcn_s_barrier()
; #define PG8_SCHED __builtin_amdgcn_sched_barrier(0)
; template <class Epi, class Sched, bool ALIGN_EPI = false, bool SP2 = false>
; __device__ __forceinline__ void gemm_phase(PG8_LAS unsigned char* lds, const Gemm g, const Sched& S, const Epi& E) {
;     ...
;             PG8_WAIT_V(8); PG8_WAIT_L(0); PG8_BAR; PG8_MMA(1, 0, At, B0); PG8_MMA(1, 1, At, B1); PG8_BAR; PG8_SCHED;
;             PG8_LDB(B0, 1, 0); PG8_LDB(B1, 1, 1); PG8_SCHED; PG8_LDA(At, 1, 0); PG8_STAGE(PG8_SA(0, 1), a2 + hstepA, voffA);
;             PG8_WAIT_V(8); PG8_WAIT_L(0); PG8_BAR; PG8_MMA(0, 0, At, B0); PG8_MMA(0, 1, At, B1); PG8_BAR; PG8_SCHED;
	s_setprio 1
	s_waitcnt lgkmcnt(0)
	v_mfma_f32_16x16x32_bf16 v[60:63], v[142:145], v[174:177], 0
	v_mfma_f32_16x16x32_bf16 v[56:59], v[150:153], v[174:177], 0
	v_mfma_f32_16x16x32_bf16 v[52:55], v[142:145], v[182:185], 0
	v_mfma_f32_16x16x32_bf16 v[48:51], v[150:153], v[182:185], 0
	v_mfma_f32_16x16x32_bf16 v[36:39], v[142:145], v[190:193], 0
	v_mfma_f32_16x16x32_bf16 v[32:35], v[150:153], v[190:193], 0
	v_mfma_f32_16x16x32_bf16 v[20:23], v[142:145], v[198:201], 0
	v_mfma_f32_16x16x32_bf16 v[16:19], v[150:153], v[198:201], 0
	v_mfma_f32_16x16x32_bf16 v[60:63], v[146:149], v[178:181], v[60:63]
	v_mfma_f32_16x16x32_bf16 v[56:59], v[154:157], v[178:181], v[56:59]
	v_mfma_f32_16x16x32_bf16 v[52:55], v[146:149], v[186:189], v[52:55]
	v_mfma_f32_16x16x32_bf16 v[48:51], v[154:157], v[186:189], v[48:51]
	v_mfma_f32_16x16x32_bf16 v[36:39], v[146:149], v[194:197], v[36:39]
	v_mfma_f32_16x16x32_bf16 v[32:35], v[154:157], v[194:197], v[32:35]
	v_mfma_f32_16x16x32_bf16 v[20:23], v[146:149], v[202:205], v[20:23]
	v_mfma_f32_16x16x32_bf16 v[16:19], v[154:157], v[202:205], v[16:19]
	s_setprio 0
	s_setprio 1
	v_mfma_f32_16x16x32_bf16 v[44:47], v[158:161], v[174:177], 0
	v_mfma_f32_16x16x32_bf16 v[40:43], v[166:169], v[174:177], 0
	v_mfma_f32_16x16x32_bf16 v[28:31], v[158:161], v[182:185], 0
	v_mfma_f32_16x16x32_bf16 v[24:27], v[166:169], v[182:185], 0
	v_mfma_f32_16x16x32_bf16 v[12:15], v[158:161], v[190:193], 0
	v_mfma_f32_16x16x32_bf16 v[8:11], v[166:169], v[190:193], 0
	v_mfma_f32_16x16x32_bf16 v[4:7], v[158:161], v[198:201], 0
	v_mfma_f32_16x16x32_bf16 v[0:3], v[166:169], v[198:201], 0
	v_mfma_f32_16x16x32_bf16 v[44:47], v[162:165], v[178:181], v[44:47]
	v_mfma_f32_16x16x32_bf16 v[40:43], v[170:173], v[178:181], v[40:43]
	v_mfma_f32_16x16x32_bf16 v[28:31], v[162:165], v[186:189], v[28:31]
	v_mfma_f32_16x16x32_bf16 v[24:27], v[170:173], v[186:189], v[24:27]
	v_mfma_f32_16x16x32_bf16 v[12:15], v[162:165], v[194:197], v[12:15]
	v_mfma_f32_16x16x32_bf16 v[8:11], v[170:173], v[194:197], v[8:11]
	v_mfma_f32_16x16x32_bf16 v[4:7], v[162:165], v[202:205], v[4:7]
	v_mfma_f32_16x16x32_bf16 v[0:3], v[170:173], v[202:205], v[0:3]
	s_setprio 0
	s_barrier
	s_add_i32 s28, 0, 0x18000
	s_add_i32 s29, 0, 0x1c000
	v_add_u32_e32 v154, s28, v139
	v_add_u32_e32 v170, s29, v139
	ds_read_b128 v[142:145], v154
	ds_read_b128 v[146:149], v154 offset:1024
	ds_read_b128 v[150:153], v154 offset:2048
	ds_read_b128 v[154:157], v154 offset:3072
	ds_read_b128 v[158:161], v170
	ds_read_b128 v[162:165], v170 offset:1024
	ds_read_b128 v[166:169], v170 offset:2048
	ds_read_b128 v[170:173], v170 offset:3072
	s_add_u32 s46, s46, 0x40000
	s_addc_u32 s47, s47, 0
	s_mov_b32 m0, s26
	v_lshl_add_u64 v[224:225], s[46:47], 0, v[132:133]
	ds_read_b128 v[174:177], v141 offset:32768
	ds_read_b128 v[178:181], v141 offset:33792
	ds_read_b128 v[182:185], v141 offset:34816
	ds_read_b128 v[186:189], v141 offset:35840
	ds_read_b128 v[190:193], v141 offset:36864
	ds_read_b128 v[194:197], v141 offset:37888
	ds_read_b128 v[198:201], v141 offset:38912
	ds_read_b128 v[202:205], v141 offset:39936
	global_load_lds_dwordx4 v[224:225], off
	v_lshl_add_u64 v[224:225], s[46:47], 0, v[130:131]
	s_mov_b32 m0, s34
	s_nop 0
	global_load_lds_dwordx4 v[224:225], off
	s_waitcnt vmcnt(8)
	s_waitcnt lgkmcnt(0)
	s_barrier
	s_setprio 1
	s_waitcnt lgkmcnt(0)
	v_mfma_f32_16x16x32_bf16 v[124:127], v[142:145], v[174:177], v[124:127]
	v_mfma_f32_16x16x32_bf16 v[120:123], v[150:153], v[174:177], v[120:123]
	v_mfma_f32_16x16x32_bf16 v[116:119], v[142:145], v[182:185], v[116:119]
	v_mfma_f32_16x16x32_bf16 v[112:115], v[150:153], v[182:185], v[112:115]
	v_mfma_f32_16x16x32_bf16 v[100:103], v[142:145], v[190:193], v[100:103]
	v_mfma_f32_16x16x32_bf16 v[96:99], v[150:153], v[190:193], v[96:99]
	v_mfma_f32_16x16x32_bf16 v[84:87], v[142:145], v[198:201], v[84:87]
	v_mfma_f32_16x16x32_bf16 v[80:83], v[150:153], v[198:201], v[80:83]
	v_mfma_f32_16x16x32_bf16 v[124:127], v[146:149], v[178:181], v[124:127]
	v_mfma_f32_16x16x32_bf16 v[120:123], v[154:157], v[178:181], v[120:123]
	v_mfma_f32_16x16x32_bf16 v[116:119], v[146:149], v[186:189], v[116:119]
	v_mfma_f32_16x16x32_bf16 v[112:115], v[154:157], v[186:189], v[112:115]
	v_mfma_f32_16x16x32_bf16 v[100:103], v[146:149], v[194:197], v[100:103]
	v_mfma_f32_16x16x32_bf16 v[96:99], v[154:157], v[194:197], v[96:99]
	v_mfma_f32_16x16x32_bf16 v[84:87], v[146:149], v[202:205], v[84:87]
	v_mfma_f32_16x16x32_bf16 v[80:83], v[154:157], v[202:205], v[80:83]
	s_setprio 0
	s_setprio 1
	v_mfma_f32_16x16x32_bf16 v[108:111], v[158:161], v[174:177], v[108:111]
	v_mfma_f32_16x16x32_bf16 v[104:107], v[166:169], v[174:177], v[104:107]
	v_mfma_f32_16x16x32_bf16 v[92:95], v[158:161], v[182:185], v[92:95]
	v_mfma_f32_16x16x32_bf16 v[88:91], v[166:169], v[182:185], v[88:91]
	v_mfma_f32_16x16x32_bf16 v[76:79], v[158:161], v[190:193], v[76:79]
	v_mfma_f32_16x16x32_bf16 v[72:75], v[166:169], v[190:193], v[72:75]
	v_mfma_f32_16x16x32_bf16 v[68:71], v[158:161], v[198:201], v[68:71]
	v_mfma_f32_16x16x32_bf16 v[64:67], v[166:169], v[198:201], v[64:67]
	v_mfma_f32_16x16x32_bf16 v[108:111], v[162:165], v[178:181], v[108:111]
	v_mfma_f32_16x16x32_bf16 v[104:107], v[170:173], v[178:181], v[104:107]
	v_mfma_f32_16x16x32_bf16 v[92:95], v[162:165], v[186:189], v[92:95]
	v_mfma_f32_16x16x32_bf16 v[88:91], v[170:173], v[186:189], v[88:91]
	v_mfma_f32_16x16x32_bf16 v[76:79], v[162:165], v[194:197], v[76:79]
	v_mfma_f32_16x16x32_bf16 v[72:75], v[170:173], v[194:197], v[72:75]
	v_mfma_f32_16x16x32_bf16 v[68:71], v[162:165], v[202:205], v[68:71]
	v_mfma_f32_16x16x32_bf16 v[64:67], v[170:173], v[202:205], v[64:67]
	s_setprio 0
	s_barrier
; #define PG8_STAGE(bufoff, gbase, voff) do { _Pragma("unroll") for (int _i = 0; _i < 2; ++_i) \
;         __builtin_amdgcn_global_load_lds((const unsigned*)((const char*)(gbase) + (voff)[_i]), (PG8_LAS unsigned*)(lds + (bufoff) + ldsw + _i * 8192), 16, 0, 0); } while (0)
; #define PG8_LDA(dst, b, h) do { _Pragma("unroll") for (int m = 0; m < 4; ++m) _Pragma("unroll") for (int k = 0; k < 2; ++k) dst[m][k] = *(const PG8_LAS bf16x8*)(lds + PG8_SA(b, h) + aoff + m * 2048 + k * 1024); } while (0)
; #define PG8_MMA(ai, bj, At, Bt) do { __builtin_amdgcn_s_setprio(1); _Pragma("unroll") for (int m = 0; m < 4; ++m) _Pragma("unroll") for (int n = 0; n < 2; ++n) _Pragma("unroll") for (int k = 0; k < 2; ++k) \
;         acc[ai][bj][m][n] = __builtin_amdgcn_mfma_f32_16x16x32_bf16(Bt[n][k], At[m][k], acc[ai][bj][m][n], 0, 0, 0); __builtin_amdgcn_s_setprio(0); } while (0)
; #define PG8_WAIT_V(n) asm volatile("s_waitcnt vmcnt(" #n ")" ::: "memory")
; #define PG8_WAIT_L(n) asm volatile("s_waitcnt lgkmcnt(" #n ")" ::: "memory")
; #define PG8_BAR __builtin_amdgcn_s_barrier()
; #define PG8_SCHED __builtin_amdgcn_sched_barrier(0)
; template <class Epi, class Sched, bool ALIGN_EPI = false, bool SP2 = false>
; __device__ __forceinline__ void gemm_phase(PG8_LAS unsigned char* lds, const Gemm g, const Sched& S, const Epi& E) {
;     ...
;             PG8_LDA(At, 1, 1); PG8_STAGE(PG8_SB(1, 0), b3, voffB); PG8_STAGE(PG8_SB(1, 1), b3 + hstepB, voffB); PG8_STAGE(PG8_SA(1, 0), a3, voffA);
;             PG8_WAIT_V(8); PG8_WAIT_L(0); PG8_BAR; PG8_MMA(1, 0, At, B0); PG8_MMA(1, 1, At, B1); PG8_BAR; PG8_SCHED;
	s_add_i32 s28, s28, s18
	v_lshl_add_u64 v[206:207], v[206:207], 0, s[10:11]
	s_mov_b32 m0, s28
	ds_read_b128 v[174:177], v141 offset:49152
	ds_read_b128 v[178:181], v141 offset:50176
	ds_read_b128 v[182:185], v141 offset:51200
	ds_read_b128 v[186:189], v141 offset:52224
	ds_read_b128 v[190:193], v141 offset:53248
	ds_read_b128 v[194:197], v141 offset:54272
	ds_read_b128 v[198:201], v141 offset:55296
	ds_read_b128 v[202:205], v141 offset:56320
	global_load_lds_dwordx4 v[206:207], off
	s_add_i32 m0, s28, 0x2000
	s_add_u32 s22, s22, 0x40080
	v_lshl_add_u64 v[206:207], v[210:211], 0, s[10:11]
	s_addc_u32 s23, s23, 0
	s_add_i32 s28, s29, s18
	global_load_lds_dwordx4 v[206:207], off
	v_lshl_add_u64 v[206:207], s[22:23], 0, v[208:209]
	s_mov_b32 m0, s28
	s_nop 0
	global_load_lds_dwordx4 v[206:207], off
	v_lshl_add_u64 v[206:207], s[22:23], 0, v[128:129]
	s_add_i32 m0, s28, 0x2000
	s_nop 0
	global_load_lds_dwordx4 v[206:207], off
	v_lshl_add_u64 v[206:207], v[212:213], 0, s[10:11]
	s_mov_b32 m0, s35
	s_nop 0
	global_load_lds_dwordx4 v[206:207], off
	v_lshl_add_u64 v[206:207], v[222:223], 0, s[10:11]
	s_mov_b32 m0, s39
	s_nop 0
	global_load_lds_dwordx4 v[206:207], off
	s_waitcnt vmcnt(8)
	s_waitcnt lgkmcnt(0)
	s_barrier
	s_setprio 1
	s_waitcnt lgkmcnt(0)
	v_mfma_f32_16x16x32_bf16 v[60:63], v[142:145], v[174:177], v[60:63]
	v_mfma_f32_16x16x32_bf16 v[56:59], v[150:153], v[174:177], v[56:59]
	v_mfma_f32_16x16x32_bf16 v[52:55], v[142:145], v[182:185], v[52:55]
	v_mfma_f32_16x16x32_bf16 v[48:51], v[150:153], v[182:185], v[48:51]
	v_mfma_f32_16x16x32_bf16 v[36:39], v[142:145], v[190:193], v[36:39]
	v_mfma_f32_16x16x32_bf16 v[32:35], v[150:153], v[190:193], v[32:35]
	v_mfma_f32_16x16x32_bf16 v[20:23], v[142:145], v[198:201], v[20:23]
	v_mfma_f32_16x16x32_bf16 v[16:19], v[150:153], v[198:201], v[16:19]
	v_mfma_f32_16x16x32_bf16 v[60:63], v[146:149], v[178:181], v[60:63]
	v_mfma_f32_16x16x32_bf16 v[56:59], v[154:157], v[178:181], v[56:59]
	v_mfma_f32_16x16x32_bf16 v[52:55], v[146:149], v[186:189], v[52:55]
	v_mfma_f32_16x16x32_bf16 v[48:51], v[154:157], v[186:189], v[48:51]
	v_mfma_f32_16x16x32_bf16 v[36:39], v[146:149], v[194:197], v[36:39]
	v_mfma_f32_16x16x32_bf16 v[32:35], v[154:157], v[194:197], v[32:35]
	v_mfma_f32_16x16x32_bf16 v[20:23], v[146:149], v[202:205], v[20:23]
	v_mfma_f32_16x16x32_bf16 v[16:19], v[154:157], v[202:205], v[16:19]
	s_setprio 0
	s_setprio 1
	v_mfma_f32_16x16x32_bf16 v[44:47], v[158:161], v[174:177], v[44:47]
	v_mfma_f32_16x16x32_bf16 v[40:43], v[166:169], v[174:177], v[40:43]
	v_mfma_f32_16x16x32_bf16 v[28:31], v[158:161], v[182:185], v[28:31]
	v_mfma_f32_16x16x32_bf16 v[24:27], v[166:169], v[182:185], v[24:27]
	v_mfma_f32_16x16x32_bf16 v[12:15], v[158:161], v[190:193], v[12:15]
	v_mfma_f32_16x16x32_bf16 v[8:11], v[166:169], v[190:193], v[8:11]
	v_mfma_f32_16x16x32_bf16 v[4:7], v[158:161], v[198:201], v[4:7]
	v_mfma_f32_16x16x32_bf16 v[0:3], v[166:169], v[198:201], v[0:3]
	v_mfma_f32_16x16x32_bf16 v[44:47], v[162:165], v[178:181], v[44:47]
	v_mfma_f32_16x16x32_bf16 v[40:43], v[170:173], v[178:181], v[40:43]
	v_mfma_f32_16x16x32_bf16 v[28:31], v[162:165], v[186:189], v[28:31]
	v_mfma_f32_16x16x32_bf16 v[24:27], v[170:173], v[186:189], v[24:27]
	v_mfma_f32_16x16x32_bf16 v[12:15], v[162:165], v[194:197], v[12:15]
	v_mfma_f32_16x16x32_bf16 v[8:11], v[170:173], v[194:197], v[8:11]
	v_mfma_f32_16x16x32_bf16 v[4:7], v[162:165], v[202:205], v[4:7]
	v_mfma_f32_16x16x32_bf16 v[0:3], v[170:173], v[202:205], v[0:3]
	s_setprio 0
	s_barrier
	s_add_i32 s51, s51, 2
	s_add_u32 s44, s44, 0x100
	s_addc_u32 s45, s45, 0
	s_add_u32 s49, s49, 0x100
	s_addc_u32 s50, s50, 0
	s_cmp_gt_u32 s51, 13
	s_cbranch_scc0 .LBB0_354
	s_branch .Lpeel_done_354

; #define PG8_STAGE(bufoff, gbase, voff) do { _Pragma("unroll") for (int _i = 0; _i < 2; ++_i) \
;         __builtin_amdgcn_global_load_lds((const unsigned*)((const char*)(gbase) + (voff)[_i]), (PG8_LAS unsigned*)(lds + (bufoff) + ldsw + _i * 8192), 16, 0, 0); } while (0)
; #define PG8_LDA(dst, b, h) do { _Pragma("unroll") for (int m = 0; m < 4; ++m) _Pragma("unroll") for (int k = 0; k < 2; ++k) dst[m][k] = *(const PG8_LAS bf16x8*)(lds + PG8_SA(b, h) + aoff + m * 2048 + k * 1024); } while (0)
; #define PG8_LDB(dst, b, h) do { _Pragma("unroll") for (int n = 0; n < 2; ++n) _Pragma("unroll") for (int k = 0; k < 2; ++k) dst[n][k] = *(const PG8_LAS bf16x8*)(lds + PG8_SB(b, h) + boff + n * 2048 + k * 1024); } while (0)
; #define PG8_MMA(ai, bj, At, Bt) do { __builtin_amdgcn_s_setprio(1); _Pragma("unroll") for (int m = 0; m < 4; ++m) _Pragma("unroll") for (int n = 0; n < 2; ++n) _Pragma("unroll") for (int k = 0; k < 2; ++k) \
;         acc[ai][bj][m][n] = __builtin_amdgcn_mfma_f32_16x16x32_bf16(Bt[n][k], At[m][k], acc[ai][bj][m][n], 0, 0, 0); __builtin_amdgcn_s_setprio(0); } while (0)
; #define PG8_WAIT_V(n) asm volatile("s_waitcnt vmcnt(" #n ")" ::: "memory")
; #define PG8_BAR __builtin_amdgcn_s_barrier()
; template <class Epi, class Sched, bool ALIGN_EPI = false, bool SP2 = false>
; __device__ __forceinline__ void gemm_phase(PG8_LAS unsigned char* lds, const Gemm g, const Sched& S, const Epi& E) {
;     ...
;         for (int t = 0; t < nt; t += 2) {
;             const bool last = (t == nt - 2);
;             const char* a1 = cA + (size_t)(t + 1) * kstep;
;             const char* a2 = last ? nA : cA + (size_t)(t + 2) * kstep; const char* b2 = last ? nB : cB + (size_t)(t + 2) * kstep;
;             const char* a3 = a2 + kstep; const char* b3 = b2 + kstep;
;             if (last && has_next) S.a_ready(nxt);
;             if constexpr (SP2) {
;             PG8_LDB(B0, 0, 0); PG8_LDB(B1, 0, 1); PG8_SCHED; PG8_LDA(At, 0, 0); PG8_STAGE(PG8_SA(1, 1), a1 + hstepA, voffA);
;             PG8_WAIT_V(8); PG8_WAIT_L(0); PG8_BAR; PG8_MMA(0, 0, At, B0); PG8_MMA(0, 1, At, B1); PG8_BAR; PG8_SCHED;
;             PG8_LDA(At, 0, 1); PG8_STAGE(PG8_SB(0, 0), b2, voffB); PG8_STAGE(PG8_SB(0, 1), b2 + hstepB, voffB); PG8_STAGE(PG8_SA(0, 0), a2, voffA);
;             PG8_WAIT_V(8); PG8_WAIT_L(0); PG8_BAR; PG8_MMA(1, 0, At, B0); PG8_MMA(1, 1, At, B1); PG8_BAR; PG8_SCHED;
.LBB0_606:
	s_ashr_i32 s43, s42, 31
	s_lshl_b64 s[14:15], s[42:43], 19
	v_readlane_b32 s22, v252, 2
	v_readlane_b32 s23, v252, 3
	s_add_u32 s44, s22, s14
	s_addc_u32 s45, s23, s15
	s_and_b64 s[14:15], s[40:41], exec
	s_cselect_b32 s14, s45, s1
	s_cselect_b32 s15, s44, s0
	s_ashr_i32 s9, s8, 31
	s_lshl_b64 s[22:23], s[8:9], 19
	v_readlane_b32 s9, v254, 3
	s_add_u32 s46, s9, s22
	v_readlane_b32 s9, v254, 4
	s_addc_u32 s47, s9, s23
	s_and_b64 s[22:23], s[40:41], exec
	s_cselect_b32 s9, s47, s25
	s_cselect_b32 s38, s46, s24
	s_add_u32 s0, s0, 0x40080
	s_addc_u32 s1, s1, 0
	s_add_u32 s43, s24, 0x100
	s_addc_u32 s50, s25, 0
	s_mov_b32 s51, -2
	s_add_u32 s22, s0, 0xfffc0080
	s_addc_u32 s23, s1, -1
	s_add_i32 s28, 0, 0x10000
	s_cmp_eq_u32 s51, 12
	s_cselect_b32 s25, s14, s23
	s_cselect_b32 s24, s15, s22
	s_cselect_b32 s23, s9, s50
	s_cselect_b32 s22, s38, s43
	s_add_i32 s29, 0, 0x14000
	v_add_u32_e32 v154, s28, v143
	v_add_u32_e32 v170, s29, v143
	ds_read_b128 v[138:141], v154
	ds_read_b128 v[146:149], v154 offset:1024
	ds_read_b128 v[150:153], v154 offset:2048
	ds_read_b128 v[154:157], v154 offset:3072
	ds_read_b128 v[158:161], v170
	ds_read_b128 v[162:165], v170 offset:1024
	ds_read_b128 v[166:169], v170 offset:2048
	ds_read_b128 v[170:173], v170 offset:3072
	v_lshl_add_u64 v[206:207], s[0:1], 0, v[134:135]
	s_add_i32 m0, s21, 0xc000
	ds_read_b128 v[174:177], v145
	ds_read_b128 v[178:181], v145 offset:1024
	ds_read_b128 v[182:185], v145 offset:2048
	ds_read_b128 v[186:189], v145 offset:3072
	ds_read_b128 v[190:193], v145 offset:4096
	ds_read_b128 v[194:197], v145 offset:5120
	ds_read_b128 v[198:201], v145 offset:6144
	ds_read_b128 v[202:205], v145 offset:7168
	global_load_lds_dwordx4 v[206:207], off
	v_lshl_add_u64 v[206:207], s[0:1], 0, v[136:137]
	s_add_i32 m0, s21, 0xe000
	s_nop 0
	global_load_lds_dwordx4 v[206:207], off
	s_waitcnt vmcnt(8)
	s_waitcnt lgkmcnt(0)
	s_barrier
	s_setprio 1
	s_waitcnt lgkmcnt(0)
	v_mfma_f32_16x16x32_bf16 v[124:127], v[138:141], v[174:177], 0
	v_mfma_f32_16x16x32_bf16 v[120:123], v[150:153], v[174:177], 0
	v_mfma_f32_16x16x32_bf16 v[108:111], v[138:141], v[182:185], 0
	v_mfma_f32_16x16x32_bf16 v[104:107], v[150:153], v[182:185], 0
	v_mfma_f32_16x16x32_bf16 v[92:95], v[138:141], v[190:193], 0
	v_mfma_f32_16x16x32_bf16 v[88:91], v[150:153], v[190:193], 0
	v_mfma_f32_16x16x32_bf16 v[76:79], v[138:141], v[198:201], 0
	v_mfma_f32_16x16x32_bf16 v[72:75], v[150:153], v[198:201], 0
	v_mfma_f32_16x16x32_bf16 v[124:127], v[146:149], v[178:181], v[124:127]
	v_mfma_f32_16x16x32_bf16 v[120:123], v[154:157], v[178:181], v[120:123]
	v_mfma_f32_16x16x32_bf16 v[108:111], v[146:149], v[186:189], v[108:111]
	v_mfma_f32_16x16x32_bf16 v[104:107], v[154:157], v[186:189], v[104:107]
	v_mfma_f32_16x16x32_bf16 v[92:95], v[146:149], v[194:197], v[92:95]
	v_mfma_f32_16x16x32_bf16 v[88:91], v[154:157], v[194:197], v[88:91]
	v_mfma_f32_16x16x32_bf16 v[76:79], v[146:149], v[202:205], v[76:79]
	v_mfma_f32_16x16x32_bf16 v[72:75], v[154:157], v[202:205], v[72:75]
	s_setprio 0
	s_setprio 1
	v_mfma_f32_16x16x32_bf16 v[116:119], v[158:161], v[174:177], 0
	v_mfma_f32_16x16x32_bf16 v[112:115], v[166:169], v[174:177], 0
	v_mfma_f32_16x16x32_bf16 v[100:103], v[158:161], v[182:185], 0
	v_mfma_f32_16x16x32_bf16 v[96:99], v[166:169], v[182:185], 0
	v_mfma_f32_16x16x32_bf16 v[84:87], v[158:161], v[190:193], 0
	v_mfma_f32_16x16x32_bf16 v[80:83], v[166:169], v[190:193], 0
	v_mfma_f32_16x16x32_bf16 v[68:71], v[158:161], v[198:201], 0
	v_mfma_f32_16x16x32_bf16 v[64:67], v[166:169], v[198:201], 0
	v_mfma_f32_16x16x32_bf16 v[116:119], v[162:165], v[178:181], v[116:119]
	v_mfma_f32_16x16x32_bf16 v[112:115], v[170:173], v[178:181], v[112:115]
	v_mfma_f32_16x16x32_bf16 v[100:103], v[162:165], v[186:189], v[100:103]
	v_mfma_f32_16x16x32_bf16 v[96:99], v[170:173], v[186:189], v[96:99]
	v_mfma_f32_16x16x32_bf16 v[84:87], v[162:165], v[194:197], v[84:87]
	v_mfma_f32_16x16x32_bf16 v[80:83], v[170:173], v[194:197], v[80:83]
	v_mfma_f32_16x16x32_bf16 v[68:71], v[162:165], v[202:205], v[68:71]
	v_mfma_f32_16x16x32_bf16 v[64:67], v[170:173], v[202:205], v[64:67]
	s_setprio 0
	s_barrier
	s_add_i32 s28, s28, s26
	v_lshl_add_u64 v[206:207], s[22:23], 0, v[208:209]
	s_mov_b32 m0, s28
	ds_read_b128 v[174:177], v145 offset:16384
	ds_read_b128 v[178:181], v145 offset:17408
	ds_read_b128 v[182:185], v145 offset:18432
	ds_read_b128 v[186:189], v145 offset:19456
	ds_read_b128 v[190:193], v145 offset:20480
	ds_read_b128 v[194:197], v145 offset:21504
	ds_read_b128 v[198:201], v145 offset:22528
	ds_read_b128 v[202:205], v145 offset:23552
	global_load_lds_dwordx4 v[206:207], off
	s_add_i32 m0, s28, 0x2000
	s_add_u32 s52, s22, 0x40000
	v_lshl_add_u64 v[210:211], s[22:23], 0, v[128:129]
	s_addc_u32 s53, s23, 0
	s_add_i32 s28, s29, s26
	global_load_lds_dwordx4 v[210:211], off
	v_lshl_add_u64 v[212:213], s[52:53], 0, v[208:209]
	s_mov_b32 m0, s28
	v_lshl_add_u64 v[222:223], s[24:25], 0, v[130:131]
	global_load_lds_dwordx4 v[212:213], off
	v_lshl_add_u64 v[212:213], s[52:53], 0, v[128:129]
	s_add_i32 m0, s28, 0x2000
	s_nop 0
	global_load_lds_dwordx4 v[212:213], off
	v_lshl_add_u64 v[212:213], s[24:25], 0, v[132:133]
	s_mov_b32 m0, s21
	s_nop 0
	global_load_lds_dwordx4 v[212:213], off
	s_mov_b32 m0, s18
	s_nop 0
	global_load_lds_dwordx4 v[222:223], off
	s_waitcnt vmcnt(8)
	s_waitcnt lgkmcnt(0)
	s_barrier
; #define PG8_STAGE(bufoff, gbase, voff) do { _Pragma("unroll") for (int _i = 0; _i < 2; ++_i) \
;         __builtin_amdgcn_global_load_lds((const unsigned*)((const char*)(gbase) + (voff)[_i]), (PG8_LAS unsigned*)(lds + (bufoff) + ldsw + _i * 8192), 16, 0, 0); } while (0)
; #define PG8_LDA(dst, b, h) do { _Pragma("unroll") for (int m = 0; m < 4; ++m) _Pragma("unroll") for (int k = 0; k < 2; ++k) dst[m][k] = *(const PG8_LAS bf16x8*)(lds + PG8_SA(b, h) + aoff + m * 2048 + k * 1024); } while (0)
; #define PG8_LDB(dst, b, h) do { _Pragma("unroll") for (int n = 0; n < 2; ++n) _Pragma("unroll") for (int k = 0; k < 2; ++k) dst[n][k] = *(const PG8_LAS bf16x8*)(lds + PG8_SB(b, h) + boff + n * 2048 + k * 1024); } while (0)
; #define PG8_MMA(ai, bj, At, Bt) do { __builtin_amdgcn_s_setprio(1); _Pragma("unroll") for (int m = 0; m < 4; ++m) _Pragma("unroll") for (int n = 0; n < 2; ++n) _Pragma("unroll") for (int k = 0; k < 2; ++k) \
;         acc[ai][bj][m][n] = __builtin_amdgcn_mfma_f32_16x16x32_bf16(Bt[n][k], At[m][k], acc[ai][bj][m][n], 0, 0, 0); __builtin_amdgcn_s_setprio(0); } while (0)
; #define PG8_WAIT_V(n) asm volatile("s_waitcnt vmcnt(" #n ")" ::: "memory")
; #define PG8_WAIT_L(n) asm volatile("s_waitcnt lgkmcnt(" #n ")" ::: "memory")
; #define PG8_BAR __builtin_amdgcn_s_barrier()
; #define PG8_SCHED __builtin_amdgcn_sched_barrier(0)
; template <class Epi, class Sched, bool ALIGN_EPI = false, bool SP2 = false>
; __device__ __forceinline__ void gemm_phase(PG8_LAS unsigned char* lds, const Gemm g, const Sched& S, const Epi& E) {
;     ...
;             PG8_WAIT_V(8); PG8_WAIT_L(0); PG8_BAR; PG8_MMA(1, 0, At, B0); PG8_MMA(1, 1, At, B1); PG8_BAR; PG8_SCHED;
;             PG8_LDB(B0, 1, 0); PG8_LDB(B1, 1, 1); PG8_SCHED; PG8_LDA(At, 1, 0); PG8_STAGE(PG8_SA(0, 1), a2 + hstepA, voffA);
;             PG8_WAIT_V(8); PG8_WAIT_L(0); PG8_BAR; PG8_MMA(0, 0, At, B0); PG8_MMA(0, 1, At, B1); PG8_BAR; PG8_SCHED;
	s_setprio 1
	s_waitcnt lgkmcnt(0)
	v_mfma_f32_16x16x32_bf16 v[60:63], v[138:141], v[174:177], 0
	v_mfma_f32_16x16x32_bf16 v[56:59], v[150:153], v[174:177], 0
	v_mfma_f32_16x16x32_bf16 v[44:47], v[138:141], v[182:185], 0
	v_mfma_f32_16x16x32_bf16 v[40:43], v[150:153], v[182:185], 0
	v_mfma_f32_16x16x32_bf16 v[28:31], v[138:141], v[190:193], 0
	v_mfma_f32_16x16x32_bf16 v[24:27], v[150:153], v[190:193], 0
	v_mfma_f32_16x16x32_bf16 v[12:15], v[138:141], v[198:201], 0
	v_mfma_f32_16x16x32_bf16 v[8:11], v[150:153], v[198:201], 0
	v_mfma_f32_16x16x32_bf16 v[60:63], v[146:149], v[178:181], v[60:63]
	v_mfma_f32_16x16x32_bf16 v[56:59], v[154:157], v[178:181], v[56:59]
	v_mfma_f32_16x16x32_bf16 v[44:47], v[146:149], v[186:189], v[44:47]
	v_mfma_f32_16x16x32_bf16 v[40:43], v[154:157], v[186:189], v[40:43]
	v_mfma_f32_16x16x32_bf16 v[28:31], v[146:149], v[194:197], v[28:31]
	v_mfma_f32_16x16x32_bf16 v[24:27], v[154:157], v[194:197], v[24:27]
	v_mfma_f32_16x16x32_bf16 v[12:15], v[146:149], v[202:205], v[12:15]
	v_mfma_f32_16x16x32_bf16 v[8:11], v[154:157], v[202:205], v[8:11]
	s_setprio 0
	s_setprio 1
	v_mfma_f32_16x16x32_bf16 v[52:55], v[158:161], v[174:177], 0
	v_mfma_f32_16x16x32_bf16 v[48:51], v[166:169], v[174:177], 0
	v_mfma_f32_16x16x32_bf16 v[36:39], v[158:161], v[182:185], 0
	v_mfma_f32_16x16x32_bf16 v[32:35], v[166:169], v[182:185], 0
	v_mfma_f32_16x16x32_bf16 v[20:23], v[158:161], v[190:193], 0
	v_mfma_f32_16x16x32_bf16 v[16:19], v[166:169], v[190:193], 0
	v_mfma_f32_16x16x32_bf16 v[4:7], v[158:161], v[198:201], 0
	v_mfma_f32_16x16x32_bf16 v[0:3], v[166:169], v[198:201], 0
	v_mfma_f32_16x16x32_bf16 v[52:55], v[162:165], v[178:181], v[52:55]
	v_mfma_f32_16x16x32_bf16 v[48:51], v[170:173], v[178:181], v[48:51]
	v_mfma_f32_16x16x32_bf16 v[36:39], v[162:165], v[186:189], v[36:39]
	v_mfma_f32_16x16x32_bf16 v[32:35], v[170:173], v[186:189], v[32:35]
	v_mfma_f32_16x16x32_bf16 v[20:23], v[162:165], v[194:197], v[20:23]
	v_mfma_f32_16x16x32_bf16 v[16:19], v[170:173], v[194:197], v[16:19]
	v_mfma_f32_16x16x32_bf16 v[4:7], v[162:165], v[202:205], v[4:7]
	v_mfma_f32_16x16x32_bf16 v[0:3], v[170:173], v[202:205], v[0:3]
	s_setprio 0
	s_barrier
	s_add_i32 s28, 0, 0x18000
	s_add_i32 s29, 0, 0x1c000
	v_add_u32_e32 v154, s28, v143
	v_add_u32_e32 v170, s29, v143
	ds_read_b128 v[138:141], v154
	ds_read_b128 v[146:149], v154 offset:1024
	ds_read_b128 v[150:153], v154 offset:2048
	ds_read_b128 v[154:157], v154 offset:3072
	ds_read_b128 v[158:161], v170
	ds_read_b128 v[162:165], v170 offset:1024
	ds_read_b128 v[166:169], v170 offset:2048
	ds_read_b128 v[170:173], v170 offset:3072
	s_add_u32 s24, s24, 0x40000
	s_addc_u32 s25, s25, 0
	s_mov_b32 m0, s19
	v_lshl_add_u64 v[224:225], s[24:25], 0, v[132:133]
	ds_read_b128 v[174:177], v145 offset:32768
	ds_read_b128 v[178:181], v145 offset:33792
	ds_read_b128 v[182:185], v145 offset:34816
	ds_read_b128 v[186:189], v145 offset:35840
	ds_read_b128 v[190:193], v145 offset:36864
	ds_read_b128 v[194:197], v145 offset:37888
	ds_read_b128 v[198:201], v145 offset:38912
	ds_read_b128 v[202:205], v145 offset:39936
	global_load_lds_dwordx4 v[224:225], off
	v_lshl_add_u64 v[224:225], s[24:25], 0, v[130:131]
	s_mov_b32 m0, s34
	s_nop 0
	global_load_lds_dwordx4 v[224:225], off
	s_waitcnt vmcnt(8)
	s_waitcnt lgkmcnt(0)
	s_barrier
	s_setprio 1
	s_waitcnt lgkmcnt(0)
	v_mfma_f32_16x16x32_bf16 v[124:127], v[138:141], v[174:177], v[124:127]
	v_mfma_f32_16x16x32_bf16 v[120:123], v[150:153], v[174:177], v[120:123]
	v_mfma_f32_16x16x32_bf16 v[108:111], v[138:141], v[182:185], v[108:111]
	v_mfma_f32_16x16x32_bf16 v[104:107], v[150:153], v[182:185], v[104:107]
	v_mfma_f32_16x16x32_bf16 v[92:95], v[138:141], v[190:193], v[92:95]
	v_mfma_f32_16x16x32_bf16 v[88:91], v[150:153], v[190:193], v[88:91]
	v_mfma_f32_16x16x32_bf16 v[76:79], v[138:141], v[198:201], v[76:79]
	v_mfma_f32_16x16x32_bf16 v[72:75], v[150:153], v[198:201], v[72:75]
	v_mfma_f32_16x16x32_bf16 v[124:127], v[146:149], v[178:181], v[124:127]
	v_mfma_f32_16x16x32_bf16 v[120:123], v[154:157], v[178:181], v[120:123]
	v_mfma_f32_16x16x32_bf16 v[108:111], v[146:149], v[186:189], v[108:111]
	v_mfma_f32_16x16x32_bf16 v[104:107], v[154:157], v[186:189], v[104:107]
	v_mfma_f32_16x16x32_bf16 v[92:95], v[146:149], v[194:197], v[92:95]
	v_mfma_f32_16x16x32_bf16 v[88:91], v[154:157], v[194:197], v[88:91]
	v_mfma_f32_16x16x32_bf16 v[76:79], v[146:149], v[202:205], v[76:79]
	v_mfma_f32_16x16x32_bf16 v[72:75], v[154:157], v[202:205], v[72:75]
	s_setprio 0
	s_setprio 1
	v_mfma_f32_16x16x32_bf16 v[116:119], v[158:161], v[174:177], v[116:119]
	v_mfma_f32_16x16x32_bf16 v[112:115], v[166:169], v[174:177], v[112:115]
	v_mfma_f32_16x16x32_bf16 v[100:103], v[158:161], v[182:185], v[100:103]
	v_mfma_f32_16x16x32_bf16 v[96:99], v[166:169], v[182:185], v[96:99]
	v_mfma_f32_16x16x32_bf16 v[84:87], v[158:161], v[190:193], v[84:87]
	v_mfma_f32_16x16x32_bf16 v[80:83], v[166:169], v[190:193], v[80:83]
	v_mfma_f32_16x16x32_bf16 v[68:71], v[158:161], v[198:201], v[68:71]
	v_mfma_f32_16x16x32_bf16 v[64:67], v[166:169], v[198:201], v[64:67]
	v_mfma_f32_16x16x32_bf16 v[116:119], v[162:165], v[178:181], v[116:119]
	v_mfma_f32_16x16x32_bf16 v[112:115], v[170:173], v[178:181], v[112:115]
	v_mfma_f32_16x16x32_bf16 v[100:103], v[162:165], v[186:189], v[100:103]
	v_mfma_f32_16x16x32_bf16 v[96:99], v[170:173], v[186:189], v[96:99]
	v_mfma_f32_16x16x32_bf16 v[84:87], v[162:165], v[194:197], v[84:87]
	v_mfma_f32_16x16x32_bf16 v[80:83], v[170:173], v[194:197], v[80:83]
	v_mfma_f32_16x16x32_bf16 v[68:71], v[162:165], v[202:205], v[68:71]
	v_mfma_f32_16x16x32_bf16 v[64:67], v[170:173], v[202:205], v[64:67]
	s_setprio 0
	s_barrier
; #define PG8_STAGE(bufoff, gbase, voff) do { _Pragma("unroll") for (int _i = 0; _i < 2; ++_i) \
;         __builtin_amdgcn_global_load_lds((const unsigned*)((const char*)(gbase) + (voff)[_i]), (PG8_LAS unsigned*)(lds + (bufoff) + ldsw + _i * 8192), 16, 0, 0); } while (0)
; #define PG8_LDA(dst, b, h) do { _Pragma("unroll") for (int m = 0; m < 4; ++m) _Pragma("unroll") for (int k = 0; k < 2; ++k) dst[m][k] = *(const PG8_LAS bf16x8*)(lds + PG8_SA(b, h) + aoff + m * 2048 + k * 1024); } while (0)
; #define PG8_MMA(ai, bj, At, Bt) do { __builtin_amdgcn_s_setprio(1); _Pragma("unroll") for (int m = 0; m < 4; ++m) _Pragma("unroll") for (int n = 0; n < 2; ++n) _Pragma("unroll") for (int k = 0; k < 2; ++k) \
;         acc[ai][bj][m][n] = __builtin_amdgcn_mfma_f32_16x16x32_bf16(Bt[n][k], At[m][k], acc[ai][bj][m][n], 0, 0, 0); __builtin_amdgcn_s_setprio(0); } while (0)
; #define PG8_WAIT_V(n) asm volatile("s_waitcnt vmcnt(" #n ")" ::: "memory")
; #define PG8_WAIT_L(n) asm volatile("s_waitcnt lgkmcnt(" #n ")" ::: "memory")
; #define PG8_BAR __builtin_amdgcn_s_barrier()
; #define PG8_SCHED __builtin_amdgcn_sched_barrier(0)
; template <class Epi, class Sched, bool ALIGN_EPI = false, bool SP2 = false>
; __device__ __forceinline__ void gemm_phase(PG8_LAS unsigned char* lds, const Gemm g, const Sched& S, const Epi& E) {
;     ...
;             PG8_LDA(At, 1, 1); PG8_STAGE(PG8_SB(1, 0), b3, voffB); PG8_STAGE(PG8_SB(1, 1), b3 + hstepB, voffB); PG8_STAGE(PG8_SA(1, 0), a3, voffA);
;             PG8_WAIT_V(8); PG8_WAIT_L(0); PG8_BAR; PG8_MMA(1, 0, At, B0); PG8_MMA(1, 1, At, B1); PG8_BAR; PG8_SCHED;
	s_add_i32 s24, s28, s26
	v_lshl_add_u64 v[206:207], v[206:207], 0, s[10:11]
	s_mov_b32 m0, s24
	ds_read_b128 v[174:177], v145 offset:49152
	ds_read_b128 v[178:181], v145 offset:50176
	ds_read_b128 v[182:185], v145 offset:51200
	ds_read_b128 v[186:189], v145 offset:52224
	ds_read_b128 v[190:193], v145 offset:53248
	ds_read_b128 v[194:197], v145 offset:54272
	ds_read_b128 v[198:201], v145 offset:55296
	ds_read_b128 v[202:205], v145 offset:56320
	global_load_lds_dwordx4 v[206:207], off
	s_add_i32 m0, s24, 0x2000
	s_add_u32 s22, s22, 0x40080
	v_lshl_add_u64 v[206:207], v[210:211], 0, s[10:11]
	s_addc_u32 s23, s23, 0
	s_add_i32 s24, s29, s26
	global_load_lds_dwordx4 v[206:207], off
	v_lshl_add_u64 v[206:207], s[22:23], 0, v[208:209]
	s_mov_b32 m0, s24
	s_nop 0
	global_load_lds_dwordx4 v[206:207], off
	v_lshl_add_u64 v[206:207], s[22:23], 0, v[128:129]
	s_add_i32 m0, s24, 0x2000
	s_nop 0
	global_load_lds_dwordx4 v[206:207], off
	v_lshl_add_u64 v[206:207], v[212:213], 0, s[10:11]
	s_mov_b32 m0, s35
	s_nop 0
	global_load_lds_dwordx4 v[206:207], off
	v_lshl_add_u64 v[206:207], v[222:223], 0, s[10:11]
	s_mov_b32 m0, s39
	s_nop 0
	global_load_lds_dwordx4 v[206:207], off
	s_waitcnt vmcnt(8)
	s_waitcnt lgkmcnt(0)
	s_barrier
	s_setprio 1
	s_waitcnt lgkmcnt(0)
	v_mfma_f32_16x16x32_bf16 v[60:63], v[138:141], v[174:177], v[60:63]
	v_mfma_f32_16x16x32_bf16 v[56:59], v[150:153], v[174:177], v[56:59]
	v_mfma_f32_16x16x32_bf16 v[44:47], v[138:141], v[182:185], v[44:47]
	v_mfma_f32_16x16x32_bf16 v[40:43], v[150:153], v[182:185], v[40:43]
	v_mfma_f32_16x16x32_bf16 v[28:31], v[138:141], v[190:193], v[28:31]
	v_mfma_f32_16x16x32_bf16 v[24:27], v[150:153], v[190:193], v[24:27]
	v_mfma_f32_16x16x32_bf16 v[12:15], v[138:141], v[198:201], v[12:15]
	v_mfma_f32_16x16x32_bf16 v[8:11], v[150:153], v[198:201], v[8:11]
	v_mfma_f32_16x16x32_bf16 v[60:63], v[146:149], v[178:181], v[60:63]
	v_mfma_f32_16x16x32_bf16 v[56:59], v[154:157], v[178:181], v[56:59]
	v_mfma_f32_16x16x32_bf16 v[44:47], v[146:149], v[186:189], v[44:47]
	v_mfma_f32_16x16x32_bf16 v[40:43], v[154:157], v[186:189], v[40:43]
	v_mfma_f32_16x16x32_bf16 v[28:31], v[146:149], v[194:197], v[28:31]
	v_mfma_f32_16x16x32_bf16 v[24:27], v[154:157], v[194:197], v[24:27]
	v_mfma_f32_16x16x32_bf16 v[12:15], v[146:149], v[202:205], v[12:15]
	v_mfma_f32_16x16x32_bf16 v[8:11], v[154:157], v[202:205], v[8:11]
	s_setprio 0
	s_setprio 1
	v_mfma_f32_16x16x32_bf16 v[52:55], v[158:161], v[174:177], v[52:55]
	v_mfma_f32_16x16x32_bf16 v[48:51], v[166:169], v[174:177], v[48:51]
	v_mfma_f32_16x16x32_bf16 v[36:39], v[158:161], v[182:185], v[36:39]
	v_mfma_f32_16x16x32_bf16 v[32:35], v[166:169], v[182:185], v[32:35]
	v_mfma_f32_16x16x32_bf16 v[20:23], v[158:161], v[190:193], v[20:23]
	v_mfma_f32_16x16x32_bf16 v[16:19], v[166:169], v[190:193], v[16:19]
	v_mfma_f32_16x16x32_bf16 v[4:7], v[158:161], v[198:201], v[4:7]
	v_mfma_f32_16x16x32_bf16 v[0:3], v[166:169], v[198:201], v[0:3]
	v_mfma_f32_16x16x32_bf16 v[52:55], v[162:165], v[178:181], v[52:55]
	v_mfma_f32_16x16x32_bf16 v[48:51], v[170:173], v[178:181], v[48:51]
	v_mfma_f32_16x16x32_bf16 v[36:39], v[162:165], v[186:189], v[36:39]
	v_mfma_f32_16x16x32_bf16 v[32:35], v[170:173], v[186:189], v[32:35]
	v_mfma_f32_16x16x32_bf16 v[20:23], v[162:165], v[194:197], v[20:23]
	v_mfma_f32_16x16x32_bf16 v[16:19], v[170:173], v[194:197], v[16:19]
	v_mfma_f32_16x16x32_bf16 v[4:7], v[162:165], v[202:205], v[4:7]
	v_mfma_f32_16x16x32_bf16 v[0:3], v[170:173], v[202:205], v[0:3]
	s_setprio 0
	s_barrier
	s_add_i32 s51, s51, 2
	s_add_u32 s0, s0, 0x100
	s_addc_u32 s1, s1, 0
	s_add_u32 s43, s43, 0x100
	s_addc_u32 s50, s50, 0
	s_cmp_gt_u32 s51, 13
	s_cbranch_scc0 .LBB0_607
	s_branch .Lpeel_done_607

; #define PG8_STAGE(bufoff, gbase, voff) do { _Pragma("unroll") for (int _i = 0; _i < 2; ++_i) \
;         __builtin_amdgcn_global_load_lds((const unsigned*)((const char*)(gbase) + (voff)[_i]), (PG8_LAS unsigned*)(lds + (bufoff) + ldsw + _i * 8192), 16, 0, 0); } while (0)
; #define PG8_LDA(dst, b, h) do { _Pragma("unroll") for (int m = 0; m < 4; ++m) _Pragma("unroll") for (int k = 0; k < 2; ++k) dst[m][k] = *(const PG8_LAS bf16x8*)(lds + PG8_SA(b, h) + aoff + m * 2048 + k * 1024); } while (0)
; #define PG8_LDB(dst, b, h) do { _Pragma("unroll") for (int n = 0; n < 2; ++n) _Pragma("unroll") for (int k = 0; k < 2; ++k) dst[n][k] = *(const PG8_LAS bf16x8*)(lds + PG8_SB(b, h) + boff + n * 2048 + k * 1024); } while (0)
; #define PG8_MMA(ai, bj, At, Bt) do { __builtin_amdgcn_s_setprio(1); _Pragma("unroll") for (int m = 0; m < 4; ++m) _Pragma("unroll") for (int n = 0; n < 2; ++n) _Pragma("unroll") for (int k = 0; k < 2; ++k) \
;         acc[ai][bj][m][n] = __builtin_amdgcn_mfma_f32_16x16x32_bf16(Bt[n][k], At[m][k], acc[ai][bj][m][n], 0, 0, 0); __builtin_amdgcn_s_setprio(0); } while (0)
; #define PG8_WAIT_V(n) asm volatile("s_waitcnt vmcnt(" #n ")" ::: "memory")
; #define PG8_BAR __builtin_amdgcn_s_barrier()
; template <class Epi, class Sched, bool ALIGN_EPI = false, bool SP2 = false>
; __device__ __forceinline__ void gemm_phase(PG8_LAS unsigned char* lds, const Gemm g, const Sched& S, const Epi& E) {
;     ...
;         for (int t = 0; t < nt; t += 2) {
;             const bool last = (t == nt - 2);
;             const char* a1 = cA + (size_t)(t + 1) * kstep;
;             const char* a2 = last ? nA : cA + (size_t)(t + 2) * kstep; const char* b2 = last ? nB : cB + (size_t)(t + 2) * kstep;
;             const char* a3 = a2 + kstep; const char* b3 = b2 + kstep;
;             if (last && has_next) S.a_ready(nxt);
;             if constexpr (SP2) {
;             PG8_LDB(B0, 0, 0); PG8_LDB(B1, 0, 1); PG8_SCHED; PG8_LDA(At, 0, 0); PG8_STAGE(PG8_SA(1, 1), a1 + hstepA, voffA);
;             PG8_WAIT_V(8); PG8_WAIT_L(0); PG8_BAR; PG8_MMA(0, 0, At, B0); PG8_MMA(0, 1, At, B1); PG8_BAR; PG8_SCHED;
;             PG8_LDA(At, 0, 1); PG8_STAGE(PG8_SB(0, 0), b2, voffB); PG8_STAGE(PG8_SB(0, 1), b2 + hstepB, voffB); PG8_STAGE(PG8_SA(0, 0), a2, voffA);
;             PG8_WAIT_V(8); PG8_WAIT_L(0); PG8_BAR; PG8_MMA(1, 0, At, B0); PG8_MMA(1, 1, At, B1); PG8_BAR; PG8_SCHED;
.LBB0_689:
	s_ashr_i32 s47, s46, 31
	s_lshl_b64 s[14:15], s[46:47], 18
	s_add_u32 s50, s54, s14
	s_addc_u32 s51, s55, s15
	s_and_b64 s[4:5], s[4:5], exec
	s_cselect_b32 s14, s51, s21
	s_cselect_b32 s15, s50, s20
	s_add_u32 s18, s20, 0x100
	s_addc_u32 s19, s21, 0
	s_mov_b32 s34, -2
	s_add_u32 s4, s0, 0x100
	s_addc_u32 s5, s1, 0
	s_add_i32 s28, 0, 0x10000
	s_cmp_eq_u32 s34, 4
	s_cselect_b32 s23, s49, s5
	s_cselect_b32 s22, s48, s4
	s_cselect_b32 s21, s14, s19
	s_cselect_b32 s20, s15, s18
	s_add_i32 s29, 0, 0x14000
	v_add_u32_e32 v140, s28, v211
	v_add_u32_e32 v156, s29, v211
	ds_read_b128 v[128:131], v140
	ds_read_b128 v[132:135], v140 offset:1024
	ds_read_b128 v[136:139], v140 offset:2048
	ds_read_b128 v[140:143], v140 offset:3072
	ds_read_b128 v[144:147], v156
	ds_read_b128 v[148:151], v156 offset:1024
	ds_read_b128 v[152:155], v156 offset:2048
	ds_read_b128 v[156:159], v156 offset:3072
	v_lshl_add_u64 v[202:203], s[0:1], 0, v[198:199]
	s_add_i32 m0, s53, 0xc000
	ds_read_b128 v[160:163], v231
	ds_read_b128 v[164:167], v231 offset:1024
	ds_read_b128 v[168:171], v231 offset:2048
	ds_read_b128 v[172:175], v231 offset:3072
	ds_read_b128 v[176:179], v231 offset:4096
	ds_read_b128 v[180:183], v231 offset:5120
	ds_read_b128 v[184:187], v231 offset:6144
	ds_read_b128 v[188:191], v231 offset:7168
	global_load_lds_dwordx4 v[202:203], off
	v_lshl_add_u64 v[202:203], s[0:1], 0, v[200:201]
	s_add_i32 m0, s53, 0xe000
	s_nop 0
	global_load_lds_dwordx4 v[202:203], off
	s_waitcnt vmcnt(8)
	s_waitcnt lgkmcnt(0)
	s_barrier
	s_setprio 1
	s_waitcnt lgkmcnt(0)
	v_mfma_f32_16x16x32_bf16 v[124:127], v[128:131], v[160:163], 0
	v_mfma_f32_16x16x32_bf16 v[120:123], v[136:139], v[160:163], 0
	v_mfma_f32_16x16x32_bf16 v[112:115], v[128:131], v[168:171], 0
	v_mfma_f32_16x16x32_bf16 v[104:107], v[136:139], v[168:171], 0
	v_mfma_f32_16x16x32_bf16 v[96:99], v[128:131], v[176:179], 0
	v_mfma_f32_16x16x32_bf16 v[88:91], v[136:139], v[176:179], 0
	v_mfma_f32_16x16x32_bf16 v[80:83], v[128:131], v[184:187], 0
	v_mfma_f32_16x16x32_bf16 v[72:75], v[136:139], v[184:187], 0
	v_mfma_f32_16x16x32_bf16 v[124:127], v[132:135], v[164:167], v[124:127]
	v_mfma_f32_16x16x32_bf16 v[120:123], v[140:143], v[164:167], v[120:123]
	v_mfma_f32_16x16x32_bf16 v[112:115], v[132:135], v[172:175], v[112:115]
	v_mfma_f32_16x16x32_bf16 v[104:107], v[140:143], v[172:175], v[104:107]
	v_mfma_f32_16x16x32_bf16 v[96:99], v[132:135], v[180:183], v[96:99]
	v_mfma_f32_16x16x32_bf16 v[88:91], v[140:143], v[180:183], v[88:91]
	v_mfma_f32_16x16x32_bf16 v[80:83], v[132:135], v[188:191], v[80:83]
	v_mfma_f32_16x16x32_bf16 v[72:75], v[140:143], v[188:191], v[72:75]
	s_setprio 0
	s_setprio 1
	v_mfma_f32_16x16x32_bf16 v[116:119], v[144:147], v[160:163], 0
	v_mfma_f32_16x16x32_bf16 v[108:111], v[152:155], v[160:163], 0
	v_mfma_f32_16x16x32_bf16 v[100:103], v[144:147], v[168:171], 0
	v_mfma_f32_16x16x32_bf16 v[92:95], v[152:155], v[168:171], 0
	v_mfma_f32_16x16x32_bf16 v[84:87], v[144:147], v[176:179], 0
	v_mfma_f32_16x16x32_bf16 v[76:79], v[152:155], v[176:179], 0
	v_mfma_f32_16x16x32_bf16 v[68:71], v[144:147], v[184:187], 0
	v_mfma_f32_16x16x32_bf16 v[64:67], v[152:155], v[184:187], 0
	v_mfma_f32_16x16x32_bf16 v[116:119], v[148:151], v[164:167], v[116:119]
	v_mfma_f32_16x16x32_bf16 v[108:111], v[156:159], v[164:167], v[108:111]
	v_mfma_f32_16x16x32_bf16 v[100:103], v[148:151], v[172:175], v[100:103]
	v_mfma_f32_16x16x32_bf16 v[92:95], v[156:159], v[172:175], v[92:95]
	v_mfma_f32_16x16x32_bf16 v[84:87], v[148:151], v[180:183], v[84:87]
	v_mfma_f32_16x16x32_bf16 v[76:79], v[156:159], v[180:183], v[76:79]
	v_mfma_f32_16x16x32_bf16 v[68:71], v[148:151], v[188:191], v[68:71]
	v_mfma_f32_16x16x32_bf16 v[64:67], v[156:159], v[188:191], v[64:67]
	s_setprio 0
	s_barrier
	s_add_i32 s0, s28, s56
	v_lshl_add_u64 v[202:203], s[20:21], 0, v[208:209]
	s_mov_b32 m0, s0
	ds_read_b128 v[160:163], v231 offset:16384
	ds_read_b128 v[164:167], v231 offset:17408
	ds_read_b128 v[168:171], v231 offset:18432
	ds_read_b128 v[172:175], v231 offset:19456
	ds_read_b128 v[176:179], v231 offset:20480
	ds_read_b128 v[180:183], v231 offset:21504
	ds_read_b128 v[184:187], v231 offset:22528
	ds_read_b128 v[188:191], v231 offset:23552
	global_load_lds_dwordx4 v[202:203], off
	s_add_i32 m0, s0, 0x2000
	s_add_u32 s0, s20, 0x20000
	v_lshl_add_u64 v[204:205], s[20:21], 0, v[196:197]
	s_addc_u32 s1, s21, 0
	s_add_i32 s28, s29, s56
	global_load_lds_dwordx4 v[204:205], off
	v_lshl_add_u64 v[206:207], s[0:1], 0, v[208:209]
	s_mov_b32 m0, s28
	v_lshl_add_u64 v[212:213], s[22:23], 0, v[194:195]
	global_load_lds_dwordx4 v[206:207], off
	v_lshl_add_u64 v[206:207], s[0:1], 0, v[196:197]
	s_add_i32 m0, s28, 0x2000
	s_nop 0
	global_load_lds_dwordx4 v[206:207], off
	v_lshl_add_u64 v[206:207], s[22:23], 0, v[192:193]
	s_mov_b32 m0, s53
	s_nop 0
	global_load_lds_dwordx4 v[206:207], off
	s_mov_b32 m0, s57
	s_nop 0
	global_load_lds_dwordx4 v[212:213], off
	s_waitcnt vmcnt(8)
	s_waitcnt lgkmcnt(0)
	s_barrier
; #define PG8_STAGE(bufoff, gbase, voff) do { _Pragma("unroll") for (int _i = 0; _i < 2; ++_i) \
;         __builtin_amdgcn_global_load_lds((const unsigned*)((const char*)(gbase) + (voff)[_i]), (PG8_LAS unsigned*)(lds + (bufoff) + ldsw + _i * 8192), 16, 0, 0); } while (0)
; #define PG8_LDA(dst, b, h) do { _Pragma("unroll") for (int m = 0; m < 4; ++m) _Pragma("unroll") for (int k = 0; k < 2; ++k) dst[m][k] = *(const PG8_LAS bf16x8*)(lds + PG8_SA(b, h) + aoff + m * 2048 + k * 1024); } while (0)
; #define PG8_LDB(dst, b, h) do { _Pragma("unroll") for (int n = 0; n < 2; ++n) _Pragma("unroll") for (int k = 0; k < 2; ++k) dst[n][k] = *(const PG8_LAS bf16x8*)(lds + PG8_SB(b, h) + boff + n * 2048 + k * 1024); } while (0)
; #define PG8_MMA(ai, bj, At, Bt) do { __builtin_amdgcn_s_setprio(1); _Pragma("unroll") for (int m = 0; m < 4; ++m) _Pragma("unroll") for (int n = 0; n < 2; ++n) _Pragma("unroll") for (int k = 0; k < 2; ++k) \
;         acc[ai][bj][m][n] = __builtin_amdgcn_mfma_f32_16x16x32_bf16(Bt[n][k], At[m][k], acc[ai][bj][m][n], 0, 0, 0); __builtin_amdgcn_s_setprio(0); } while (0)
; #define PG8_WAIT_V(n) asm volatile("s_waitcnt vmcnt(" #n ")" ::: "memory")
; #define PG8_WAIT_L(n) asm volatile("s_waitcnt lgkmcnt(" #n ")" ::: "memory")
; #define PG8_BAR __builtin_amdgcn_s_barrier()
; #define PG8_SCHED __builtin_amdgcn_sched_barrier(0)
; template <class Epi, class Sched, bool ALIGN_EPI = false, bool SP2 = false>
; __device__ __forceinline__ void gemm_phase(PG8_LAS unsigned char* lds, const Gemm g, const Sched& S, const Epi& E) {
;     ...
;             PG8_WAIT_V(8); PG8_WAIT_L(0); PG8_BAR; PG8_MMA(1, 0, At, B0); PG8_MMA(1, 1, At, B1); PG8_BAR; PG8_SCHED;
;             PG8_LDB(B0, 1, 0); PG8_LDB(B1, 1, 1); PG8_SCHED; PG8_LDA(At, 1, 0); PG8_STAGE(PG8_SA(0, 1), a2 + hstepA, voffA);
;             PG8_WAIT_V(8); PG8_WAIT_L(0); PG8_BAR; PG8_MMA(0, 0, At, B0); PG8_MMA(0, 1, At, B1); PG8_BAR; PG8_SCHED;
	s_setprio 1
	s_waitcnt lgkmcnt(0)
	v_mfma_f32_16x16x32_bf16 v[60:63], v[128:131], v[160:163], 0
	v_mfma_f32_16x16x32_bf16 v[56:59], v[136:139], v[160:163], 0
	v_mfma_f32_16x16x32_bf16 v[48:51], v[128:131], v[168:171], 0
	v_mfma_f32_16x16x32_bf16 v[40:43], v[136:139], v[168:171], 0
	v_mfma_f32_16x16x32_bf16 v[32:35], v[128:131], v[176:179], 0
	v_mfma_f32_16x16x32_bf16 v[24:27], v[136:139], v[176:179], 0
	v_mfma_f32_16x16x32_bf16 v[16:19], v[128:131], v[184:187], 0
	v_mfma_f32_16x16x32_bf16 v[8:11], v[136:139], v[184:187], 0
	v_mfma_f32_16x16x32_bf16 v[60:63], v[132:135], v[164:167], v[60:63]
	v_mfma_f32_16x16x32_bf16 v[56:59], v[140:143], v[164:167], v[56:59]
	v_mfma_f32_16x16x32_bf16 v[48:51], v[132:135], v[172:175], v[48:51]
	v_mfma_f32_16x16x32_bf16 v[40:43], v[140:143], v[172:175], v[40:43]
	v_mfma_f32_16x16x32_bf16 v[32:35], v[132:135], v[180:183], v[32:35]
	v_mfma_f32_16x16x32_bf16 v[24:27], v[140:143], v[180:183], v[24:27]
	v_mfma_f32_16x16x32_bf16 v[16:19], v[132:135], v[188:191], v[16:19]
	v_mfma_f32_16x16x32_bf16 v[8:11], v[140:143], v[188:191], v[8:11]
	s_setprio 0
	s_setprio 1
	v_mfma_f32_16x16x32_bf16 v[52:55], v[144:147], v[160:163], 0
	v_mfma_f32_16x16x32_bf16 v[44:47], v[152:155], v[160:163], 0
	v_mfma_f32_16x16x32_bf16 v[36:39], v[144:147], v[168:171], 0
	v_mfma_f32_16x16x32_bf16 v[28:31], v[152:155], v[168:171], 0
	v_mfma_f32_16x16x32_bf16 v[20:23], v[144:147], v[176:179], 0
	v_mfma_f32_16x16x32_bf16 v[12:15], v[152:155], v[176:179], 0
	v_mfma_f32_16x16x32_bf16 v[4:7], v[144:147], v[184:187], 0
	v_mfma_f32_16x16x32_bf16 v[0:3], v[152:155], v[184:187], 0
	v_mfma_f32_16x16x32_bf16 v[52:55], v[148:151], v[164:167], v[52:55]
	v_mfma_f32_16x16x32_bf16 v[44:47], v[156:159], v[164:167], v[44:47]
	v_mfma_f32_16x16x32_bf16 v[36:39], v[148:151], v[172:175], v[36:39]
	v_mfma_f32_16x16x32_bf16 v[28:31], v[156:159], v[172:175], v[28:31]
	v_mfma_f32_16x16x32_bf16 v[20:23], v[148:151], v[180:183], v[20:23]
	v_mfma_f32_16x16x32_bf16 v[12:15], v[156:159], v[180:183], v[12:15]
	v_mfma_f32_16x16x32_bf16 v[4:7], v[148:151], v[188:191], v[4:7]
	v_mfma_f32_16x16x32_bf16 v[0:3], v[156:159], v[188:191], v[0:3]
	s_setprio 0
	s_barrier
	s_add_i32 s28, 0, 0x18000
	s_add_i32 s29, 0, 0x1c000
	v_add_u32_e32 v140, s28, v211
	v_add_u32_e32 v156, s29, v211
	ds_read_b128 v[128:131], v140
	ds_read_b128 v[132:135], v140 offset:1024
	ds_read_b128 v[136:139], v140 offset:2048
	ds_read_b128 v[140:143], v140 offset:3072
	ds_read_b128 v[144:147], v156
	ds_read_b128 v[148:151], v156 offset:1024
	ds_read_b128 v[152:155], v156 offset:2048
	ds_read_b128 v[156:159], v156 offset:3072
	s_add_u32 s0, s22, 0x60000
	s_addc_u32 s1, s23, 0
	s_mov_b32 m0, s58
	v_lshl_add_u64 v[222:223], s[0:1], 0, v[192:193]
	ds_read_b128 v[160:163], v231 offset:32768
	ds_read_b128 v[164:167], v231 offset:33792
	ds_read_b128 v[168:171], v231 offset:34816
	ds_read_b128 v[172:175], v231 offset:35840
	ds_read_b128 v[176:179], v231 offset:36864
	ds_read_b128 v[180:183], v231 offset:37888
	ds_read_b128 v[184:187], v231 offset:38912
	ds_read_b128 v[188:191], v231 offset:39936
	global_load_lds_dwordx4 v[222:223], off
	v_lshl_add_u64 v[222:223], s[0:1], 0, v[194:195]
	s_mov_b32 m0, s59
	s_nop 0
	global_load_lds_dwordx4 v[222:223], off
	s_waitcnt vmcnt(8)
	s_waitcnt lgkmcnt(0)
	s_barrier
	s_setprio 1
	s_waitcnt lgkmcnt(0)
	v_mfma_f32_16x16x32_bf16 v[124:127], v[128:131], v[160:163], v[124:127]
	v_mfma_f32_16x16x32_bf16 v[120:123], v[136:139], v[160:163], v[120:123]
	v_mfma_f32_16x16x32_bf16 v[112:115], v[128:131], v[168:171], v[112:115]
	v_mfma_f32_16x16x32_bf16 v[104:107], v[136:139], v[168:171], v[104:107]
	v_mfma_f32_16x16x32_bf16 v[96:99], v[128:131], v[176:179], v[96:99]
	v_mfma_f32_16x16x32_bf16 v[88:91], v[136:139], v[176:179], v[88:91]
	v_mfma_f32_16x16x32_bf16 v[80:83], v[128:131], v[184:187], v[80:83]
	v_mfma_f32_16x16x32_bf16 v[72:75], v[136:139], v[184:187], v[72:75]
	v_mfma_f32_16x16x32_bf16 v[124:127], v[132:135], v[164:167], v[124:127]
	v_mfma_f32_16x16x32_bf16 v[120:123], v[140:143], v[164:167], v[120:123]
	v_mfma_f32_16x16x32_bf16 v[112:115], v[132:135], v[172:175], v[112:115]
	v_mfma_f32_16x16x32_bf16 v[104:107], v[140:143], v[172:175], v[104:107]
	v_mfma_f32_16x16x32_bf16 v[96:99], v[132:135], v[180:183], v[96:99]
	v_mfma_f32_16x16x32_bf16 v[88:91], v[140:143], v[180:183], v[88:91]
	v_mfma_f32_16x16x32_bf16 v[80:83], v[132:135], v[188:191], v[80:83]
	v_mfma_f32_16x16x32_bf16 v[72:75], v[140:143], v[188:191], v[72:75]
	s_setprio 0
	s_setprio 1
	v_mfma_f32_16x16x32_bf16 v[116:119], v[144:147], v[160:163], v[116:119]
	v_mfma_f32_16x16x32_bf16 v[108:111], v[152:155], v[160:163], v[108:111]
	v_mfma_f32_16x16x32_bf16 v[100:103], v[144:147], v[168:171], v[100:103]
	v_mfma_f32_16x16x32_bf16 v[92:95], v[152:155], v[168:171], v[92:95]
	v_mfma_f32_16x16x32_bf16 v[84:87], v[144:147], v[176:179], v[84:87]
	v_mfma_f32_16x16x32_bf16 v[76:79], v[152:155], v[176:179], v[76:79]
	v_mfma_f32_16x16x32_bf16 v[68:71], v[144:147], v[184:187], v[68:71]
	v_mfma_f32_16x16x32_bf16 v[64:67], v[152:155], v[184:187], v[64:67]
	v_mfma_f32_16x16x32_bf16 v[116:119], v[148:151], v[164:167], v[116:119]
	v_mfma_f32_16x16x32_bf16 v[108:111], v[156:159], v[164:167], v[108:111]
	v_mfma_f32_16x16x32_bf16 v[100:103], v[148:151], v[172:175], v[100:103]
	v_mfma_f32_16x16x32_bf16 v[92:95], v[156:159], v[172:175], v[92:95]
	v_mfma_f32_16x16x32_bf16 v[84:87], v[148:151], v[180:183], v[84:87]
	v_mfma_f32_16x16x32_bf16 v[76:79], v[156:159], v[180:183], v[76:79]
	v_mfma_f32_16x16x32_bf16 v[68:71], v[148:151], v[188:191], v[68:71]
	v_mfma_f32_16x16x32_bf16 v[64:67], v[156:159], v[188:191], v[64:67]
	s_setprio 0
	s_barrier
; #define PG8_STAGE(bufoff, gbase, voff) do { _Pragma("unroll") for (int _i = 0; _i < 2; ++_i) \
;         __builtin_amdgcn_global_load_lds((const unsigned*)((const char*)(gbase) + (voff)[_i]), (PG8_LAS unsigned*)(lds + (bufoff) + ldsw + _i * 8192), 16, 0, 0); } while (0)
; #define PG8_LDA(dst, b, h) do { _Pragma("unroll") for (int m = 0; m < 4; ++m) _Pragma("unroll") for (int k = 0; k < 2; ++k) dst[m][k] = *(const PG8_LAS bf16x8*)(lds + PG8_SA(b, h) + aoff + m * 2048 + k * 1024); } while (0)
; #define PG8_MMA(ai, bj, At, Bt) do { __builtin_amdgcn_s_setprio(1); _Pragma("unroll") for (int m = 0; m < 4; ++m) _Pragma("unroll") for (int n = 0; n < 2; ++n) _Pragma("unroll") for (int k = 0; k < 2; ++k) \
;         acc[ai][bj][m][n] = __builtin_amdgcn_mfma_f32_16x16x32_bf16(Bt[n][k], At[m][k], acc[ai][bj][m][n], 0, 0, 0); __builtin_amdgcn_s_setprio(0); } while (0)
; #define PG8_WAIT_V(n) asm volatile("s_waitcnt vmcnt(" #n ")" ::: "memory")
; #define PG8_WAIT_L(n) asm volatile("s_waitcnt lgkmcnt(" #n ")" ::: "memory")
; #define PG8_BAR __builtin_amdgcn_s_barrier()
; #define PG8_SCHED __builtin_amdgcn_sched_barrier(0)
; template <class Epi, class Sched, bool ALIGN_EPI = false, bool SP2 = false>
; __device__ __forceinline__ void gemm_phase(PG8_LAS unsigned char* lds, const Gemm g, const Sched& S, const Epi& E) {
;     ...
;         for (int t = 0; t < nt; t += 2) {
;             const bool last = (t == nt - 2);
;     ...
;             PG8_LDA(At, 1, 1); PG8_STAGE(PG8_SB(1, 0), b3, voffB); PG8_STAGE(PG8_SB(1, 1), b3 + hstepB, voffB); PG8_STAGE(PG8_SA(1, 0), a3, voffA);
;             PG8_WAIT_V(8); PG8_WAIT_L(0); PG8_BAR; PG8_MMA(1, 0, At, B0); PG8_MMA(1, 1, At, B1); PG8_BAR; PG8_SCHED;
	s_add_i32 s0, s28, s56
	v_lshl_add_u64 v[202:203], v[202:203], 0, s[10:11]
	s_mov_b32 m0, s0
	ds_read_b128 v[160:163], v231 offset:49152
	ds_read_b128 v[164:167], v231 offset:50176
	ds_read_b128 v[168:171], v231 offset:51200
	ds_read_b128 v[172:175], v231 offset:52224
	ds_read_b128 v[176:179], v231 offset:53248
	ds_read_b128 v[180:183], v231 offset:54272
	ds_read_b128 v[184:187], v231 offset:55296
	ds_read_b128 v[188:191], v231 offset:56320
	global_load_lds_dwordx4 v[202:203], off
	s_add_i32 m0, s0, 0x2000
	s_add_u32 s0, s20, 0x20080
	v_lshl_add_u64 v[202:203], v[204:205], 0, s[10:11]
	s_addc_u32 s1, s21, 0
	s_add_i32 s20, s29, s56
	global_load_lds_dwordx4 v[202:203], off
	v_lshl_add_u64 v[202:203], s[0:1], 0, v[208:209]
	s_mov_b32 m0, s20
	s_nop 0
	global_load_lds_dwordx4 v[202:203], off
	v_lshl_add_u64 v[202:203], s[0:1], 0, v[196:197]
	s_add_i32 m0, s20, 0x2000
	s_nop 0
	global_load_lds_dwordx4 v[202:203], off
	v_lshl_add_u64 v[202:203], v[206:207], 0, s[10:11]
	s_mov_b32 m0, s61
	s_nop 0
	global_load_lds_dwordx4 v[202:203], off
	v_lshl_add_u64 v[202:203], v[212:213], 0, s[10:11]
	s_mov_b32 m0, s62
	s_nop 0
	global_load_lds_dwordx4 v[202:203], off
	s_waitcnt vmcnt(8)
	s_waitcnt lgkmcnt(0)
	s_barrier
	s_setprio 1
	s_waitcnt lgkmcnt(0)
	v_mfma_f32_16x16x32_bf16 v[60:63], v[128:131], v[160:163], v[60:63]
	v_mfma_f32_16x16x32_bf16 v[56:59], v[136:139], v[160:163], v[56:59]
	v_mfma_f32_16x16x32_bf16 v[48:51], v[128:131], v[168:171], v[48:51]
	v_mfma_f32_16x16x32_bf16 v[40:43], v[136:139], v[168:171], v[40:43]
	v_mfma_f32_16x16x32_bf16 v[32:35], v[128:131], v[176:179], v[32:35]
	v_mfma_f32_16x16x32_bf16 v[24:27], v[136:139], v[176:179], v[24:27]
	v_mfma_f32_16x16x32_bf16 v[16:19], v[128:131], v[184:187], v[16:19]
	v_mfma_f32_16x16x32_bf16 v[8:11], v[136:139], v[184:187], v[8:11]
	v_mfma_f32_16x16x32_bf16 v[60:63], v[132:135], v[164:167], v[60:63]
	v_mfma_f32_16x16x32_bf16 v[56:59], v[140:143], v[164:167], v[56:59]
	v_mfma_f32_16x16x32_bf16 v[48:51], v[132:135], v[172:175], v[48:51]
	v_mfma_f32_16x16x32_bf16 v[40:43], v[140:143], v[172:175], v[40:43]
	v_mfma_f32_16x16x32_bf16 v[32:35], v[132:135], v[180:183], v[32:35]
	v_mfma_f32_16x16x32_bf16 v[24:27], v[140:143], v[180:183], v[24:27]
	v_mfma_f32_16x16x32_bf16 v[16:19], v[132:135], v[188:191], v[16:19]
	v_mfma_f32_16x16x32_bf16 v[8:11], v[140:143], v[188:191], v[8:11]
	s_setprio 0
	s_setprio 1
	v_mfma_f32_16x16x32_bf16 v[52:55], v[144:147], v[160:163], v[52:55]
	v_mfma_f32_16x16x32_bf16 v[44:47], v[152:155], v[160:163], v[44:47]
	v_mfma_f32_16x16x32_bf16 v[36:39], v[144:147], v[168:171], v[36:39]
	v_mfma_f32_16x16x32_bf16 v[28:31], v[152:155], v[168:171], v[28:31]
	v_mfma_f32_16x16x32_bf16 v[20:23], v[144:147], v[176:179], v[20:23]
	v_mfma_f32_16x16x32_bf16 v[12:15], v[152:155], v[176:179], v[12:15]
	v_mfma_f32_16x16x32_bf16 v[4:7], v[144:147], v[184:187], v[4:7]
	v_mfma_f32_16x16x32_bf16 v[0:3], v[152:155], v[184:187], v[0:3]
	v_mfma_f32_16x16x32_bf16 v[52:55], v[148:151], v[164:167], v[52:55]
	v_mfma_f32_16x16x32_bf16 v[44:47], v[156:159], v[164:167], v[44:47]
	v_mfma_f32_16x16x32_bf16 v[36:39], v[148:151], v[172:175], v[36:39]
	v_mfma_f32_16x16x32_bf16 v[28:31], v[156:159], v[172:175], v[28:31]
	v_mfma_f32_16x16x32_bf16 v[20:23], v[148:151], v[180:183], v[20:23]
	v_mfma_f32_16x16x32_bf16 v[12:15], v[156:159], v[180:183], v[12:15]
	v_mfma_f32_16x16x32_bf16 v[4:7], v[148:151], v[188:191], v[4:7]
	v_mfma_f32_16x16x32_bf16 v[0:3], v[156:159], v[188:191], v[0:3]
	s_setprio 0
	s_barrier
	s_add_i32 s34, s34, 2
	s_add_u32 s18, s18, 0x100
	s_addc_u32 s19, s19, 0
	s_cmp_gt_u32 s34, 5
	s_mov_b64 s[0:1], s[4:5]
	s_cbranch_scc0 .LBB0_690
	s_branch .Lpeel_done_690

; #define PG8_BAR __builtin_amdgcn_s_barrier()
; template <class Epi, class Sched, bool ALIGN_EPI = false, bool SP2 = false>
; __device__ __forceinline__ void gemm_phase(PG8_LAS unsigned char* lds, const Gemm g, const Sched& S, const Epi& E) {
;     ...
;         }
;         if constexpr (ALIGN_EPI) { if (wr == 0) PG8_BAR; }
.Lpeel_done_690:
	s_and_b64 vcc, exec, s[44:45]
	s_cbranch_vccz .LBB0_693
	s_barrier

; #define PG8_STAGE(bufoff, gbase, voff) do { _Pragma("unroll") for (int _i = 0; _i < 2; ++_i) \
;         __builtin_amdgcn_global_load_lds((const unsigned*)((const char*)(gbase) + (voff)[_i]), (PG8_LAS unsigned*)(lds + (bufoff) + ldsw + _i * 8192), 16, 0, 0); } while (0)
; #define PG8_LDA(dst, b, h) do { _Pragma("unroll") for (int m = 0; m < 4; ++m) _Pragma("unroll") for (int k = 0; k < 2; ++k) dst[m][k] = *(const PG8_LAS bf16x8*)(lds + PG8_SA(b, h) + aoff + m * 2048 + k * 1024); } while (0)
; #define PG8_LDB(dst, b, h) do { _Pragma("unroll") for (int n = 0; n < 2; ++n) _Pragma("unroll") for (int k = 0; k < 2; ++k) dst[n][k] = *(const PG8_LAS bf16x8*)(lds + PG8_SB(b, h) + boff + n * 2048 + k * 1024); } while (0)
; #define PG8_WAIT_V(n) asm volatile("s_waitcnt vmcnt(" #n ")" ::: "memory")
; #define PG8_WAIT_L(n) asm volatile("s_waitcnt lgkmcnt(" #n ")" ::: "memory")
; #define PG8_BAR __builtin_amdgcn_s_barrier()
; #define PG8_SCHED __builtin_amdgcn_sched_barrier(0)
; template <class Epi, class Sched, bool ALIGN_EPI = false, bool SP2 = false>
; __device__ __forceinline__ void gemm_phase(PG8_LAS unsigned char* lds, const Gemm g, const Sched& S, const Epi& E) {
;     ...
;         const bool has_next = S.next(ui + 1, nxt);
;         const char* nA = has_next ? (const char*)g.A + (size_t)nxt.pm * tstepA : cA; const char* nB = has_next ? (const char*)g.Bt + (size_t)nxt.pn * tstepB : cB;
;         for (int t = 0; t < nt; t += 2) {
;             const bool last = (t == nt - 2);
;             const char* a1 = cA + (size_t)(t + 1) * kstep;
;             const char* a2 = last ? nA : cA + (size_t)(t + 2) * kstep; const char* b2 = last ? nB : cB + (size_t)(t + 2) * kstep;
;             const char* a3 = a2 + kstep; const char* b3 = b2 + kstep;
;             if (last && has_next) S.a_ready(nxt);
;             if constexpr (SP2) {
;             PG8_LDB(B0, 0, 0); PG8_LDB(B1, 0, 1); PG8_SCHED; PG8_LDA(At, 0, 0); PG8_STAGE(PG8_SA(1, 1), a1 + hstepA, voffA);
;             PG8_WAIT_V(8); PG8_WAIT_L(0); PG8_BAR; PG8_MMA(0, 0, At, B0); PG8_MMA(0, 1, At, B1); PG8_BAR; PG8_SCHED;
;             PG8_LDA(At, 0, 1); PG8_STAGE(PG8_SB(0, 0), b2, voffB); PG8_STAGE(PG8_SB(0, 1), b2 + hstepB, voffB); PG8_STAGE(PG8_SA(0, 0), a2, voffA);
;             PG8_WAIT_V(8); PG8_WAIT_L(0); PG8_BAR; PG8_MMA(1, 0, At, B0); PG8_MMA(1, 1, At, B1); PG8_BAR; PG8_SCHED;
.LBB0_796:
	s_ashr_i32 s43, s42, 31
	s_lshl_b64 s[14:15], s[42:43], 19
	s_add_u32 s44, s16, s14
	s_addc_u32 s45, s17, s15
	s_and_b64 s[14:15], s[40:41], exec
	s_cselect_b32 s14, s45, s1
	s_cselect_b32 s15, s44, s0
	s_ashr_i32 s9, s8, 31
	s_lshl_b64 s[22:23], s[8:9], 19
	s_add_u32 s46, s31, s22
	v_readlane_b32 s9, v254, 8
	s_addc_u32 s47, s9, s23
	s_and_b64 s[22:23], s[40:41], exec
	s_cselect_b32 s9, s47, s25
	s_cselect_b32 s38, s46, s24
	s_add_u32 s0, s0, 0x40080
	s_addc_u32 s1, s1, 0
	s_add_u32 s43, s24, 0x100
	s_addc_u32 s50, s25, 0
	s_mov_b32 s51, -2
	s_add_u32 s22, s0, 0xfffc0080
	s_addc_u32 s23, s1, -1
	s_add_i32 s28, 0, 0x10000
	s_cmp_eq_u32 s51, 12
	s_cselect_b32 s25, s14, s23
	s_cselect_b32 s24, s15, s22
	v_add_u32_e32 v138, s28, v141
	s_cselect_b32 s23, s9, s50
	s_cselect_b32 s22, s38, s43
	s_add_i32 s30, 0, 0x14000
	ds_read_b128 v[134:137], v138
	ds_read_b128 v[144:147], v138 offset:1024
	ds_read_b128 v[148:151], v138 offset:2048
	ds_read_b128 v[152:155], v138 offset:3072
	v_add_u32_e32 v138, s30, v141
	ds_read_b128 v[156:159], v138
	ds_read_b128 v[160:163], v138 offset:1024
	ds_read_b128 v[164:167], v138 offset:2048
	ds_read_b128 v[168:171], v138 offset:3072
	v_lshl_add_u64 v[138:139], s[0:1], 0, v[130:131]
	s_add_i32 m0, s21, 0xc000
	ds_read_b128 v[172:175], v143
	ds_read_b128 v[176:179], v143 offset:1024
	ds_read_b128 v[180:183], v143 offset:2048
	ds_read_b128 v[184:187], v143 offset:3072
	ds_read_b128 v[188:191], v143 offset:4096
	ds_read_b128 v[192:195], v143 offset:5120
	ds_read_b128 v[196:199], v143 offset:6144
	ds_read_b128 v[200:203], v143 offset:7168
	global_load_lds_dwordx4 v[138:139], off
	v_lshl_add_u64 v[138:139], s[0:1], 0, v[132:133]
	s_add_i32 m0, s21, 0xe000
	s_nop 0
	global_load_lds_dwordx4 v[138:139], off
	s_waitcnt vmcnt(8)
	s_waitcnt lgkmcnt(0)
	s_barrier
	s_setprio 1
	s_waitcnt lgkmcnt(0)
	v_mfma_f32_16x16x32_bf16 v[124:127], v[134:137], v[172:175], 0
	v_mfma_f32_16x16x32_bf16 v[120:123], v[148:151], v[172:175], 0
	v_mfma_f32_16x16x32_bf16 v[116:119], v[134:137], v[180:183], 0
	v_mfma_f32_16x16x32_bf16 v[112:115], v[148:151], v[180:183], 0
	v_mfma_f32_16x16x32_bf16 v[108:111], v[134:137], v[188:191], 0
	v_mfma_f32_16x16x32_bf16 v[100:103], v[148:151], v[188:191], 0
	v_mfma_f32_16x16x32_bf16 v[92:95], v[134:137], v[196:199], 0
	v_mfma_f32_16x16x32_bf16 v[80:83], v[148:151], v[196:199], 0
	v_mfma_f32_16x16x32_bf16 v[124:127], v[144:147], v[176:179], v[124:127]
	v_mfma_f32_16x16x32_bf16 v[120:123], v[152:155], v[176:179], v[120:123]
	v_mfma_f32_16x16x32_bf16 v[116:119], v[144:147], v[184:187], v[116:119]
	v_mfma_f32_16x16x32_bf16 v[112:115], v[152:155], v[184:187], v[112:115]
	v_mfma_f32_16x16x32_bf16 v[108:111], v[144:147], v[192:195], v[108:111]
	v_mfma_f32_16x16x32_bf16 v[100:103], v[152:155], v[192:195], v[100:103]
	v_mfma_f32_16x16x32_bf16 v[92:95], v[144:147], v[200:203], v[92:95]
	v_mfma_f32_16x16x32_bf16 v[80:83], v[152:155], v[200:203], v[80:83]
	s_setprio 0
	s_setprio 1
	v_mfma_f32_16x16x32_bf16 v[104:107], v[156:159], v[172:175], 0
	v_mfma_f32_16x16x32_bf16 v[96:99], v[164:167], v[172:175], 0
	v_mfma_f32_16x16x32_bf16 v[88:91], v[156:159], v[180:183], 0
	v_mfma_f32_16x16x32_bf16 v[84:87], v[164:167], v[180:183], 0
	v_mfma_f32_16x16x32_bf16 v[76:79], v[156:159], v[188:191], 0
	v_mfma_f32_16x16x32_bf16 v[72:75], v[164:167], v[188:191], 0
	v_mfma_f32_16x16x32_bf16 v[68:71], v[156:159], v[196:199], 0
	v_mfma_f32_16x16x32_bf16 v[64:67], v[164:167], v[196:199], 0
	v_mfma_f32_16x16x32_bf16 v[104:107], v[160:163], v[176:179], v[104:107]
	v_mfma_f32_16x16x32_bf16 v[96:99], v[168:171], v[176:179], v[96:99]
	v_mfma_f32_16x16x32_bf16 v[88:91], v[160:163], v[184:187], v[88:91]
	v_mfma_f32_16x16x32_bf16 v[84:87], v[168:171], v[184:187], v[84:87]
	v_mfma_f32_16x16x32_bf16 v[76:79], v[160:163], v[192:195], v[76:79]
	v_mfma_f32_16x16x32_bf16 v[72:75], v[168:171], v[192:195], v[72:75]
	v_mfma_f32_16x16x32_bf16 v[68:71], v[160:163], v[200:203], v[68:71]
	v_mfma_f32_16x16x32_bf16 v[64:67], v[168:171], v[200:203], v[64:67]
	s_setprio 0
	s_barrier
	s_add_i32 s28, s28, s19
	v_lshl_add_u64 v[138:139], s[22:23], 0, v[208:209]
	s_mov_b32 m0, s28
	ds_read_b128 v[172:175], v143 offset:16384
	ds_read_b128 v[176:179], v143 offset:17408
	ds_read_b128 v[180:183], v143 offset:18432
	ds_read_b128 v[184:187], v143 offset:19456
	ds_read_b128 v[188:191], v143 offset:20480
	ds_read_b128 v[192:195], v143 offset:21504
	ds_read_b128 v[196:199], v143 offset:22528
	ds_read_b128 v[200:203], v143 offset:23552
	global_load_lds_dwordx4 v[138:139], off
	s_add_i32 m0, s28, 0x2000
	s_add_u32 s28, s22, 0x40000
	v_lshl_add_u64 v[204:205], s[22:23], 0, v[128:129]
	s_addc_u32 s29, s23, 0
	s_add_i32 s30, s30, s19
	global_load_lds_dwordx4 v[204:205], off
	v_lshl_add_u64 v[206:207], s[28:29], 0, v[208:209]
	s_mov_b32 m0, s30
	v_lshl_add_u64 v[210:211], s[24:25], 0, v[128:129]
	global_load_lds_dwordx4 v[206:207], off
	v_lshl_add_u64 v[206:207], s[28:29], 0, v[128:129]
	s_add_i32 m0, s30, 0x2000
	s_nop 0
	global_load_lds_dwordx4 v[206:207], off
	v_lshl_add_u64 v[206:207], s[24:25], 0, v[208:209]
	s_mov_b32 m0, s21
	s_nop 0
	global_load_lds_dwordx4 v[206:207], off
	s_mov_b32 m0, s26
	s_nop 0
	global_load_lds_dwordx4 v[210:211], off
	s_waitcnt vmcnt(8)
	s_waitcnt lgkmcnt(0)
	s_barrier
; #define PG8_STAGE(bufoff, gbase, voff) do { _Pragma("unroll") for (int _i = 0; _i < 2; ++_i) \
;         __builtin_amdgcn_global_load_lds((const unsigned*)((const char*)(gbase) + (voff)[_i]), (PG8_LAS unsigned*)(lds + (bufoff) + ldsw + _i * 8192), 16, 0, 0); } while (0)
; #define PG8_LDA(dst, b, h) do { _Pragma("unroll") for (int m = 0; m < 4; ++m) _Pragma("unroll") for (int k = 0; k < 2; ++k) dst[m][k] = *(const PG8_LAS bf16x8*)(lds + PG8_SA(b, h) + aoff + m * 2048 + k * 1024); } while (0)
; #define PG8_LDB(dst, b, h) do { _Pragma("unroll") for (int n = 0; n < 2; ++n) _Pragma("unroll") for (int k = 0; k < 2; ++k) dst[n][k] = *(const PG8_LAS bf16x8*)(lds + PG8_SB(b, h) + boff + n * 2048 + k * 1024); } while (0)
; #define PG8_MMA(ai, bj, At, Bt) do { __builtin_amdgcn_s_setprio(1); _Pragma("unroll") for (int m = 0; m < 4; ++m) _Pragma("unroll") for (int n = 0; n < 2; ++n) _Pragma("unroll") for (int k = 0; k < 2; ++k) \
;         acc[ai][bj][m][n] = __builtin_amdgcn_mfma_f32_16x16x32_bf16(Bt[n][k], At[m][k], acc[ai][bj][m][n], 0, 0, 0); __builtin_amdgcn_s_setprio(0); } while (0)
; #define PG8_WAIT_V(n) asm volatile("s_waitcnt vmcnt(" #n ")" ::: "memory")
; #define PG8_WAIT_L(n) asm volatile("s_waitcnt lgkmcnt(" #n ")" ::: "memory")
; #define PG8_BAR __builtin_amdgcn_s_barrier()
; #define PG8_SCHED __builtin_amdgcn_sched_barrier(0)
; template <class Epi, class Sched, bool ALIGN_EPI = false, bool SP2 = false>
; __device__ __forceinline__ void gemm_phase(PG8_LAS unsigned char* lds, const Gemm g, const Sched& S, const Epi& E) {
;     ...
;             PG8_WAIT_V(8); PG8_WAIT_L(0); PG8_BAR; PG8_MMA(1, 0, At, B0); PG8_MMA(1, 1, At, B1); PG8_BAR; PG8_SCHED;
;             PG8_LDB(B0, 1, 0); PG8_LDB(B1, 1, 1); PG8_SCHED; PG8_LDA(At, 1, 0); PG8_STAGE(PG8_SA(0, 1), a2 + hstepA, voffA);
;             PG8_WAIT_V(8); PG8_WAIT_L(0); PG8_BAR; PG8_MMA(0, 0, At, B0); PG8_MMA(0, 1, At, B1); PG8_BAR; PG8_SCHED;
	s_setprio 1
	s_waitcnt lgkmcnt(0)
	v_mfma_f32_16x16x32_bf16 v[60:63], v[134:137], v[172:175], 0
	v_mfma_f32_16x16x32_bf16 v[56:59], v[148:151], v[172:175], 0
	v_mfma_f32_16x16x32_bf16 v[52:55], v[134:137], v[180:183], 0
	v_mfma_f32_16x16x32_bf16 v[48:51], v[148:151], v[180:183], 0
	v_mfma_f32_16x16x32_bf16 v[44:47], v[134:137], v[188:191], 0
	v_mfma_f32_16x16x32_bf16 v[32:35], v[148:151], v[188:191], 0
	v_mfma_f32_16x16x32_bf16 v[16:19], v[134:137], v[196:199], 0
	v_mfma_f32_16x16x32_bf16 v[8:11], v[148:151], v[196:199], 0
	v_mfma_f32_16x16x32_bf16 v[60:63], v[144:147], v[176:179], v[60:63]
	v_mfma_f32_16x16x32_bf16 v[56:59], v[152:155], v[176:179], v[56:59]
	v_mfma_f32_16x16x32_bf16 v[52:55], v[144:147], v[184:187], v[52:55]
	v_mfma_f32_16x16x32_bf16 v[48:51], v[152:155], v[184:187], v[48:51]
	v_mfma_f32_16x16x32_bf16 v[44:47], v[144:147], v[192:195], v[44:47]
	v_mfma_f32_16x16x32_bf16 v[32:35], v[152:155], v[192:195], v[32:35]
	v_mfma_f32_16x16x32_bf16 v[16:19], v[144:147], v[200:203], v[16:19]
	v_mfma_f32_16x16x32_bf16 v[8:11], v[152:155], v[200:203], v[8:11]
	s_setprio 0
	s_setprio 1
	v_mfma_f32_16x16x32_bf16 v[40:43], v[156:159], v[172:175], 0
	v_mfma_f32_16x16x32_bf16 v[36:39], v[164:167], v[172:175], 0
	v_mfma_f32_16x16x32_bf16 v[28:31], v[156:159], v[180:183], 0
	v_mfma_f32_16x16x32_bf16 v[24:27], v[164:167], v[180:183], 0
	v_mfma_f32_16x16x32_bf16 v[20:23], v[156:159], v[188:191], 0
	v_mfma_f32_16x16x32_bf16 v[12:15], v[164:167], v[188:191], 0
	v_mfma_f32_16x16x32_bf16 v[4:7], v[156:159], v[196:199], 0
	v_mfma_f32_16x16x32_bf16 v[0:3], v[164:167], v[196:199], 0
	v_mfma_f32_16x16x32_bf16 v[40:43], v[160:163], v[176:179], v[40:43]
	v_mfma_f32_16x16x32_bf16 v[36:39], v[168:171], v[176:179], v[36:39]
	v_mfma_f32_16x16x32_bf16 v[28:31], v[160:163], v[184:187], v[28:31]
	v_mfma_f32_16x16x32_bf16 v[24:27], v[168:171], v[184:187], v[24:27]
	v_mfma_f32_16x16x32_bf16 v[20:23], v[160:163], v[192:195], v[20:23]
	v_mfma_f32_16x16x32_bf16 v[12:15], v[168:171], v[192:195], v[12:15]
	v_mfma_f32_16x16x32_bf16 v[4:7], v[160:163], v[200:203], v[4:7]
	v_mfma_f32_16x16x32_bf16 v[0:3], v[168:171], v[200:203], v[0:3]
	s_setprio 0
	s_barrier
	s_add_i32 s28, 0, 0x18000
	s_add_i32 s29, 0, 0x1c000
	v_add_u32_e32 v152, s28, v141
	v_add_u32_e32 v168, s29, v141
	ds_read_b128 v[134:137], v152
	ds_read_b128 v[144:147], v152 offset:1024
	ds_read_b128 v[148:151], v152 offset:2048
	ds_read_b128 v[152:155], v152 offset:3072
	ds_read_b128 v[156:159], v168
	ds_read_b128 v[160:163], v168 offset:1024
	ds_read_b128 v[164:167], v168 offset:2048
	ds_read_b128 v[168:171], v168 offset:3072
	s_add_u32 s24, s24, 0x40000
	s_addc_u32 s25, s25, 0
	s_mov_b32 m0, s34
	v_lshl_add_u64 v[212:213], s[24:25], 0, v[208:209]
	ds_read_b128 v[172:175], v143 offset:32768
	ds_read_b128 v[176:179], v143 offset:33792
	ds_read_b128 v[180:183], v143 offset:34816
	ds_read_b128 v[184:187], v143 offset:35840
	ds_read_b128 v[188:191], v143 offset:36864
	ds_read_b128 v[192:195], v143 offset:37888
	ds_read_b128 v[196:199], v143 offset:38912
	ds_read_b128 v[200:203], v143 offset:39936
	global_load_lds_dwordx4 v[212:213], off
	v_lshl_add_u64 v[212:213], s[24:25], 0, v[128:129]
	s_mov_b32 m0, s35
	s_nop 0
	global_load_lds_dwordx4 v[212:213], off
	s_waitcnt vmcnt(8)
	s_waitcnt lgkmcnt(0)
	s_barrier
	s_setprio 1
	s_waitcnt lgkmcnt(0)
	v_mfma_f32_16x16x32_bf16 v[124:127], v[134:137], v[172:175], v[124:127]
	v_mfma_f32_16x16x32_bf16 v[120:123], v[148:151], v[172:175], v[120:123]
	v_mfma_f32_16x16x32_bf16 v[116:119], v[134:137], v[180:183], v[116:119]
	v_mfma_f32_16x16x32_bf16 v[112:115], v[148:151], v[180:183], v[112:115]
	v_mfma_f32_16x16x32_bf16 v[108:111], v[134:137], v[188:191], v[108:111]
	v_mfma_f32_16x16x32_bf16 v[100:103], v[148:151], v[188:191], v[100:103]
	v_mfma_f32_16x16x32_bf16 v[92:95], v[134:137], v[196:199], v[92:95]
	v_mfma_f32_16x16x32_bf16 v[80:83], v[148:151], v[196:199], v[80:83]
	v_mfma_f32_16x16x32_bf16 v[124:127], v[144:147], v[176:179], v[124:127]
	v_mfma_f32_16x16x32_bf16 v[120:123], v[152:155], v[176:179], v[120:123]
	v_mfma_f32_16x16x32_bf16 v[116:119], v[144:147], v[184:187], v[116:119]
	v_mfma_f32_16x16x32_bf16 v[112:115], v[152:155], v[184:187], v[112:115]
	v_mfma_f32_16x16x32_bf16 v[108:111], v[144:147], v[192:195], v[108:111]
	v_mfma_f32_16x16x32_bf16 v[100:103], v[152:155], v[192:195], v[100:103]
	v_mfma_f32_16x16x32_bf16 v[92:95], v[144:147], v[200:203], v[92:95]
	v_mfma_f32_16x16x32_bf16 v[80:83], v[152:155], v[200:203], v[80:83]
	s_setprio 0
	s_setprio 1
	v_mfma_f32_16x16x32_bf16 v[104:107], v[156:159], v[172:175], v[104:107]
	v_mfma_f32_16x16x32_bf16 v[96:99], v[164:167], v[172:175], v[96:99]
	v_mfma_f32_16x16x32_bf16 v[88:91], v[156:159], v[180:183], v[88:91]
	v_mfma_f32_16x16x32_bf16 v[84:87], v[164:167], v[180:183], v[84:87]
	v_mfma_f32_16x16x32_bf16 v[76:79], v[156:159], v[188:191], v[76:79]
	v_mfma_f32_16x16x32_bf16 v[72:75], v[164:167], v[188:191], v[72:75]
	v_mfma_f32_16x16x32_bf16 v[68:71], v[156:159], v[196:199], v[68:71]
	v_mfma_f32_16x16x32_bf16 v[64:67], v[164:167], v[196:199], v[64:67]
	v_mfma_f32_16x16x32_bf16 v[104:107], v[160:163], v[176:179], v[104:107]
	v_mfma_f32_16x16x32_bf16 v[96:99], v[168:171], v[176:179], v[96:99]
	v_mfma_f32_16x16x32_bf16 v[88:91], v[160:163], v[184:187], v[88:91]
	v_mfma_f32_16x16x32_bf16 v[84:87], v[168:171], v[184:187], v[84:87]
	v_mfma_f32_16x16x32_bf16 v[76:79], v[160:163], v[192:195], v[76:79]
	v_mfma_f32_16x16x32_bf16 v[72:75], v[168:171], v[192:195], v[72:75]
	v_mfma_f32_16x16x32_bf16 v[68:71], v[160:163], v[200:203], v[68:71]
	v_mfma_f32_16x16x32_bf16 v[64:67], v[168:171], v[200:203], v[64:67]
	s_setprio 0
	s_barrier
; #define PG8_STAGE(bufoff, gbase, voff) do { _Pragma("unroll") for (int _i = 0; _i < 2; ++_i) \
;         __builtin_amdgcn_global_load_lds((const unsigned*)((const char*)(gbase) + (voff)[_i]), (PG8_LAS unsigned*)(lds + (bufoff) + ldsw + _i * 8192), 16, 0, 0); } while (0)
; #define PG8_LDA(dst, b, h) do { _Pragma("unroll") for (int m = 0; m < 4; ++m) _Pragma("unroll") for (int k = 0; k < 2; ++k) dst[m][k] = *(const PG8_LAS bf16x8*)(lds + PG8_SA(b, h) + aoff + m * 2048 + k * 1024); } while (0)
; #define PG8_MMA(ai, bj, At, Bt) do { __builtin_amdgcn_s_setprio(1); _Pragma("unroll") for (int m = 0; m < 4; ++m) _Pragma("unroll") for (int n = 0; n < 2; ++n) _Pragma("unroll") for (int k = 0; k < 2; ++k) \
;         acc[ai][bj][m][n] = __builtin_amdgcn_mfma_f32_16x16x32_bf16(Bt[n][k], At[m][k], acc[ai][bj][m][n], 0, 0, 0); __builtin_amdgcn_s_setprio(0); } while (0)
; #define PG8_WAIT_V(n) asm volatile("s_waitcnt vmcnt(" #n ")" ::: "memory")
; #define PG8_WAIT_L(n) asm volatile("s_waitcnt lgkmcnt(" #n ")" ::: "memory")
; #define PG8_BAR __builtin_amdgcn_s_barrier()
; #define PG8_SCHED __builtin_amdgcn_sched_barrier(0)
; template <class Epi, class Sched, bool ALIGN_EPI = false, bool SP2 = false>
; __device__ __forceinline__ void gemm_phase(PG8_LAS unsigned char* lds, const Gemm g, const Sched& S, const Epi& E) {
;     ...
;         for (int t = 0; t < nt; t += 2) {
;             const bool last = (t == nt - 2);
;     ...
;             PG8_LDA(At, 1, 1); PG8_STAGE(PG8_SB(1, 0), b3, voffB); PG8_STAGE(PG8_SB(1, 1), b3 + hstepB, voffB); PG8_STAGE(PG8_SA(1, 0), a3, voffA);
;             PG8_WAIT_V(8); PG8_WAIT_L(0); PG8_BAR; PG8_MMA(1, 0, At, B0); PG8_MMA(1, 1, At, B1); PG8_BAR; PG8_SCHED;
	s_add_i32 s24, s28, s19
	v_lshl_add_u64 v[138:139], v[138:139], 0, s[10:11]
	s_mov_b32 m0, s24
	ds_read_b128 v[172:175], v143 offset:49152
	ds_read_b128 v[176:179], v143 offset:50176
	ds_read_b128 v[180:183], v143 offset:51200
	ds_read_b128 v[184:187], v143 offset:52224
	ds_read_b128 v[188:191], v143 offset:53248
	ds_read_b128 v[192:195], v143 offset:54272
	ds_read_b128 v[196:199], v143 offset:55296
	ds_read_b128 v[200:203], v143 offset:56320
	global_load_lds_dwordx4 v[138:139], off
	s_add_i32 m0, s24, 0x2000
	s_add_u32 s22, s22, 0x40080
	v_lshl_add_u64 v[138:139], v[204:205], 0, s[10:11]
	s_addc_u32 s23, s23, 0
	s_add_i32 s24, s29, s19
	global_load_lds_dwordx4 v[138:139], off
	v_lshl_add_u64 v[138:139], s[22:23], 0, v[208:209]
	s_mov_b32 m0, s24
	s_nop 0
	global_load_lds_dwordx4 v[138:139], off
	v_lshl_add_u64 v[138:139], s[22:23], 0, v[128:129]
	s_add_i32 m0, s24, 0x2000
	s_nop 0
	global_load_lds_dwordx4 v[138:139], off
	v_lshl_add_u64 v[138:139], v[206:207], 0, s[10:11]
	s_mov_b32 m0, s39
	s_nop 0
	global_load_lds_dwordx4 v[138:139], off
	v_lshl_add_u64 v[138:139], v[210:211], 0, s[10:11]
	s_mov_b32 m0, s48
	s_nop 0
	global_load_lds_dwordx4 v[138:139], off
	s_waitcnt vmcnt(8)
	s_waitcnt lgkmcnt(0)
	s_barrier
	s_setprio 1
	s_waitcnt lgkmcnt(0)
	v_mfma_f32_16x16x32_bf16 v[60:63], v[134:137], v[172:175], v[60:63]
	v_mfma_f32_16x16x32_bf16 v[56:59], v[148:151], v[172:175], v[56:59]
	v_mfma_f32_16x16x32_bf16 v[52:55], v[134:137], v[180:183], v[52:55]
	v_mfma_f32_16x16x32_bf16 v[48:51], v[148:151], v[180:183], v[48:51]
	v_mfma_f32_16x16x32_bf16 v[44:47], v[134:137], v[188:191], v[44:47]
	v_mfma_f32_16x16x32_bf16 v[32:35], v[148:151], v[188:191], v[32:35]
	v_mfma_f32_16x16x32_bf16 v[16:19], v[134:137], v[196:199], v[16:19]
	v_mfma_f32_16x16x32_bf16 v[8:11], v[148:151], v[196:199], v[8:11]
	v_mfma_f32_16x16x32_bf16 v[60:63], v[144:147], v[176:179], v[60:63]
	v_mfma_f32_16x16x32_bf16 v[56:59], v[152:155], v[176:179], v[56:59]
	v_mfma_f32_16x16x32_bf16 v[52:55], v[144:147], v[184:187], v[52:55]
	v_mfma_f32_16x16x32_bf16 v[48:51], v[152:155], v[184:187], v[48:51]
	v_mfma_f32_16x16x32_bf16 v[44:47], v[144:147], v[192:195], v[44:47]
	v_mfma_f32_16x16x32_bf16 v[32:35], v[152:155], v[192:195], v[32:35]
	v_mfma_f32_16x16x32_bf16 v[16:19], v[144:147], v[200:203], v[16:19]
	v_mfma_f32_16x16x32_bf16 v[8:11], v[152:155], v[200:203], v[8:11]
	s_setprio 0
	s_setprio 1
	v_mfma_f32_16x16x32_bf16 v[40:43], v[156:159], v[172:175], v[40:43]
	v_mfma_f32_16x16x32_bf16 v[36:39], v[164:167], v[172:175], v[36:39]
	v_mfma_f32_16x16x32_bf16 v[28:31], v[156:159], v[180:183], v[28:31]
	v_mfma_f32_16x16x32_bf16 v[24:27], v[164:167], v[180:183], v[24:27]
	v_mfma_f32_16x16x32_bf16 v[20:23], v[156:159], v[188:191], v[20:23]
	v_mfma_f32_16x16x32_bf16 v[12:15], v[164:167], v[188:191], v[12:15]
	v_mfma_f32_16x16x32_bf16 v[4:7], v[156:159], v[196:199], v[4:7]
	v_mfma_f32_16x16x32_bf16 v[0:3], v[164:167], v[196:199], v[0:3]
	v_mfma_f32_16x16x32_bf16 v[40:43], v[160:163], v[176:179], v[40:43]
	v_mfma_f32_16x16x32_bf16 v[36:39], v[168:171], v[176:179], v[36:39]
	v_mfma_f32_16x16x32_bf16 v[28:31], v[160:163], v[184:187], v[28:31]
	v_mfma_f32_16x16x32_bf16 v[24:27], v[168:171], v[184:187], v[24:27]
	v_mfma_f32_16x16x32_bf16 v[20:23], v[160:163], v[192:195], v[20:23]
	v_mfma_f32_16x16x32_bf16 v[12:15], v[168:171], v[192:195], v[12:15]
	v_mfma_f32_16x16x32_bf16 v[4:7], v[160:163], v[200:203], v[4:7]
	v_mfma_f32_16x16x32_bf16 v[0:3], v[168:171], v[200:203], v[0:3]
	s_setprio 0
	s_barrier
	s_add_i32 s51, s51, 2
	s_add_u32 s0, s0, 0x100
	s_addc_u32 s1, s1, 0
	s_add_u32 s43, s43, 0x100
	s_addc_u32 s50, s50, 0
	s_cmp_gt_u32 s51, 13
	s_cbranch_scc0 .LBB0_797
	s_branch .Lpeel_done_797

; #define PG8_STAGE(bufoff, gbase, voff) do { _Pragma("unroll") for (int _i = 0; _i < 2; ++_i) \
;         __builtin_amdgcn_global_load_lds((const unsigned*)((const char*)(gbase) + (voff)[_i]), (PG8_LAS unsigned*)(lds + (bufoff) + ldsw + _i * 8192), 16, 0, 0); } while (0)
; #define PG8_LDA(dst, b, h) do { _Pragma("unroll") for (int m = 0; m < 4; ++m) _Pragma("unroll") for (int k = 0; k < 2; ++k) dst[m][k] = *(const PG8_LAS bf16x8*)(lds + PG8_SA(b, h) + aoff + m * 2048 + k * 1024); } while (0)
; #define PG8_LDB(dst, b, h) do { _Pragma("unroll") for (int n = 0; n < 2; ++n) _Pragma("unroll") for (int k = 0; k < 2; ++k) dst[n][k] = *(const PG8_LAS bf16x8*)(lds + PG8_SB(b, h) + boff + n * 2048 + k * 1024); } while (0)
; #define PG8_WAIT_V(n) asm volatile("s_waitcnt vmcnt(" #n ")" ::: "memory")
; #define PG8_WAIT_L(n) asm volatile("s_waitcnt lgkmcnt(" #n ")" ::: "memory")
; #define PG8_BAR __builtin_amdgcn_s_barrier()
; #define PG8_SCHED __builtin_amdgcn_sched_barrier(0)
; template <class Epi, class Sched, bool ALIGN_EPI = false, bool SP2 = false>
; __device__ __forceinline__ void gemm_phase(PG8_LAS unsigned char* lds, const Gemm g, const Sched& S, const Epi& E) {
;     ...
;         const bool has_next = S.next(ui + 1, nxt);
;         const char* nA = has_next ? (const char*)g.A + (size_t)nxt.pm * tstepA : cA; const char* nB = has_next ? (const char*)g.Bt + (size_t)nxt.pn * tstepB : cB;
;         for (int t = 0; t < nt; t += 2) {
;             const bool last = (t == nt - 2);
;             const char* a1 = cA + (size_t)(t + 1) * kstep;
;             const char* a2 = last ? nA : cA + (size_t)(t + 2) * kstep; const char* b2 = last ? nB : cB + (size_t)(t + 2) * kstep;
;             const char* a3 = a2 + kstep; const char* b3 = b2 + kstep;
;             if (last && has_next) S.a_ready(nxt);
;             if constexpr (SP2) {
;             PG8_LDB(B0, 0, 0); PG8_LDB(B1, 0, 1); PG8_SCHED; PG8_LDA(At, 0, 0); PG8_STAGE(PG8_SA(1, 1), a1 + hstepA, voffA);
;             PG8_WAIT_V(8); PG8_WAIT_L(0); PG8_BAR; PG8_MMA(0, 0, At, B0); PG8_MMA(0, 1, At, B1); PG8_BAR; PG8_SCHED;
;             PG8_LDA(At, 0, 1); PG8_STAGE(PG8_SB(0, 0), b2, voffB); PG8_STAGE(PG8_SB(0, 1), b2 + hstepB, voffB); PG8_STAGE(PG8_SA(0, 0), a2, voffA);
;             PG8_WAIT_V(8); PG8_WAIT_L(0); PG8_BAR; PG8_MMA(1, 0, At, B0); PG8_MMA(1, 1, At, B1); PG8_BAR; PG8_SCHED;
.LBB0_919:
	s_ashr_i32 s43, s42, 31
	s_lshl_b64 s[14:15], s[42:43], 19
	v_readlane_b32 s22, v252, 2
	v_readlane_b32 s23, v252, 3
	s_add_u32 s44, s22, s14
	s_addc_u32 s45, s23, s15
	s_and_b64 s[14:15], s[40:41], exec
	s_cselect_b32 s14, s45, s1
	s_cselect_b32 s15, s44, s0
	s_ashr_i32 s9, s8, 31
	s_lshl_b64 s[22:23], s[8:9], 19
	s_add_u32 s46, s31, s22
	v_readlane_b32 s9, v254, 10
	s_addc_u32 s47, s9, s23
	s_and_b64 s[22:23], s[40:41], exec
	s_cselect_b32 s9, s47, s25
	s_cselect_b32 s38, s46, s24
	s_add_u32 s0, s0, 0x40080
	s_addc_u32 s1, s1, 0
	s_add_u32 s43, s24, 0x100
	s_addc_u32 s50, s25, 0
	s_mov_b32 s51, -2
	s_add_u32 s22, s0, 0xfffc0080
	s_addc_u32 s23, s1, -1
	s_add_i32 s28, 0, 0x10000
	s_cmp_eq_u32 s51, 12
	s_cselect_b32 s25, s14, s23
	s_cselect_b32 s24, s15, s22
	v_add_u32_e32 v138, s28, v141
	s_cselect_b32 s23, s9, s50
	s_cselect_b32 s22, s38, s43
	s_add_i32 s30, 0, 0x14000
	ds_read_b128 v[144:147], v138
	ds_read_b128 v[148:151], v138 offset:1024
	ds_read_b128 v[152:155], v138 offset:2048
	ds_read_b128 v[156:159], v138 offset:3072
	v_add_u32_e32 v138, s30, v141
	ds_read_b128 v[160:163], v138
	ds_read_b128 v[164:167], v138 offset:1024
	ds_read_b128 v[168:171], v138 offset:2048
	ds_read_b128 v[172:175], v138 offset:3072
	v_lshl_add_u64 v[138:139], s[0:1], 0, v[134:135]
	s_add_i32 m0, s21, 0xc000
	ds_read_b128 v[176:179], v143
	ds_read_b128 v[180:183], v143 offset:1024
	ds_read_b128 v[184:187], v143 offset:2048
	ds_read_b128 v[188:191], v143 offset:3072
	ds_read_b128 v[192:195], v143 offset:4096
	ds_read_b128 v[196:199], v143 offset:5120
	ds_read_b128 v[200:203], v143 offset:6144
	ds_read_b128 v[204:207], v143 offset:7168
	global_load_lds_dwordx4 v[138:139], off
	v_lshl_add_u64 v[138:139], s[0:1], 0, v[136:137]
	s_add_i32 m0, s21, 0xe000
	s_nop 0
	global_load_lds_dwordx4 v[138:139], off
	s_waitcnt vmcnt(8)
	s_waitcnt lgkmcnt(0)
	s_barrier
	s_setprio 1
	s_waitcnt lgkmcnt(0)
	v_mfma_f32_16x16x32_bf16 v[124:127], v[144:147], v[176:179], 0
	v_mfma_f32_16x16x32_bf16 v[120:123], v[152:155], v[176:179], 0
	v_mfma_f32_16x16x32_bf16 v[108:111], v[144:147], v[184:187], 0
	v_mfma_f32_16x16x32_bf16 v[104:107], v[152:155], v[184:187], 0
	v_mfma_f32_16x16x32_bf16 v[92:95], v[144:147], v[192:195], 0
	v_mfma_f32_16x16x32_bf16 v[88:91], v[152:155], v[192:195], 0
	v_mfma_f32_16x16x32_bf16 v[76:79], v[144:147], v[200:203], 0
	v_mfma_f32_16x16x32_bf16 v[72:75], v[152:155], v[200:203], 0
	v_mfma_f32_16x16x32_bf16 v[124:127], v[148:151], v[180:183], v[124:127]
	v_mfma_f32_16x16x32_bf16 v[120:123], v[156:159], v[180:183], v[120:123]
	v_mfma_f32_16x16x32_bf16 v[108:111], v[148:151], v[188:191], v[108:111]
	v_mfma_f32_16x16x32_bf16 v[104:107], v[156:159], v[188:191], v[104:107]
	v_mfma_f32_16x16x32_bf16 v[92:95], v[148:151], v[196:199], v[92:95]
	v_mfma_f32_16x16x32_bf16 v[88:91], v[156:159], v[196:199], v[88:91]
	v_mfma_f32_16x16x32_bf16 v[76:79], v[148:151], v[204:207], v[76:79]
	v_mfma_f32_16x16x32_bf16 v[72:75], v[156:159], v[204:207], v[72:75]
	s_setprio 0
	s_setprio 1
	v_mfma_f32_16x16x32_bf16 v[116:119], v[160:163], v[176:179], 0
	v_mfma_f32_16x16x32_bf16 v[112:115], v[168:171], v[176:179], 0
	v_mfma_f32_16x16x32_bf16 v[100:103], v[160:163], v[184:187], 0
	v_mfma_f32_16x16x32_bf16 v[96:99], v[168:171], v[184:187], 0
	v_mfma_f32_16x16x32_bf16 v[84:87], v[160:163], v[192:195], 0
	v_mfma_f32_16x16x32_bf16 v[80:83], v[168:171], v[192:195], 0
	v_mfma_f32_16x16x32_bf16 v[68:71], v[160:163], v[200:203], 0
	v_mfma_f32_16x16x32_bf16 v[64:67], v[168:171], v[200:203], 0
	v_mfma_f32_16x16x32_bf16 v[116:119], v[164:167], v[180:183], v[116:119]
	v_mfma_f32_16x16x32_bf16 v[112:115], v[172:175], v[180:183], v[112:115]
	v_mfma_f32_16x16x32_bf16 v[100:103], v[164:167], v[188:191], v[100:103]
	v_mfma_f32_16x16x32_bf16 v[96:99], v[172:175], v[188:191], v[96:99]
	v_mfma_f32_16x16x32_bf16 v[84:87], v[164:167], v[196:199], v[84:87]
	v_mfma_f32_16x16x32_bf16 v[80:83], v[172:175], v[196:199], v[80:83]
	v_mfma_f32_16x16x32_bf16 v[68:71], v[164:167], v[204:207], v[68:71]
	v_mfma_f32_16x16x32_bf16 v[64:67], v[172:175], v[204:207], v[64:67]
	s_setprio 0
	s_barrier
	s_add_i32 s28, s28, s18
	v_lshl_add_u64 v[138:139], s[22:23], 0, v[208:209]
	s_mov_b32 m0, s28
	ds_read_b128 v[176:179], v143 offset:16384
	ds_read_b128 v[180:183], v143 offset:17408
	ds_read_b128 v[184:187], v143 offset:18432
	ds_read_b128 v[188:191], v143 offset:19456
	ds_read_b128 v[192:195], v143 offset:20480
	ds_read_b128 v[196:199], v143 offset:21504
	ds_read_b128 v[200:203], v143 offset:22528
	ds_read_b128 v[204:207], v143 offset:23552
	global_load_lds_dwordx4 v[138:139], off
	s_add_i32 m0, s28, 0x2000
	s_add_u32 s28, s22, 0x40000
	v_lshl_add_u64 v[210:211], s[22:23], 0, v[128:129]
	s_addc_u32 s29, s23, 0
	s_add_i32 s30, s30, s18
	global_load_lds_dwordx4 v[210:211], off
	v_lshl_add_u64 v[212:213], s[28:29], 0, v[208:209]
	s_mov_b32 m0, s30
	v_lshl_add_u64 v[222:223], s[24:25], 0, v[130:131]
	global_load_lds_dwordx4 v[212:213], off
	v_lshl_add_u64 v[212:213], s[28:29], 0, v[128:129]
	s_add_i32 m0, s30, 0x2000
	s_nop 0
	global_load_lds_dwordx4 v[212:213], off
	v_lshl_add_u64 v[212:213], s[24:25], 0, v[132:133]
	s_mov_b32 m0, s21
	s_nop 0
	global_load_lds_dwordx4 v[212:213], off
	s_mov_b32 m0, s26
	s_nop 0
	global_load_lds_dwordx4 v[222:223], off
	s_waitcnt vmcnt(8)
	s_waitcnt lgkmcnt(0)
	s_barrier
; #define PG8_STAGE(bufoff, gbase, voff) do { _Pragma("unroll") for (int _i = 0; _i < 2; ++_i) \
;         __builtin_amdgcn_global_load_lds((const unsigned*)((const char*)(gbase) + (voff)[_i]), (PG8_LAS unsigned*)(lds + (bufoff) + ldsw + _i * 8192), 16, 0, 0); } while (0)
; #define PG8_LDA(dst, b, h) do { _Pragma("unroll") for (int m = 0; m < 4; ++m) _Pragma("unroll") for (int k = 0; k < 2; ++k) dst[m][k] = *(const PG8_LAS bf16x8*)(lds + PG8_SA(b, h) + aoff + m * 2048 + k * 1024); } while (0)
; #define PG8_LDB(dst, b, h) do { _Pragma("unroll") for (int n = 0; n < 2; ++n) _Pragma("unroll") for (int k = 0; k < 2; ++k) dst[n][k] = *(const PG8_LAS bf16x8*)(lds + PG8_SB(b, h) + boff + n * 2048 + k * 1024); } while (0)
; #define PG8_MMA(ai, bj, At, Bt) do { __builtin_amdgcn_s_setprio(1); _Pragma("unroll") for (int m = 0; m < 4; ++m) _Pragma("unroll") for (int n = 0; n < 2; ++n) _Pragma("unroll") for (int k = 0; k < 2; ++k) \
;         acc[ai][bj][m][n] = __builtin_amdgcn_mfma_f32_16x16x32_bf16(Bt[n][k], At[m][k], acc[ai][bj][m][n], 0, 0, 0); __builtin_amdgcn_s_setprio(0); } while (0)
; #define PG8_WAIT_V(n) asm volatile("s_waitcnt vmcnt(" #n ")" ::: "memory")
; #define PG8_WAIT_L(n) asm volatile("s_waitcnt lgkmcnt(" #n ")" ::: "memory")
; #define PG8_BAR __builtin_amdgcn_s_barrier()
; #define PG8_SCHED __builtin_amdgcn_sched_barrier(0)
; template <class Epi, class Sched, bool ALIGN_EPI = false, bool SP2 = false>
; __device__ __forceinline__ void gemm_phase(PG8_LAS unsigned char* lds, const Gemm g, const Sched& S, const Epi& E) {
;     ...
;             PG8_WAIT_V(8); PG8_WAIT_L(0); PG8_BAR; PG8_MMA(1, 0, At, B0); PG8_MMA(1, 1, At, B1); PG8_BAR; PG8_SCHED;
;             PG8_LDB(B0, 1, 0); PG8_LDB(B1, 1, 1); PG8_SCHED; PG8_LDA(At, 1, 0); PG8_STAGE(PG8_SA(0, 1), a2 + hstepA, voffA);
;             PG8_WAIT_V(8); PG8_WAIT_L(0); PG8_BAR; PG8_MMA(0, 0, At, B0); PG8_MMA(0, 1, At, B1); PG8_BAR; PG8_SCHED;
	s_setprio 1
	s_waitcnt lgkmcnt(0)
	v_mfma_f32_16x16x32_bf16 v[60:63], v[144:147], v[176:179], 0
	v_mfma_f32_16x16x32_bf16 v[56:59], v[152:155], v[176:179], 0
	v_mfma_f32_16x16x32_bf16 v[44:47], v[144:147], v[184:187], 0
	v_mfma_f32_16x16x32_bf16 v[40:43], v[152:155], v[184:187], 0
	v_mfma_f32_16x16x32_bf16 v[28:31], v[144:147], v[192:195], 0
	v_mfma_f32_16x16x32_bf16 v[24:27], v[152:155], v[192:195], 0
	v_mfma_f32_16x16x32_bf16 v[12:15], v[144:147], v[200:203], 0
	v_mfma_f32_16x16x32_bf16 v[8:11], v[152:155], v[200:203], 0
	v_mfma_f32_16x16x32_bf16 v[60:63], v[148:151], v[180:183], v[60:63]
	v_mfma_f32_16x16x32_bf16 v[56:59], v[156:159], v[180:183], v[56:59]
	v_mfma_f32_16x16x32_bf16 v[44:47], v[148:151], v[188:191], v[44:47]
	v_mfma_f32_16x16x32_bf16 v[40:43], v[156:159], v[188:191], v[40:43]
	v_mfma_f32_16x16x32_bf16 v[28:31], v[148:151], v[196:199], v[28:31]
	v_mfma_f32_16x16x32_bf16 v[24:27], v[156:159], v[196:199], v[24:27]
	v_mfma_f32_16x16x32_bf16 v[12:15], v[148:151], v[204:207], v[12:15]
	v_mfma_f32_16x16x32_bf16 v[8:11], v[156:159], v[204:207], v[8:11]
	s_setprio 0
	s_setprio 1
	v_mfma_f32_16x16x32_bf16 v[52:55], v[160:163], v[176:179], 0
	v_mfma_f32_16x16x32_bf16 v[48:51], v[168:171], v[176:179], 0
	v_mfma_f32_16x16x32_bf16 v[36:39], v[160:163], v[184:187], 0
	v_mfma_f32_16x16x32_bf16 v[32:35], v[168:171], v[184:187], 0
	v_mfma_f32_16x16x32_bf16 v[20:23], v[160:163], v[192:195], 0
	v_mfma_f32_16x16x32_bf16 v[16:19], v[168:171], v[192:195], 0
	v_mfma_f32_16x16x32_bf16 v[4:7], v[160:163], v[200:203], 0
	v_mfma_f32_16x16x32_bf16 v[0:3], v[168:171], v[200:203], 0
	v_mfma_f32_16x16x32_bf16 v[52:55], v[164:167], v[180:183], v[52:55]
	v_mfma_f32_16x16x32_bf16 v[48:51], v[172:175], v[180:183], v[48:51]
	v_mfma_f32_16x16x32_bf16 v[36:39], v[164:167], v[188:191], v[36:39]
	v_mfma_f32_16x16x32_bf16 v[32:35], v[172:175], v[188:191], v[32:35]
	v_mfma_f32_16x16x32_bf16 v[20:23], v[164:167], v[196:199], v[20:23]
	v_mfma_f32_16x16x32_bf16 v[16:19], v[172:175], v[196:199], v[16:19]
	v_mfma_f32_16x16x32_bf16 v[4:7], v[164:167], v[204:207], v[4:7]
	v_mfma_f32_16x16x32_bf16 v[0:3], v[172:175], v[204:207], v[0:3]
	s_setprio 0
	s_barrier
	s_add_i32 s28, 0, 0x18000
	s_add_i32 s29, 0, 0x1c000
	v_add_u32_e32 v156, s28, v141
	v_add_u32_e32 v172, s29, v141
	ds_read_b128 v[144:147], v156
	ds_read_b128 v[148:151], v156 offset:1024
	ds_read_b128 v[152:155], v156 offset:2048
	ds_read_b128 v[156:159], v156 offset:3072
	ds_read_b128 v[160:163], v172
	ds_read_b128 v[164:167], v172 offset:1024
	ds_read_b128 v[168:171], v172 offset:2048
	ds_read_b128 v[172:175], v172 offset:3072
	s_add_u32 s24, s24, 0x40000
	s_addc_u32 s25, s25, 0
	s_mov_b32 m0, s34
	v_lshl_add_u64 v[224:225], s[24:25], 0, v[132:133]
	ds_read_b128 v[176:179], v143 offset:32768
	ds_read_b128 v[180:183], v143 offset:33792
	ds_read_b128 v[184:187], v143 offset:34816
	ds_read_b128 v[188:191], v143 offset:35840
	ds_read_b128 v[192:195], v143 offset:36864
	ds_read_b128 v[196:199], v143 offset:37888
	ds_read_b128 v[200:203], v143 offset:38912
	ds_read_b128 v[204:207], v143 offset:39936
	global_load_lds_dwordx4 v[224:225], off
	v_lshl_add_u64 v[224:225], s[24:25], 0, v[130:131]
	s_mov_b32 m0, s35
	s_nop 0
	global_load_lds_dwordx4 v[224:225], off
	s_waitcnt vmcnt(8)
	s_waitcnt lgkmcnt(0)
	s_barrier
	s_setprio 1
	s_waitcnt lgkmcnt(0)
	v_mfma_f32_16x16x32_bf16 v[124:127], v[144:147], v[176:179], v[124:127]
	v_mfma_f32_16x16x32_bf16 v[120:123], v[152:155], v[176:179], v[120:123]
	v_mfma_f32_16x16x32_bf16 v[108:111], v[144:147], v[184:187], v[108:111]
	v_mfma_f32_16x16x32_bf16 v[104:107], v[152:155], v[184:187], v[104:107]
	v_mfma_f32_16x16x32_bf16 v[92:95], v[144:147], v[192:195], v[92:95]
	v_mfma_f32_16x16x32_bf16 v[88:91], v[152:155], v[192:195], v[88:91]
	v_mfma_f32_16x16x32_bf16 v[76:79], v[144:147], v[200:203], v[76:79]
	v_mfma_f32_16x16x32_bf16 v[72:75], v[152:155], v[200:203], v[72:75]
	v_mfma_f32_16x16x32_bf16 v[124:127], v[148:151], v[180:183], v[124:127]
	v_mfma_f32_16x16x32_bf16 v[120:123], v[156:159], v[180:183], v[120:123]
	v_mfma_f32_16x16x32_bf16 v[108:111], v[148:151], v[188:191], v[108:111]
	v_mfma_f32_16x16x32_bf16 v[104:107], v[156:159], v[188:191], v[104:107]
	v_mfma_f32_16x16x32_bf16 v[92:95], v[148:151], v[196:199], v[92:95]
	v_mfma_f32_16x16x32_bf16 v[88:91], v[156:159], v[196:199], v[88:91]
	v_mfma_f32_16x16x32_bf16 v[76:79], v[148:151], v[204:207], v[76:79]
	v_mfma_f32_16x16x32_bf16 v[72:75], v[156:159], v[204:207], v[72:75]
	s_setprio 0
	s_setprio 1
	v_mfma_f32_16x16x32_bf16 v[116:119], v[160:163], v[176:179], v[116:119]
	v_mfma_f32_16x16x32_bf16 v[112:115], v[168:171], v[176:179], v[112:115]
	v_mfma_f32_16x16x32_bf16 v[100:103], v[160:163], v[184:187], v[100:103]
	v_mfma_f32_16x16x32_bf16 v[96:99], v[168:171], v[184:187], v[96:99]
	v_mfma_f32_16x16x32_bf16 v[84:87], v[160:163], v[192:195], v[84:87]
	v_mfma_f32_16x16x32_bf16 v[80:83], v[168:171], v[192:195], v[80:83]
	v_mfma_f32_16x16x32_bf16 v[68:71], v[160:163], v[200:203], v[68:71]
	v_mfma_f32_16x16x32_bf16 v[64:67], v[168:171], v[200:203], v[64:67]
	v_mfma_f32_16x16x32_bf16 v[116:119], v[164:167], v[180:183], v[116:119]
	v_mfma_f32_16x16x32_bf16 v[112:115], v[172:175], v[180:183], v[112:115]
	v_mfma_f32_16x16x32_bf16 v[100:103], v[164:167], v[188:191], v[100:103]
	v_mfma_f32_16x16x32_bf16 v[96:99], v[172:175], v[188:191], v[96:99]
	v_mfma_f32_16x16x32_bf16 v[84:87], v[164:167], v[196:199], v[84:87]
	v_mfma_f32_16x16x32_bf16 v[80:83], v[172:175], v[196:199], v[80:83]
	v_mfma_f32_16x16x32_bf16 v[68:71], v[164:167], v[204:207], v[68:71]
	v_mfma_f32_16x16x32_bf16 v[64:67], v[172:175], v[204:207], v[64:67]
	s_setprio 0
	s_barrier
; #define PG8_STAGE(bufoff, gbase, voff) do { _Pragma("unroll") for (int _i = 0; _i < 2; ++_i) \
;         __builtin_amdgcn_global_load_lds((const unsigned*)((const char*)(gbase) + (voff)[_i]), (PG8_LAS unsigned*)(lds + (bufoff) + ldsw + _i * 8192), 16, 0, 0); } while (0)
; #define PG8_LDA(dst, b, h) do { _Pragma("unroll") for (int m = 0; m < 4; ++m) _Pragma("unroll") for (int k = 0; k < 2; ++k) dst[m][k] = *(const PG8_LAS bf16x8*)(lds + PG8_SA(b, h) + aoff + m * 2048 + k * 1024); } while (0)
; #define PG8_MMA(ai, bj, At, Bt) do { __builtin_amdgcn_s_setprio(1); _Pragma("unroll") for (int m = 0; m < 4; ++m) _Pragma("unroll") for (int n = 0; n < 2; ++n) _Pragma("unroll") for (int k = 0; k < 2; ++k) \
;         acc[ai][bj][m][n] = __builtin_amdgcn_mfma_f32_16x16x32_bf16(Bt[n][k], At[m][k], acc[ai][bj][m][n], 0, 0, 0); __builtin_amdgcn_s_setprio(0); } while (0)
; #define PG8_WAIT_V(n) asm volatile("s_waitcnt vmcnt(" #n ")" ::: "memory")
; #define PG8_WAIT_L(n) asm volatile("s_waitcnt lgkmcnt(" #n ")" ::: "memory")
; #define PG8_BAR __builtin_amdgcn_s_barrier()
; #define PG8_SCHED __builtin_amdgcn_sched_barrier(0)
; template <class Epi, class Sched, bool ALIGN_EPI = false, bool SP2 = false>
; __device__ __forceinline__ void gemm_phase(PG8_LAS unsigned char* lds, const Gemm g, const Sched& S, const Epi& E) {
;     ...
;         for (int t = 0; t < nt; t += 2) {
;             const bool last = (t == nt - 2);
;     ...
;             PG8_LDA(At, 1, 1); PG8_STAGE(PG8_SB(1, 0), b3, voffB); PG8_STAGE(PG8_SB(1, 1), b3 + hstepB, voffB); PG8_STAGE(PG8_SA(1, 0), a3, voffA);
;             PG8_WAIT_V(8); PG8_WAIT_L(0); PG8_BAR; PG8_MMA(1, 0, At, B0); PG8_MMA(1, 1, At, B1); PG8_BAR; PG8_SCHED;
	s_add_i32 s24, s28, s18
	v_lshl_add_u64 v[138:139], v[138:139], 0, s[10:11]
	s_mov_b32 m0, s24
	ds_read_b128 v[176:179], v143 offset:49152
	ds_read_b128 v[180:183], v143 offset:50176
	ds_read_b128 v[184:187], v143 offset:51200
	ds_read_b128 v[188:191], v143 offset:52224
	ds_read_b128 v[192:195], v143 offset:53248
	ds_read_b128 v[196:199], v143 offset:54272
	ds_read_b128 v[200:203], v143 offset:55296
	ds_read_b128 v[204:207], v143 offset:56320
	global_load_lds_dwordx4 v[138:139], off
	s_add_i32 m0, s24, 0x2000
	s_add_u32 s22, s22, 0x40080
	v_lshl_add_u64 v[138:139], v[210:211], 0, s[10:11]
	s_addc_u32 s23, s23, 0
	s_add_i32 s24, s29, s18
	global_load_lds_dwordx4 v[138:139], off
	v_lshl_add_u64 v[138:139], s[22:23], 0, v[208:209]
	s_mov_b32 m0, s24
	s_nop 0
	global_load_lds_dwordx4 v[138:139], off
	v_lshl_add_u64 v[138:139], s[22:23], 0, v[128:129]
	s_add_i32 m0, s24, 0x2000
	s_nop 0
	global_load_lds_dwordx4 v[138:139], off
	v_lshl_add_u64 v[138:139], v[212:213], 0, s[10:11]
	s_mov_b32 m0, s39
	s_nop 0
	global_load_lds_dwordx4 v[138:139], off
	v_lshl_add_u64 v[138:139], v[222:223], 0, s[10:11]
	s_mov_b32 m0, s48
	s_nop 0
	global_load_lds_dwordx4 v[138:139], off
	s_waitcnt vmcnt(8)
	s_waitcnt lgkmcnt(0)
	s_barrier
	s_setprio 1
	s_waitcnt lgkmcnt(0)
	v_mfma_f32_16x16x32_bf16 v[60:63], v[144:147], v[176:179], v[60:63]
	v_mfma_f32_16x16x32_bf16 v[56:59], v[152:155], v[176:179], v[56:59]
	v_mfma_f32_16x16x32_bf16 v[44:47], v[144:147], v[184:187], v[44:47]
	v_mfma_f32_16x16x32_bf16 v[40:43], v[152:155], v[184:187], v[40:43]
	v_mfma_f32_16x16x32_bf16 v[28:31], v[144:147], v[192:195], v[28:31]
	v_mfma_f32_16x16x32_bf16 v[24:27], v[152:155], v[192:195], v[24:27]
	v_mfma_f32_16x16x32_bf16 v[12:15], v[144:147], v[200:203], v[12:15]
	v_mfma_f32_16x16x32_bf16 v[8:11], v[152:155], v[200:203], v[8:11]
	v_mfma_f32_16x16x32_bf16 v[60:63], v[148:151], v[180:183], v[60:63]
	v_mfma_f32_16x16x32_bf16 v[56:59], v[156:159], v[180:183], v[56:59]
	v_mfma_f32_16x16x32_bf16 v[44:47], v[148:151], v[188:191], v[44:47]
	v_mfma_f32_16x16x32_bf16 v[40:43], v[156:159], v[188:191], v[40:43]
	v_mfma_f32_16x16x32_bf16 v[28:31], v[148:151], v[196:199], v[28:31]
	v_mfma_f32_16x16x32_bf16 v[24:27], v[156:159], v[196:199], v[24:27]
	v_mfma_f32_16x16x32_bf16 v[12:15], v[148:151], v[204:207], v[12:15]
	v_mfma_f32_16x16x32_bf16 v[8:11], v[156:159], v[204:207], v[8:11]
	s_setprio 0
	s_setprio 1
	v_mfma_f32_16x16x32_bf16 v[52:55], v[160:163], v[176:179], v[52:55]
	v_mfma_f32_16x16x32_bf16 v[48:51], v[168:171], v[176:179], v[48:51]
	v_mfma_f32_16x16x32_bf16 v[36:39], v[160:163], v[184:187], v[36:39]
	v_mfma_f32_16x16x32_bf16 v[32:35], v[168:171], v[184:187], v[32:35]
	v_mfma_f32_16x16x32_bf16 v[20:23], v[160:163], v[192:195], v[20:23]
	v_mfma_f32_16x16x32_bf16 v[16:19], v[168:171], v[192:195], v[16:19]
	v_mfma_f32_16x16x32_bf16 v[4:7], v[160:163], v[200:203], v[4:7]
	v_mfma_f32_16x16x32_bf16 v[0:3], v[168:171], v[200:203], v[0:3]
	v_mfma_f32_16x16x32_bf16 v[52:55], v[164:167], v[180:183], v[52:55]
	v_mfma_f32_16x16x32_bf16 v[48:51], v[172:175], v[180:183], v[48:51]
	v_mfma_f32_16x16x32_bf16 v[36:39], v[164:167], v[188:191], v[36:39]
	v_mfma_f32_16x16x32_bf16 v[32:35], v[172:175], v[188:191], v[32:35]
	v_mfma_f32_16x16x32_bf16 v[20:23], v[164:167], v[196:199], v[20:23]
	v_mfma_f32_16x16x32_bf16 v[16:19], v[172:175], v[196:199], v[16:19]
	v_mfma_f32_16x16x32_bf16 v[4:7], v[164:167], v[204:207], v[4:7]
	v_mfma_f32_16x16x32_bf16 v[0:3], v[172:175], v[204:207], v[0:3]
	s_setprio 0
	s_barrier
	s_add_i32 s51, s51, 2
	s_add_u32 s0, s0, 0x100
	s_addc_u32 s1, s1, 0
	s_add_u32 s43, s43, 0x100
	s_addc_u32 s50, s50, 0
	s_cmp_gt_u32 s51, 13
	s_cbranch_scc0 .LBB0_920
	s_branch .Lpeel_done_920

; #define PG8_STAGE(bufoff, gbase, voff) do { _Pragma("unroll") for (int _i = 0; _i < 2; ++_i) \
;         __builtin_amdgcn_global_load_lds((const unsigned*)((const char*)(gbase) + (voff)[_i]), (PG8_LAS unsigned*)(lds + (bufoff) + ldsw + _i * 8192), 16, 0, 0); } while (0)
; #define PG8_LDA(dst, b, h) do { _Pragma("unroll") for (int m = 0; m < 4; ++m) _Pragma("unroll") for (int k = 0; k < 2; ++k) dst[m][k] = *(const PG8_LAS bf16x8*)(lds + PG8_SA(b, h) + aoff + m * 2048 + k * 1024); } while (0)
; #define PG8_LDB(dst, b, h) do { _Pragma("unroll") for (int n = 0; n < 2; ++n) _Pragma("unroll") for (int k = 0; k < 2; ++k) dst[n][k] = *(const PG8_LAS bf16x8*)(lds + PG8_SB(b, h) + boff + n * 2048 + k * 1024); } while (0)
; #define PG8_WAIT_V(n) asm volatile("s_waitcnt vmcnt(" #n ")" ::: "memory")
; #define PG8_WAIT_L(n) asm volatile("s_waitcnt lgkmcnt(" #n ")" ::: "memory")
; #define PG8_BAR __builtin_amdgcn_s_barrier()
; #define PG8_SCHED __builtin_amdgcn_sched_barrier(0)
; template <class Epi, class Sched, bool ALIGN_EPI = false, bool SP2 = false>
; __device__ __forceinline__ void gemm_phase(PG8_LAS unsigned char* lds, const Gemm g, const Sched& S, const Epi& E) {
;     ...
;         const bool has_next = S.next(ui + 1, nxt);
;         const char* nA = has_next ? (const char*)g.A + (size_t)nxt.pm * tstepA : cA; const char* nB = has_next ? (const char*)g.Bt + (size_t)nxt.pn * tstepB : cB;
;         for (int t = 0; t < nt; t += 2) {
;             const bool last = (t == nt - 2);
;             const char* a1 = cA + (size_t)(t + 1) * kstep;
;             const char* a2 = last ? nA : cA + (size_t)(t + 2) * kstep; const char* b2 = last ? nB : cB + (size_t)(t + 2) * kstep;
;             const char* a3 = a2 + kstep; const char* b3 = b2 + kstep;
;             if (last && has_next) S.a_ready(nxt);
;             if constexpr (SP2) {
;             PG8_LDB(B0, 0, 0); PG8_LDB(B1, 0, 1); PG8_SCHED; PG8_LDA(At, 0, 0); PG8_STAGE(PG8_SA(1, 1), a1 + hstepA, voffA);
;             PG8_WAIT_V(8); PG8_WAIT_L(0); PG8_BAR; PG8_MMA(0, 0, At, B0); PG8_MMA(0, 1, At, B1); PG8_BAR; PG8_SCHED;
;             PG8_LDA(At, 0, 1); PG8_STAGE(PG8_SB(0, 0), b2, voffB); PG8_STAGE(PG8_SB(0, 1), b2 + hstepB, voffB); PG8_STAGE(PG8_SA(0, 0), a2, voffA);
;             PG8_WAIT_V(8); PG8_WAIT_L(0); PG8_BAR; PG8_MMA(1, 0, At, B0); PG8_MMA(1, 1, At, B1); PG8_BAR; PG8_SCHED;
.LBB0_999:
	s_add_u32 s14, s20, 0x100
	s_addc_u32 s15, s21, 0
	s_mov_b32 s49, -2
	s_add_u32 s20, s0, 0x100
	s_addc_u32 s21, s1, 0
	s_add_i32 s28, 0, 0x10000
	s_cmp_eq_u32 s49, 40
	s_cselect_b32 s25, s5, s21
	s_cselect_b32 s24, s4, s20
	v_add_u32_e32 v138, s28, v141
	s_cselect_b32 s23, s43, s15
	s_cselect_b32 s22, s42, s14
	s_add_i32 s29, 0, 0x14000
	ds_read_b128 v[134:137], v138
	ds_read_b128 v[144:147], v138 offset:1024
	ds_read_b128 v[148:151], v138 offset:2048
	ds_read_b128 v[152:155], v138 offset:3072
	v_add_u32_e32 v138, s29, v141
	ds_read_b128 v[156:159], v138
	ds_read_b128 v[160:163], v138 offset:1024
	ds_read_b128 v[164:167], v138 offset:2048
	ds_read_b128 v[168:171], v138 offset:3072
	v_lshl_add_u64 v[138:139], s[0:1], 0, v[130:131]
	s_add_i32 m0, s26, 0xc000
	ds_read_b128 v[172:175], v143
	ds_read_b128 v[176:179], v143 offset:1024
	ds_read_b128 v[180:183], v143 offset:2048
	ds_read_b128 v[184:187], v143 offset:3072
	ds_read_b128 v[188:191], v143 offset:4096
	ds_read_b128 v[192:195], v143 offset:5120
	ds_read_b128 v[196:199], v143 offset:6144
	ds_read_b128 v[200:203], v143 offset:7168
	global_load_lds_dwordx4 v[138:139], off
	v_lshl_add_u64 v[138:139], s[0:1], 0, v[132:133]
	s_add_i32 m0, s26, 0xe000
	s_nop 0
	global_load_lds_dwordx4 v[138:139], off
	s_waitcnt vmcnt(8)
	s_waitcnt lgkmcnt(0)
	s_barrier
	s_setprio 1
	s_waitcnt lgkmcnt(0)
	v_mfma_f32_16x16x32_bf16 v[124:127], v[134:137], v[172:175], 0
	v_mfma_f32_16x16x32_bf16 v[120:123], v[148:151], v[172:175], 0
	v_mfma_f32_16x16x32_bf16 v[116:119], v[134:137], v[180:183], 0
	v_mfma_f32_16x16x32_bf16 v[112:115], v[148:151], v[180:183], 0
	v_mfma_f32_16x16x32_bf16 v[108:111], v[134:137], v[188:191], 0
	v_mfma_f32_16x16x32_bf16 v[100:103], v[148:151], v[188:191], 0
	v_mfma_f32_16x16x32_bf16 v[92:95], v[134:137], v[196:199], 0
	v_mfma_f32_16x16x32_bf16 v[80:83], v[148:151], v[196:199], 0
	v_mfma_f32_16x16x32_bf16 v[124:127], v[144:147], v[176:179], v[124:127]
	v_mfma_f32_16x16x32_bf16 v[120:123], v[152:155], v[176:179], v[120:123]
	v_mfma_f32_16x16x32_bf16 v[116:119], v[144:147], v[184:187], v[116:119]
	v_mfma_f32_16x16x32_bf16 v[112:115], v[152:155], v[184:187], v[112:115]
	v_mfma_f32_16x16x32_bf16 v[108:111], v[144:147], v[192:195], v[108:111]
	v_mfma_f32_16x16x32_bf16 v[100:103], v[152:155], v[192:195], v[100:103]
	v_mfma_f32_16x16x32_bf16 v[92:95], v[144:147], v[200:203], v[92:95]
	v_mfma_f32_16x16x32_bf16 v[80:83], v[152:155], v[200:203], v[80:83]
	s_setprio 0
	s_setprio 1
	v_mfma_f32_16x16x32_bf16 v[104:107], v[156:159], v[172:175], 0
	v_mfma_f32_16x16x32_bf16 v[96:99], v[164:167], v[172:175], 0
	v_mfma_f32_16x16x32_bf16 v[88:91], v[156:159], v[180:183], 0
	v_mfma_f32_16x16x32_bf16 v[84:87], v[164:167], v[180:183], 0
	v_mfma_f32_16x16x32_bf16 v[76:79], v[156:159], v[188:191], 0
	v_mfma_f32_16x16x32_bf16 v[72:75], v[164:167], v[188:191], 0
	v_mfma_f32_16x16x32_bf16 v[68:71], v[156:159], v[196:199], 0
	v_mfma_f32_16x16x32_bf16 v[64:67], v[164:167], v[196:199], 0
	v_mfma_f32_16x16x32_bf16 v[104:107], v[160:163], v[176:179], v[104:107]
	v_mfma_f32_16x16x32_bf16 v[96:99], v[168:171], v[176:179], v[96:99]
	v_mfma_f32_16x16x32_bf16 v[88:91], v[160:163], v[184:187], v[88:91]
	v_mfma_f32_16x16x32_bf16 v[84:87], v[168:171], v[184:187], v[84:87]
	v_mfma_f32_16x16x32_bf16 v[76:79], v[160:163], v[192:195], v[76:79]
	v_mfma_f32_16x16x32_bf16 v[72:75], v[168:171], v[192:195], v[72:75]
	v_mfma_f32_16x16x32_bf16 v[68:71], v[160:163], v[200:203], v[68:71]
	v_mfma_f32_16x16x32_bf16 v[64:67], v[168:171], v[200:203], v[64:67]
	s_setprio 0
	s_barrier
	s_add_i32 s0, s28, s19
	v_lshl_add_u64 v[138:139], s[22:23], 0, v[208:209]
	s_mov_b32 m0, s0
	ds_read_b128 v[172:175], v143 offset:16384
	ds_read_b128 v[176:179], v143 offset:17408
	ds_read_b128 v[180:183], v143 offset:18432
	ds_read_b128 v[184:187], v143 offset:19456
	ds_read_b128 v[188:191], v143 offset:20480
	ds_read_b128 v[192:195], v143 offset:21504
	ds_read_b128 v[196:199], v143 offset:22528
	ds_read_b128 v[200:203], v143 offset:23552
	global_load_lds_dwordx4 v[138:139], off
	s_add_i32 m0, s0, 0x2000
	s_add_u32 s0, s22, 0xb0000
	v_lshl_add_u64 v[204:205], s[22:23], 0, v[128:129]
	s_addc_u32 s1, s23, 0
	s_add_i32 s28, s29, s19
	global_load_lds_dwordx4 v[204:205], off
	v_lshl_add_u64 v[206:207], s[0:1], 0, v[208:209]
	s_mov_b32 m0, s28
	v_lshl_add_u64 v[210:211], s[24:25], 0, v[128:129]
	global_load_lds_dwordx4 v[206:207], off
	v_lshl_add_u64 v[206:207], s[0:1], 0, v[128:129]
	s_add_i32 m0, s28, 0x2000
	s_nop 0
	global_load_lds_dwordx4 v[206:207], off
	v_lshl_add_u64 v[206:207], s[24:25], 0, v[208:209]
	s_mov_b32 m0, s26
	s_nop 0
	global_load_lds_dwordx4 v[206:207], off
	s_mov_b32 m0, s34
	s_nop 0
	global_load_lds_dwordx4 v[210:211], off
	s_waitcnt vmcnt(8)
	s_waitcnt lgkmcnt(0)
	s_barrier
; #define PG8_STAGE(bufoff, gbase, voff) do { _Pragma("unroll") for (int _i = 0; _i < 2; ++_i) \
;         __builtin_amdgcn_global_load_lds((const unsigned*)((const char*)(gbase) + (voff)[_i]), (PG8_LAS unsigned*)(lds + (bufoff) + ldsw + _i * 8192), 16, 0, 0); } while (0)
; #define PG8_LDA(dst, b, h) do { _Pragma("unroll") for (int m = 0; m < 4; ++m) _Pragma("unroll") for (int k = 0; k < 2; ++k) dst[m][k] = *(const PG8_LAS bf16x8*)(lds + PG8_SA(b, h) + aoff + m * 2048 + k * 1024); } while (0)
; #define PG8_LDB(dst, b, h) do { _Pragma("unroll") for (int n = 0; n < 2; ++n) _Pragma("unroll") for (int k = 0; k < 2; ++k) dst[n][k] = *(const PG8_LAS bf16x8*)(lds + PG8_SB(b, h) + boff + n * 2048 + k * 1024); } while (0)
; #define PG8_MMA(ai, bj, At, Bt) do { __builtin_amdgcn_s_setprio(1); _Pragma("unroll") for (int m = 0; m < 4; ++m) _Pragma("unroll") for (int n = 0; n < 2; ++n) _Pragma("unroll") for (int k = 0; k < 2; ++k) \
;         acc[ai][bj][m][n] = __builtin_amdgcn_mfma_f32_16x16x32_bf16(Bt[n][k], At[m][k], acc[ai][bj][m][n], 0, 0, 0); __builtin_amdgcn_s_setprio(0); } while (0)
; #define PG8_WAIT_V(n) asm volatile("s_waitcnt vmcnt(" #n ")" ::: "memory")
; #define PG8_WAIT_L(n) asm volatile("s_waitcnt lgkmcnt(" #n ")" ::: "memory")
; #define PG8_BAR __builtin_amdgcn_s_barrier()
; #define PG8_SCHED __builtin_amdgcn_sched_barrier(0)
; template <class Epi, class Sched, bool ALIGN_EPI = false, bool SP2 = false>
; __device__ __forceinline__ void gemm_phase(PG8_LAS unsigned char* lds, const Gemm g, const Sched& S, const Epi& E) {
;     ...
;             PG8_WAIT_V(8); PG8_WAIT_L(0); PG8_BAR; PG8_MMA(1, 0, At, B0); PG8_MMA(1, 1, At, B1); PG8_BAR; PG8_SCHED;
;             PG8_LDB(B0, 1, 0); PG8_LDB(B1, 1, 1); PG8_SCHED; PG8_LDA(At, 1, 0); PG8_STAGE(PG8_SA(0, 1), a2 + hstepA, voffA);
;             PG8_WAIT_V(8); PG8_WAIT_L(0); PG8_BAR; PG8_MMA(0, 0, At, B0); PG8_MMA(0, 1, At, B1); PG8_BAR; PG8_SCHED;
	s_setprio 1
	s_waitcnt lgkmcnt(0)
	v_mfma_f32_16x16x32_bf16 v[60:63], v[134:137], v[172:175], 0
	v_mfma_f32_16x16x32_bf16 v[56:59], v[148:151], v[172:175], 0
	v_mfma_f32_16x16x32_bf16 v[52:55], v[134:137], v[180:183], 0
	v_mfma_f32_16x16x32_bf16 v[48:51], v[148:151], v[180:183], 0
	v_mfma_f32_16x16x32_bf16 v[44:47], v[134:137], v[188:191], 0
	v_mfma_f32_16x16x32_bf16 v[32:35], v[148:151], v[188:191], 0
	v_mfma_f32_16x16x32_bf16 v[16:19], v[134:137], v[196:199], 0
	v_mfma_f32_16x16x32_bf16 v[8:11], v[148:151], v[196:199], 0
	v_mfma_f32_16x16x32_bf16 v[60:63], v[144:147], v[176:179], v[60:63]
	v_mfma_f32_16x16x32_bf16 v[56:59], v[152:155], v[176:179], v[56:59]
	v_mfma_f32_16x16x32_bf16 v[52:55], v[144:147], v[184:187], v[52:55]
	v_mfma_f32_16x16x32_bf16 v[48:51], v[152:155], v[184:187], v[48:51]
	v_mfma_f32_16x16x32_bf16 v[44:47], v[144:147], v[192:195], v[44:47]
	v_mfma_f32_16x16x32_bf16 v[32:35], v[152:155], v[192:195], v[32:35]
	v_mfma_f32_16x16x32_bf16 v[16:19], v[144:147], v[200:203], v[16:19]
	v_mfma_f32_16x16x32_bf16 v[8:11], v[152:155], v[200:203], v[8:11]
	s_setprio 0
	s_setprio 1
	v_mfma_f32_16x16x32_bf16 v[40:43], v[156:159], v[172:175], 0
	v_mfma_f32_16x16x32_bf16 v[36:39], v[164:167], v[172:175], 0
	v_mfma_f32_16x16x32_bf16 v[28:31], v[156:159], v[180:183], 0
	v_mfma_f32_16x16x32_bf16 v[24:27], v[164:167], v[180:183], 0
	v_mfma_f32_16x16x32_bf16 v[20:23], v[156:159], v[188:191], 0
	v_mfma_f32_16x16x32_bf16 v[12:15], v[164:167], v[188:191], 0
	v_mfma_f32_16x16x32_bf16 v[4:7], v[156:159], v[196:199], 0
	v_mfma_f32_16x16x32_bf16 v[0:3], v[164:167], v[196:199], 0
	v_mfma_f32_16x16x32_bf16 v[40:43], v[160:163], v[176:179], v[40:43]
	v_mfma_f32_16x16x32_bf16 v[36:39], v[168:171], v[176:179], v[36:39]
	v_mfma_f32_16x16x32_bf16 v[28:31], v[160:163], v[184:187], v[28:31]
	v_mfma_f32_16x16x32_bf16 v[24:27], v[168:171], v[184:187], v[24:27]
	v_mfma_f32_16x16x32_bf16 v[20:23], v[160:163], v[192:195], v[20:23]
	v_mfma_f32_16x16x32_bf16 v[12:15], v[168:171], v[192:195], v[12:15]
	v_mfma_f32_16x16x32_bf16 v[4:7], v[160:163], v[200:203], v[4:7]
	v_mfma_f32_16x16x32_bf16 v[0:3], v[168:171], v[200:203], v[0:3]
	s_setprio 0
	s_barrier
	s_add_i32 s28, 0, 0x18000
	s_add_i32 s29, 0, 0x1c000
	v_add_u32_e32 v152, s28, v141
	v_add_u32_e32 v168, s29, v141
	ds_read_b128 v[134:137], v152
	ds_read_b128 v[144:147], v152 offset:1024
	ds_read_b128 v[148:151], v152 offset:2048
	ds_read_b128 v[152:155], v152 offset:3072
	ds_read_b128 v[156:159], v168
	ds_read_b128 v[160:163], v168 offset:1024
	ds_read_b128 v[164:167], v168 offset:2048
	ds_read_b128 v[168:171], v168 offset:3072
	s_add_u32 s0, s24, 0xb0000
	s_addc_u32 s1, s25, 0
	s_mov_b32 m0, s35
	v_lshl_add_u64 v[212:213], s[0:1], 0, v[208:209]
	ds_read_b128 v[172:175], v143 offset:32768
	ds_read_b128 v[176:179], v143 offset:33792
	ds_read_b128 v[180:183], v143 offset:34816
	ds_read_b128 v[184:187], v143 offset:35840
	ds_read_b128 v[188:191], v143 offset:36864
	ds_read_b128 v[192:195], v143 offset:37888
	ds_read_b128 v[196:199], v143 offset:38912
	ds_read_b128 v[200:203], v143 offset:39936
	global_load_lds_dwordx4 v[212:213], off
	v_lshl_add_u64 v[212:213], s[0:1], 0, v[128:129]
	s_mov_b32 m0, s39
	s_nop 0
	global_load_lds_dwordx4 v[212:213], off
	s_waitcnt vmcnt(8)
	s_waitcnt lgkmcnt(0)
	s_barrier
	s_setprio 1
	s_waitcnt lgkmcnt(0)
	v_mfma_f32_16x16x32_bf16 v[124:127], v[134:137], v[172:175], v[124:127]
	v_mfma_f32_16x16x32_bf16 v[120:123], v[148:151], v[172:175], v[120:123]
	v_mfma_f32_16x16x32_bf16 v[116:119], v[134:137], v[180:183], v[116:119]
	v_mfma_f32_16x16x32_bf16 v[112:115], v[148:151], v[180:183], v[112:115]
	v_mfma_f32_16x16x32_bf16 v[108:111], v[134:137], v[188:191], v[108:111]
	v_mfma_f32_16x16x32_bf16 v[100:103], v[148:151], v[188:191], v[100:103]
	v_mfma_f32_16x16x32_bf16 v[92:95], v[134:137], v[196:199], v[92:95]
	v_mfma_f32_16x16x32_bf16 v[80:83], v[148:151], v[196:199], v[80:83]
	v_mfma_f32_16x16x32_bf16 v[124:127], v[144:147], v[176:179], v[124:127]
	v_mfma_f32_16x16x32_bf16 v[120:123], v[152:155], v[176:179], v[120:123]
	v_mfma_f32_16x16x32_bf16 v[116:119], v[144:147], v[184:187], v[116:119]
	v_mfma_f32_16x16x32_bf16 v[112:115], v[152:155], v[184:187], v[112:115]
	v_mfma_f32_16x16x32_bf16 v[108:111], v[144:147], v[192:195], v[108:111]
	v_mfma_f32_16x16x32_bf16 v[100:103], v[152:155], v[192:195], v[100:103]
	v_mfma_f32_16x16x32_bf16 v[92:95], v[144:147], v[200:203], v[92:95]
	v_mfma_f32_16x16x32_bf16 v[80:83], v[152:155], v[200:203], v[80:83]
	s_setprio 0
	s_setprio 1
	v_mfma_f32_16x16x32_bf16 v[104:107], v[156:159], v[172:175], v[104:107]
	v_mfma_f32_16x16x32_bf16 v[96:99], v[164:167], v[172:175], v[96:99]
	v_mfma_f32_16x16x32_bf16 v[88:91], v[156:159], v[180:183], v[88:91]
	v_mfma_f32_16x16x32_bf16 v[84:87], v[164:167], v[180:183], v[84:87]
	v_mfma_f32_16x16x32_bf16 v[76:79], v[156:159], v[188:191], v[76:79]
	v_mfma_f32_16x16x32_bf16 v[72:75], v[164:167], v[188:191], v[72:75]
	v_mfma_f32_16x16x32_bf16 v[68:71], v[156:159], v[196:199], v[68:71]
	v_mfma_f32_16x16x32_bf16 v[64:67], v[164:167], v[196:199], v[64:67]
	v_mfma_f32_16x16x32_bf16 v[104:107], v[160:163], v[176:179], v[104:107]
	v_mfma_f32_16x16x32_bf16 v[96:99], v[168:171], v[176:179], v[96:99]
	v_mfma_f32_16x16x32_bf16 v[88:91], v[160:163], v[184:187], v[88:91]
	v_mfma_f32_16x16x32_bf16 v[84:87], v[168:171], v[184:187], v[84:87]
	v_mfma_f32_16x16x32_bf16 v[76:79], v[160:163], v[192:195], v[76:79]
	v_mfma_f32_16x16x32_bf16 v[72:75], v[168:171], v[192:195], v[72:75]
	v_mfma_f32_16x16x32_bf16 v[68:71], v[160:163], v[200:203], v[68:71]
	v_mfma_f32_16x16x32_bf16 v[64:67], v[168:171], v[200:203], v[64:67]
	s_setprio 0
	s_barrier
; #define PG8_STAGE(bufoff, gbase, voff) do { _Pragma("unroll") for (int _i = 0; _i < 2; ++_i) \
;         __builtin_amdgcn_global_load_lds((const unsigned*)((const char*)(gbase) + (voff)[_i]), (PG8_LAS unsigned*)(lds + (bufoff) + ldsw + _i * 8192), 16, 0, 0); } while (0)
; #define PG8_LDA(dst, b, h) do { _Pragma("unroll") for (int m = 0; m < 4; ++m) _Pragma("unroll") for (int k = 0; k < 2; ++k) dst[m][k] = *(const PG8_LAS bf16x8*)(lds + PG8_SA(b, h) + aoff + m * 2048 + k * 1024); } while (0)
; #define PG8_MMA(ai, bj, At, Bt) do { __builtin_amdgcn_s_setprio(1); _Pragma("unroll") for (int m = 0; m < 4; ++m) _Pragma("unroll") for (int n = 0; n < 2; ++n) _Pragma("unroll") for (int k = 0; k < 2; ++k) \
;         acc[ai][bj][m][n] = __builtin_amdgcn_mfma_f32_16x16x32_bf16(Bt[n][k], At[m][k], acc[ai][bj][m][n], 0, 0, 0); __builtin_amdgcn_s_setprio(0); } while (0)
; #define PG8_WAIT_V(n) asm volatile("s_waitcnt vmcnt(" #n ")" ::: "memory")
; #define PG8_WAIT_L(n) asm volatile("s_waitcnt lgkmcnt(" #n ")" ::: "memory")
; #define PG8_BAR __builtin_amdgcn_s_barrier()
; #define PG8_SCHED __builtin_amdgcn_sched_barrier(0)
; template <class Epi, class Sched, bool ALIGN_EPI = false, bool SP2 = false>
; __device__ __forceinline__ void gemm_phase(PG8_LAS unsigned char* lds, const Gemm g, const Sched& S, const Epi& E) {
;     ...
;         for (int t = 0; t < nt; t += 2) {
;             const bool last = (t == nt - 2);
;     ...
;             PG8_LDA(At, 1, 1); PG8_STAGE(PG8_SB(1, 0), b3, voffB); PG8_STAGE(PG8_SB(1, 1), b3 + hstepB, voffB); PG8_STAGE(PG8_SA(1, 0), a3, voffA);
;             PG8_WAIT_V(8); PG8_WAIT_L(0); PG8_BAR; PG8_MMA(1, 0, At, B0); PG8_MMA(1, 1, At, B1); PG8_BAR; PG8_SCHED;
	s_add_i32 s0, s28, s19
	v_lshl_add_u64 v[138:139], v[138:139], 0, s[10:11]
	s_mov_b32 m0, s0
	ds_read_b128 v[172:175], v143 offset:49152
	ds_read_b128 v[176:179], v143 offset:50176
	ds_read_b128 v[180:183], v143 offset:51200
	ds_read_b128 v[184:187], v143 offset:52224
	ds_read_b128 v[188:191], v143 offset:53248
	ds_read_b128 v[192:195], v143 offset:54272
	ds_read_b128 v[196:199], v143 offset:55296
	ds_read_b128 v[200:203], v143 offset:56320
	global_load_lds_dwordx4 v[138:139], off
	s_add_i32 m0, s0, 0x2000
	s_add_u32 s0, s22, 0xb0080
	v_lshl_add_u64 v[138:139], v[204:205], 0, s[10:11]
	s_addc_u32 s1, s23, 0
	s_add_i32 s22, s29, s19
	global_load_lds_dwordx4 v[138:139], off
	v_lshl_add_u64 v[138:139], s[0:1], 0, v[208:209]
	s_mov_b32 m0, s22
	s_nop 0
	global_load_lds_dwordx4 v[138:139], off
	v_lshl_add_u64 v[138:139], s[0:1], 0, v[128:129]
	s_add_i32 m0, s22, 0x2000
	s_nop 0
	global_load_lds_dwordx4 v[138:139], off
	v_lshl_add_u64 v[138:139], v[206:207], 0, s[10:11]
	s_mov_b32 m0, s44
	s_nop 0
	global_load_lds_dwordx4 v[138:139], off
	v_lshl_add_u64 v[138:139], v[210:211], 0, s[10:11]
	s_mov_b32 m0, s45
	s_nop 0
	global_load_lds_dwordx4 v[138:139], off
	s_waitcnt vmcnt(8)
	s_waitcnt lgkmcnt(0)
	s_barrier
	s_setprio 1
	s_waitcnt lgkmcnt(0)
	v_mfma_f32_16x16x32_bf16 v[60:63], v[134:137], v[172:175], v[60:63]
	v_mfma_f32_16x16x32_bf16 v[56:59], v[148:151], v[172:175], v[56:59]
	v_mfma_f32_16x16x32_bf16 v[52:55], v[134:137], v[180:183], v[52:55]
	v_mfma_f32_16x16x32_bf16 v[48:51], v[148:151], v[180:183], v[48:51]
	v_mfma_f32_16x16x32_bf16 v[44:47], v[134:137], v[188:191], v[44:47]
	v_mfma_f32_16x16x32_bf16 v[32:35], v[148:151], v[188:191], v[32:35]
	v_mfma_f32_16x16x32_bf16 v[16:19], v[134:137], v[196:199], v[16:19]
	v_mfma_f32_16x16x32_bf16 v[8:11], v[148:151], v[196:199], v[8:11]
	v_mfma_f32_16x16x32_bf16 v[60:63], v[144:147], v[176:179], v[60:63]
	v_mfma_f32_16x16x32_bf16 v[56:59], v[152:155], v[176:179], v[56:59]
	v_mfma_f32_16x16x32_bf16 v[52:55], v[144:147], v[184:187], v[52:55]
	v_mfma_f32_16x16x32_bf16 v[48:51], v[152:155], v[184:187], v[48:51]
	v_mfma_f32_16x16x32_bf16 v[44:47], v[144:147], v[192:195], v[44:47]
	v_mfma_f32_16x16x32_bf16 v[32:35], v[152:155], v[192:195], v[32:35]
	v_mfma_f32_16x16x32_bf16 v[16:19], v[144:147], v[200:203], v[16:19]
	v_mfma_f32_16x16x32_bf16 v[8:11], v[152:155], v[200:203], v[8:11]
	s_setprio 0
	s_setprio 1
	v_mfma_f32_16x16x32_bf16 v[40:43], v[156:159], v[172:175], v[40:43]
	v_mfma_f32_16x16x32_bf16 v[36:39], v[164:167], v[172:175], v[36:39]
	v_mfma_f32_16x16x32_bf16 v[28:31], v[156:159], v[180:183], v[28:31]
	v_mfma_f32_16x16x32_bf16 v[24:27], v[164:167], v[180:183], v[24:27]
	v_mfma_f32_16x16x32_bf16 v[20:23], v[156:159], v[188:191], v[20:23]
	v_mfma_f32_16x16x32_bf16 v[12:15], v[164:167], v[188:191], v[12:15]
	v_mfma_f32_16x16x32_bf16 v[4:7], v[156:159], v[196:199], v[4:7]
	v_mfma_f32_16x16x32_bf16 v[0:3], v[164:167], v[196:199], v[0:3]
	v_mfma_f32_16x16x32_bf16 v[40:43], v[160:163], v[176:179], v[40:43]
	v_mfma_f32_16x16x32_bf16 v[36:39], v[168:171], v[176:179], v[36:39]
	v_mfma_f32_16x16x32_bf16 v[28:31], v[160:163], v[184:187], v[28:31]
	v_mfma_f32_16x16x32_bf16 v[24:27], v[168:171], v[184:187], v[24:27]
	v_mfma_f32_16x16x32_bf16 v[20:23], v[160:163], v[192:195], v[20:23]
	v_mfma_f32_16x16x32_bf16 v[12:15], v[168:171], v[192:195], v[12:15]
	v_mfma_f32_16x16x32_bf16 v[4:7], v[160:163], v[200:203], v[4:7]
	v_mfma_f32_16x16x32_bf16 v[0:3], v[168:171], v[200:203], v[0:3]
	s_setprio 0
	s_barrier
	s_add_i32 s49, s49, 2
	s_add_u32 s14, s14, 0x100
	s_addc_u32 s15, s15, 0
	s_cmp_gt_u32 s49, 41
	s_mov_b64 s[0:1], s[20:21]
	s_cbranch_scc0 .LBB0_1000
	s_branch .Lpeel_done_1000
